# k8: EpiQK store-drain waits removed + 36 duplicate lgkmcnt(0) in GEMM MMA phases deleted
# speedup vs baseline: 1.0078x; 1.0036x over previous
; #define PG8_STAGE(bufoff, gbase, voff) do { _Pragma("unroll") for (int _i = 0; _i < 2; ++_i) \
;         __builtin_amdgcn_global_load_lds((const unsigned*)((const char*)(gbase) + (voff)[_i]), (LAS unsigned*)(lds + (bufoff) + ldsw + _i * 8192), 16, 0, 0); } while (0)
; #define PG8_LDA(dst, b, h) do { _Pragma("unroll") for (int m = 0; m < 4; ++m) _Pragma("unroll") for (int k = 0; k < 2; ++k) dst[m][k] = *(const LAS bf16x8*)(lds + PG8_SA(b, h) + aoff + m * 2048 + k * 1024); } while (0)
; #define PG8_LDB(dst, b, h) do { _Pragma("unroll") for (int n = 0; n < 2; ++n) _Pragma("unroll") for (int k = 0; k < 2; ++k) dst[n][k] = *(const LAS bf16x8*)(lds + PG8_SB(b, h) + boff + n * 2048 + k * 1024); } while (0)
; #define PG8_WAIT_V(n) asm volatile("s_waitcnt vmcnt(" #n ")" ::: "memory")
; #define PG8_WAIT_L(n) asm volatile("s_waitcnt lgkmcnt(" #n ")" ::: "memory")
; #define PG8_BAR __builtin_amdgcn_s_barrier()
; #define PG8_SCHED __builtin_amdgcn_sched_barrier(0)
; template <class Epi>
; __device__ __forceinline__ void gemm_phase(LAS unsigned char* lds, const Gemm g, const Epi& E) {
;     ...
;         const bool has_next = S.next(ui + 1, nxt);
;         const char* nA = has_next ? (const char*)g.A + (size_t)g.mapA.src(nxt.pm) * tstepA + (size_t)nxt.pn * g.a_pn_step : cA;
;         const char* nB = has_next ? (const char*)g.Bt + (size_t)g.mapB.src(nxt.pn) * tstepB : cB;
;         for (int t = 0; t < nt; t += 2) {
;             const bool last = (t == nt - 2);
;             const char* a1 = cA + (size_t)(t + 1) * kstep;
;             const char* a2 = last ? nA : cA + (size_t)(t + 2) * kstep; const char* b2 = last ? nB : cB + (size_t)(t + 2) * kstep;
;             const char* a3 = a2 + kstep; const char* b3 = b2 + kstep;
;             PG8_LDB(B0, 0, 0); PG8_SCHED; PG8_LDA(At, 0, 0); PG8_STAGE(PG8_SA(1, 1), a1 + hstepA, voffA);
;             PG8_WAIT_L(8); PG8_BAR; PG8_WAIT_L(0); PG8_MMA(0, 0, At, B0); PG8_BAR; PG8_SCHED;
;             PG8_LDB(B1, 0, 1); PG8_STAGE(PG8_SB(0, 0), b2, voffB);
;             PG8_BAR; PG8_WAIT_L(0); PG8_MMA(0, 1, At, B1); PG8_BAR;
;             PG8_LDA(At, 0, 1); PG8_STAGE(PG8_SA(0, 0), a2, voffA);
;             PG8_BAR; PG8_WAIT_L(0); PG8_MMA(1, 0, At, B0); PG8_BAR; PG8_SCHED;
;             PG8_STAGE(PG8_SB(0, 1), b2 + hstepB, voffB);
;             PG8_WAIT_V(6); PG8_BAR; PG8_MMA(1, 1, At, B1); PG8_BAR;
.LBB0_296:
	s_add_u32 s9, s16, s5
	s_addc_u32 s18, s17, 0
	s_add_u32 s36, s9, 0x100
	s_addc_u32 s60, s18, 0
	s_and_b64 s[0:1], s[58:59], exec
	s_cselect_b32 s67, s11, s60
	s_cselect_b32 s66, s10, s36
	s_add_u32 s0, s14, s5
	s_addc_u32 s1, s15, 0
	s_add_u32 s5, s0, 0x100
	s_addc_u32 s36, s1, 0
	s_add_i32 s73, 0, 0x10000
	s_and_b64 s[0:1], s[58:59], exec
	s_cselect_b32 s75, s13, s36
	s_cselect_b32 s74, s12, s5
	s_add_u32 s78, s9, 0x40080
	s_addc_u32 s79, s18, 0
	s_add_i32 s72, s73, s30
	s_add_i32 m0, s26, 0xc000
	s_add_i32 s50, s26, 0xe000
	s_add_i32 s27, 0, 0x14000
	s_add_i32 s24, s72, 0x2000
	s_add_u32 s64, s74, 0x10000
	v_add_u32_e32 v142, s73, v159
	s_addc_u32 s65, s75, 0
	s_add_i32 s18, s27, s30
	ds_read_b128 v[130:133], v142
	ds_read_b128 v[134:137], v142 offset:1024
	ds_read_b128 v[138:141], v142 offset:2048
	ds_read_b128 v[142:145], v142 offset:3072
	s_add_i32 s36, s18, 0x2000
	s_add_i32 vcc_hi, 0, 0x18000
	s_add_u32 s60, s66, 0x40000
	s_addc_u32 s61, s67, 0
	s_add_i32 vcc_lo, vcc_hi, s30
	s_add_i32 s9, 0, 0x1c000
	s_add_i32 s5, vcc_lo, 0x2000
	s_add_u32 s58, s74, 0x10080
	s_addc_u32 s59, s75, 0
	s_add_i32 s0, s9, s30
	s_add_i32 s1, s0, 0x2000
	v_lshl_add_u64 v[192:193], s[78:79], 0, v[152:153]
	ds_read_b128 v[154:157], v160
	ds_read_b128 v[162:165], v160 offset:1024
	ds_read_b128 v[166:169], v160 offset:2048
	ds_read_b128 v[170:173], v160 offset:3072
	ds_read_b128 v[174:177], v160 offset:4096
	ds_read_b128 v[180:183], v160 offset:5120
	ds_read_b128 v[184:187], v160 offset:6144
	ds_read_b128 v[188:191], v160 offset:7168
	global_load_lds_dwordx4 v[192:193], off
	v_lshl_add_u64 v[192:193], s[78:79], 0, v[148:149]
	s_mov_b32 m0, s50
	s_nop 0
	global_load_lds_dwordx4 v[192:193], off
	s_waitcnt lgkmcnt(8)
	s_barrier
	s_waitcnt lgkmcnt(0)
	s_setprio 1
	v_mfma_f32_16x16x32_bf16 v[126:129], v[130:133], v[154:157], v[126:129]
	v_mfma_f32_16x16x32_bf16 v[122:125], v[138:141], v[154:157], v[122:125]
	v_mfma_f32_16x16x32_bf16 v[114:117], v[130:133], v[166:169], v[114:117]
	v_mfma_f32_16x16x32_bf16 v[110:113], v[138:141], v[166:169], v[110:113]
	v_mfma_f32_16x16x32_bf16 v[102:105], v[130:133], v[174:177], v[102:105]
	v_mfma_f32_16x16x32_bf16 v[94:97], v[138:141], v[174:177], v[94:97]
	v_mfma_f32_16x16x32_bf16 v[86:89], v[130:133], v[184:187], v[86:89]
	v_mfma_f32_16x16x32_bf16 v[78:81], v[138:141], v[184:187], v[78:81]
	v_mfma_f32_16x16x32_bf16 v[126:129], v[134:137], v[162:165], v[126:129]
	v_mfma_f32_16x16x32_bf16 v[122:125], v[142:145], v[162:165], v[122:125]
	v_mfma_f32_16x16x32_bf16 v[114:117], v[134:137], v[170:173], v[114:117]
	v_mfma_f32_16x16x32_bf16 v[110:113], v[142:145], v[170:173], v[110:113]
	v_mfma_f32_16x16x32_bf16 v[102:105], v[134:137], v[180:183], v[102:105]
	v_mfma_f32_16x16x32_bf16 v[94:97], v[142:145], v[180:183], v[94:97]
	v_mfma_f32_16x16x32_bf16 v[86:89], v[134:137], v[188:191], v[86:89]
	v_mfma_f32_16x16x32_bf16 v[78:81], v[142:145], v[188:191], v[78:81]
	s_setprio 0
	s_barrier
	s_mov_b32 m0, s72
	v_add_u32_e32 v161, s27, v159
	v_lshl_add_u64 v[208:209], s[74:75], 0, v[150:151]
	ds_read_b128 v[192:195], v161
	ds_read_b128 v[196:199], v161 offset:1024
	ds_read_b128 v[200:203], v161 offset:2048
	ds_read_b128 v[204:207], v161 offset:3072
	global_load_lds_dwordx4 v[208:209], off
	v_lshl_add_u64 v[226:227], s[74:75], 0, v[146:147]
	s_mov_b32 m0, s24
	s_nop 0
	global_load_lds_dwordx4 v[226:227], off
	s_barrier
	s_waitcnt lgkmcnt(0)
	s_setprio 1
	v_mfma_f32_16x16x32_bf16 v[118:121], v[192:195], v[154:157], v[118:121]
	v_mfma_f32_16x16x32_bf16 v[106:109], v[200:203], v[154:157], v[106:109]
	v_mfma_f32_16x16x32_bf16 v[98:101], v[192:195], v[166:169], v[98:101]
	v_mfma_f32_16x16x32_bf16 v[90:93], v[200:203], v[166:169], v[90:93]
	v_mfma_f32_16x16x32_bf16 v[82:85], v[192:195], v[174:177], v[82:85]
	v_mfma_f32_16x16x32_bf16 v[74:77], v[200:203], v[174:177], v[74:77]
	v_mfma_f32_16x16x32_bf16 v[70:73], v[192:195], v[184:187], v[70:73]
	v_mfma_f32_16x16x32_bf16 v[66:69], v[200:203], v[184:187], v[66:69]
	v_mfma_f32_16x16x32_bf16 v[118:121], v[196:199], v[162:165], v[118:121]
	v_mfma_f32_16x16x32_bf16 v[106:109], v[204:207], v[162:165], v[106:109]
	v_mfma_f32_16x16x32_bf16 v[98:101], v[196:199], v[170:173], v[98:101]
	v_mfma_f32_16x16x32_bf16 v[90:93], v[204:207], v[170:173], v[90:93]
	v_mfma_f32_16x16x32_bf16 v[82:85], v[196:199], v[180:183], v[82:85]
	v_mfma_f32_16x16x32_bf16 v[74:77], v[204:207], v[180:183], v[74:77]
	v_mfma_f32_16x16x32_bf16 v[70:73], v[196:199], v[188:191], v[70:73]
	v_mfma_f32_16x16x32_bf16 v[66:69], v[204:207], v[188:191], v[66:69]
	s_setprio 0
	s_mov_b32 m0, s26
	v_lshl_add_u64 v[228:229], s[66:67], 0, v[152:153]
	s_barrier
	ds_read_b128 v[154:157], v160 offset:16384
	ds_read_b128 v[162:165], v160 offset:17408
	ds_read_b128 v[166:169], v160 offset:18432
	ds_read_b128 v[170:173], v160 offset:19456
	ds_read_b128 v[174:177], v160 offset:20480
	ds_read_b128 v[180:183], v160 offset:21504
	ds_read_b128 v[184:187], v160 offset:22528
	ds_read_b128 v[188:191], v160 offset:23552
	global_load_lds_dwordx4 v[228:229], off
	v_lshl_add_u64 v[230:231], s[66:67], 0, v[148:149]
	s_mov_b32 m0, s52
	s_nop 0
	global_load_lds_dwordx4 v[230:231], off
	s_barrier
; #define PG8_STAGE(bufoff, gbase, voff) do { _Pragma("unroll") for (int _i = 0; _i < 2; ++_i) \
;         __builtin_amdgcn_global_load_lds((const unsigned*)((const char*)(gbase) + (voff)[_i]), (LAS unsigned*)(lds + (bufoff) + ldsw + _i * 8192), 16, 0, 0); } while (0)
; #define PG8_LDA(dst, b, h) do { _Pragma("unroll") for (int m = 0; m < 4; ++m) _Pragma("unroll") for (int k = 0; k < 2; ++k) dst[m][k] = *(const LAS bf16x8*)(lds + PG8_SA(b, h) + aoff + m * 2048 + k * 1024); } while (0)
; #define PG8_LDB(dst, b, h) do { _Pragma("unroll") for (int n = 0; n < 2; ++n) _Pragma("unroll") for (int k = 0; k < 2; ++k) dst[n][k] = *(const LAS bf16x8*)(lds + PG8_SB(b, h) + boff + n * 2048 + k * 1024); } while (0)
; #define PG8_MMA(ai, bj, At, Bt) do { __builtin_amdgcn_s_setprio(1); _Pragma("unroll") for (int m = 0; m < 4; ++m) _Pragma("unroll") for (int n = 0; n < 2; ++n) _Pragma("unroll") for (int k = 0; k < 2; ++k) \
;         acc[ai][bj][m][n] = __builtin_amdgcn_mfma_f32_16x16x32_bf16(Bt[n][k], At[m][k], acc[ai][bj][m][n], 0, 0, 0); __builtin_amdgcn_s_setprio(0); } while (0)
; #define PG8_WAIT_V(n) asm volatile("s_waitcnt vmcnt(" #n ")" ::: "memory")
; #define PG8_WAIT_L(n) asm volatile("s_waitcnt lgkmcnt(" #n ")" ::: "memory")
; #define PG8_BAR __builtin_amdgcn_s_barrier()
; #define PG8_SCHED __builtin_amdgcn_sched_barrier(0)
; template <class Epi>
; __device__ __forceinline__ void gemm_phase(LAS unsigned char* lds, const Gemm g, const Epi& E) {
;     ...
;             PG8_BAR; PG8_WAIT_L(0); PG8_MMA(0, 1, At, B1); PG8_BAR;
;             PG8_LDA(At, 0, 1); PG8_STAGE(PG8_SA(0, 0), a2, voffA);
;             PG8_BAR; PG8_WAIT_L(0); PG8_MMA(1, 0, At, B0); PG8_BAR; PG8_SCHED;
;             PG8_STAGE(PG8_SB(0, 1), b2 + hstepB, voffB);
;             PG8_WAIT_V(6); PG8_BAR; PG8_MMA(1, 1, At, B1); PG8_BAR;
;             PG8_LDB(B0, 1, 0); PG8_SCHED; PG8_LDA(At, 1, 0); PG8_STAGE(PG8_SA(0, 1), a2 + hstepA, voffA);
;             PG8_WAIT_L(8); PG8_BAR; PG8_WAIT_L(0); PG8_MMA(0, 0, At, B0); PG8_BAR; PG8_SCHED;
;             PG8_LDB(B1, 1, 1); PG8_STAGE(PG8_SB(1, 0), b3, voffB);
;             PG8_BAR; PG8_WAIT_L(0); PG8_MMA(0, 1, At, B1); PG8_BAR;
	s_waitcnt lgkmcnt(0)
	s_setprio 1
	v_mfma_f32_16x16x32_bf16 v[62:65], v[130:133], v[154:157], v[62:65]
	v_mfma_f32_16x16x32_bf16 v[58:61], v[138:141], v[154:157], v[58:61]
	v_mfma_f32_16x16x32_bf16 v[54:57], v[130:133], v[166:169], v[54:57]
	v_mfma_f32_16x16x32_bf16 v[46:49], v[138:141], v[166:169], v[46:49]
	v_mfma_f32_16x16x32_bf16 v[38:41], v[130:133], v[174:177], v[38:41]
	v_mfma_f32_16x16x32_bf16 v[30:33], v[138:141], v[174:177], v[30:33]
	v_mfma_f32_16x16x32_bf16 v[22:25], v[130:133], v[184:187], v[22:25]
	v_mfma_f32_16x16x32_bf16 v[14:17], v[138:141], v[184:187], v[14:17]
	v_mfma_f32_16x16x32_bf16 v[62:65], v[134:137], v[162:165], v[62:65]
	v_mfma_f32_16x16x32_bf16 v[58:61], v[142:145], v[162:165], v[58:61]
	v_mfma_f32_16x16x32_bf16 v[54:57], v[134:137], v[170:173], v[54:57]
	v_mfma_f32_16x16x32_bf16 v[46:49], v[142:145], v[170:173], v[46:49]
	v_mfma_f32_16x16x32_bf16 v[38:41], v[134:137], v[180:183], v[38:41]
	v_mfma_f32_16x16x32_bf16 v[30:33], v[142:145], v[180:183], v[30:33]
	v_mfma_f32_16x16x32_bf16 v[22:25], v[134:137], v[188:191], v[22:25]
	v_mfma_f32_16x16x32_bf16 v[14:17], v[142:145], v[188:191], v[14:17]
	s_setprio 0
	s_barrier
	s_mov_b32 m0, s18
	v_lshl_add_u64 v[130:131], s[64:65], 0, v[150:151]
	global_load_lds_dwordx4 v[130:131], off
	v_lshl_add_u64 v[130:131], s[64:65], 0, v[146:147]
	s_mov_b32 m0, s36
	s_nop 0
	global_load_lds_dwordx4 v[130:131], off
	s_waitcnt vmcnt(6)
	s_barrier
	s_setprio 1
	v_mfma_f32_16x16x32_bf16 v[50:53], v[192:195], v[154:157], v[50:53]
	v_mfma_f32_16x16x32_bf16 v[42:45], v[200:203], v[154:157], v[42:45]
	v_mfma_f32_16x16x32_bf16 v[34:37], v[192:195], v[166:169], v[34:37]
	v_mfma_f32_16x16x32_bf16 v[26:29], v[200:203], v[166:169], v[26:29]
	v_mfma_f32_16x16x32_bf16 v[18:21], v[192:195], v[174:177], v[18:21]
	v_mfma_f32_16x16x32_bf16 v[10:13], v[200:203], v[174:177], v[10:13]
	v_mfma_f32_16x16x32_bf16 v[6:9], v[192:195], v[184:187], v[6:9]
	v_mfma_f32_16x16x32_bf16 v[2:5], v[200:203], v[184:187], v[2:5]
	v_mfma_f32_16x16x32_bf16 v[50:53], v[196:199], v[162:165], v[50:53]
	v_mfma_f32_16x16x32_bf16 v[42:45], v[204:207], v[162:165], v[42:45]
	v_mfma_f32_16x16x32_bf16 v[34:37], v[196:199], v[170:173], v[34:37]
	v_mfma_f32_16x16x32_bf16 v[26:29], v[204:207], v[170:173], v[26:29]
	v_mfma_f32_16x16x32_bf16 v[18:21], v[196:199], v[180:183], v[18:21]
	v_mfma_f32_16x16x32_bf16 v[10:13], v[204:207], v[180:183], v[10:13]
	v_mfma_f32_16x16x32_bf16 v[6:9], v[196:199], v[188:191], v[6:9]
	v_mfma_f32_16x16x32_bf16 v[2:5], v[204:207], v[188:191], v[2:5]
	s_setprio 0
	v_add_u32_e32 v142, vcc_hi, v159
	s_barrier
	ds_read_b128 v[130:133], v142
	ds_read_b128 v[134:137], v142 offset:1024
	ds_read_b128 v[138:141], v142 offset:2048
	ds_read_b128 v[142:145], v142 offset:3072
	s_mov_b32 m0, s53
	v_lshl_add_u64 v[192:193], s[60:61], 0, v[152:153]
	ds_read_b128 v[154:157], v160 offset:32768
	ds_read_b128 v[162:165], v160 offset:33792
	ds_read_b128 v[166:169], v160 offset:34816
	ds_read_b128 v[170:173], v160 offset:35840
	ds_read_b128 v[174:177], v160 offset:36864
	ds_read_b128 v[180:183], v160 offset:37888
	ds_read_b128 v[184:187], v160 offset:38912
	ds_read_b128 v[188:191], v160 offset:39936
	global_load_lds_dwordx4 v[192:193], off
	v_lshl_add_u64 v[192:193], s[60:61], 0, v[148:149]
	s_mov_b32 m0, s68
	s_nop 0
	global_load_lds_dwordx4 v[192:193], off
	s_waitcnt lgkmcnt(8)
	s_barrier
	s_waitcnt lgkmcnt(0)
	s_setprio 1
	v_mfma_f32_16x16x32_bf16 v[126:129], v[130:133], v[154:157], v[126:129]
	v_mfma_f32_16x16x32_bf16 v[122:125], v[138:141], v[154:157], v[122:125]
	v_mfma_f32_16x16x32_bf16 v[114:117], v[130:133], v[166:169], v[114:117]
	v_mfma_f32_16x16x32_bf16 v[110:113], v[138:141], v[166:169], v[110:113]
	v_mfma_f32_16x16x32_bf16 v[102:105], v[130:133], v[174:177], v[102:105]
	v_mfma_f32_16x16x32_bf16 v[94:97], v[138:141], v[174:177], v[94:97]
	v_mfma_f32_16x16x32_bf16 v[86:89], v[130:133], v[184:187], v[86:89]
	v_mfma_f32_16x16x32_bf16 v[78:81], v[138:141], v[184:187], v[78:81]
	v_mfma_f32_16x16x32_bf16 v[126:129], v[134:137], v[162:165], v[126:129]
	v_mfma_f32_16x16x32_bf16 v[122:125], v[142:145], v[162:165], v[122:125]
	v_mfma_f32_16x16x32_bf16 v[114:117], v[134:137], v[170:173], v[114:117]
	v_mfma_f32_16x16x32_bf16 v[110:113], v[142:145], v[170:173], v[110:113]
	v_mfma_f32_16x16x32_bf16 v[102:105], v[134:137], v[180:183], v[102:105]
	v_mfma_f32_16x16x32_bf16 v[94:97], v[142:145], v[180:183], v[94:97]
	v_mfma_f32_16x16x32_bf16 v[86:89], v[134:137], v[188:191], v[86:89]
	v_mfma_f32_16x16x32_bf16 v[78:81], v[142:145], v[188:191], v[78:81]
	s_setprio 0
	s_barrier
	s_mov_b32 m0, vcc_lo
	v_add_u32_e32 v161, s9, v159
	v_lshl_add_u64 v[208:209], v[208:209], 0, s[86:87]
	ds_read_b128 v[192:195], v161
	ds_read_b128 v[196:199], v161 offset:1024
	ds_read_b128 v[200:203], v161 offset:2048
	ds_read_b128 v[204:207], v161 offset:3072
	global_load_lds_dwordx4 v[208:209], off
	v_lshl_add_u64 v[208:209], v[226:227], 0, s[86:87]
	s_mov_b32 m0, s5
	s_nop 0
	global_load_lds_dwordx4 v[208:209], off
	s_barrier
; #define PG8_STAGE(bufoff, gbase, voff) do { _Pragma("unroll") for (int _i = 0; _i < 2; ++_i) \
;         __builtin_amdgcn_global_load_lds((const unsigned*)((const char*)(gbase) + (voff)[_i]), (LAS unsigned*)(lds + (bufoff) + ldsw + _i * 8192), 16, 0, 0); } while (0)
; #define PG8_LDA(dst, b, h) do { _Pragma("unroll") for (int m = 0; m < 4; ++m) _Pragma("unroll") for (int k = 0; k < 2; ++k) dst[m][k] = *(const LAS bf16x8*)(lds + PG8_SA(b, h) + aoff + m * 2048 + k * 1024); } while (0)
; #define PG8_MMA(ai, bj, At, Bt) do { __builtin_amdgcn_s_setprio(1); _Pragma("unroll") for (int m = 0; m < 4; ++m) _Pragma("unroll") for (int n = 0; n < 2; ++n) _Pragma("unroll") for (int k = 0; k < 2; ++k) \
;         acc[ai][bj][m][n] = __builtin_amdgcn_mfma_f32_16x16x32_bf16(Bt[n][k], At[m][k], acc[ai][bj][m][n], 0, 0, 0); __builtin_amdgcn_s_setprio(0); } while (0)
; #define PG8_WAIT_V(n) asm volatile("s_waitcnt vmcnt(" #n ")" ::: "memory")
; #define PG8_WAIT_L(n) asm volatile("s_waitcnt lgkmcnt(" #n ")" ::: "memory")
; #define PG8_BAR __builtin_amdgcn_s_barrier()
; #define PG8_SCHED __builtin_amdgcn_sched_barrier(0)
; template <class Epi>
; __device__ __forceinline__ void gemm_phase(LAS unsigned char* lds, const Gemm g, const Epi& E) {
;     ...
;             PG8_BAR; PG8_WAIT_L(0); PG8_MMA(0, 1, At, B1); PG8_BAR;
;             PG8_LDA(At, 1, 1); PG8_STAGE(PG8_SA(1, 0), a3, voffA);
;             PG8_BAR; PG8_WAIT_L(0); PG8_MMA(1, 0, At, B0); PG8_BAR; PG8_SCHED;
;             PG8_STAGE(PG8_SB(1, 1), b3 + hstepB, voffB);
;             PG8_WAIT_V(6); PG8_BAR; PG8_MMA(1, 1, At, B1); PG8_BAR;
;     __device__ __forceinline__ void operator()(const AccT& acc, const Unit& u, int wr, int wc, int fr, int fq) const {
;         asm volatile("" : "+v"(fr), "+v"(fq));
;         const int gpm = mapA.src(u.pm);
;         const int mb = gpm < 32 ? 32 : (gpm - 32) >> 3;
;         const int row0 = gpm * 256 + wr * 64 + fr, col0 = u.pn * 256 + wc * 32 + 4 * fq;
;         const float* gp = modl + ((size_t)mb * 6 + gi) * 1024;
;         f32x4 gv[2][2];
; #pragma unroll
;         for (int bj = 0; bj < 2; ++bj)
; #pragma unroll
;             for (int n = 0; n < 2; ++n) { gv[bj][n] = *(const f32x4*)(gp + col0 + bj * 128 + n * 16); if (scale) gv[bj][n] = gv[bj][n] * *(const f32x4*)(scale + col0 + bj * 128 + n * 16); }
	s_waitcnt lgkmcnt(0)
	s_setprio 1
	v_mfma_f32_16x16x32_bf16 v[118:121], v[192:195], v[154:157], v[118:121]
	v_mfma_f32_16x16x32_bf16 v[106:109], v[200:203], v[154:157], v[106:109]
	v_mfma_f32_16x16x32_bf16 v[98:101], v[192:195], v[166:169], v[98:101]
	v_mfma_f32_16x16x32_bf16 v[90:93], v[200:203], v[166:169], v[90:93]
	v_mfma_f32_16x16x32_bf16 v[82:85], v[192:195], v[174:177], v[82:85]
	v_mfma_f32_16x16x32_bf16 v[74:77], v[200:203], v[174:177], v[74:77]
	v_mfma_f32_16x16x32_bf16 v[70:73], v[192:195], v[184:187], v[70:73]
	v_mfma_f32_16x16x32_bf16 v[66:69], v[200:203], v[184:187], v[66:69]
	v_mfma_f32_16x16x32_bf16 v[118:121], v[196:199], v[162:165], v[118:121]
	v_mfma_f32_16x16x32_bf16 v[106:109], v[204:207], v[162:165], v[106:109]
	v_mfma_f32_16x16x32_bf16 v[98:101], v[196:199], v[170:173], v[98:101]
	v_mfma_f32_16x16x32_bf16 v[90:93], v[204:207], v[170:173], v[90:93]
	v_mfma_f32_16x16x32_bf16 v[82:85], v[196:199], v[180:183], v[82:85]
	v_mfma_f32_16x16x32_bf16 v[74:77], v[204:207], v[180:183], v[74:77]
	v_mfma_f32_16x16x32_bf16 v[70:73], v[196:199], v[188:191], v[70:73]
	v_mfma_f32_16x16x32_bf16 v[66:69], v[204:207], v[188:191], v[66:69]
	s_setprio 0
	s_mov_b32 m0, s71
	v_lshl_add_u64 v[208:209], v[228:229], 0, s[86:87]
	s_barrier
	ds_read_b128 v[154:157], v160 offset:49152
	ds_read_b128 v[162:165], v160 offset:50176
	ds_read_b128 v[166:169], v160 offset:51200
	ds_read_b128 v[170:173], v160 offset:52224
	ds_read_b128 v[174:177], v160 offset:53248
	ds_read_b128 v[180:183], v160 offset:54272
	ds_read_b128 v[184:187], v160 offset:55296
	ds_read_b128 v[188:191], v160 offset:56320
	global_load_lds_dwordx4 v[208:209], off
	v_lshl_add_u64 v[208:209], v[230:231], 0, s[86:87]
	s_mov_b32 m0, s80
	s_nop 0
	global_load_lds_dwordx4 v[208:209], off
	s_barrier
	s_waitcnt lgkmcnt(0)
	s_setprio 1
	v_mfma_f32_16x16x32_bf16 v[62:65], v[130:133], v[154:157], v[62:65]
	v_mfma_f32_16x16x32_bf16 v[58:61], v[138:141], v[154:157], v[58:61]
	v_mfma_f32_16x16x32_bf16 v[54:57], v[130:133], v[166:169], v[54:57]
	v_mfma_f32_16x16x32_bf16 v[46:49], v[138:141], v[166:169], v[46:49]
	v_mfma_f32_16x16x32_bf16 v[38:41], v[130:133], v[174:177], v[38:41]
	v_mfma_f32_16x16x32_bf16 v[30:33], v[138:141], v[174:177], v[30:33]
	v_mfma_f32_16x16x32_bf16 v[22:25], v[130:133], v[184:187], v[22:25]
	v_mfma_f32_16x16x32_bf16 v[14:17], v[138:141], v[184:187], v[14:17]
	v_mfma_f32_16x16x32_bf16 v[62:65], v[134:137], v[162:165], v[62:65]
	v_mfma_f32_16x16x32_bf16 v[58:61], v[142:145], v[162:165], v[58:61]
	v_mfma_f32_16x16x32_bf16 v[54:57], v[134:137], v[170:173], v[54:57]
	v_mfma_f32_16x16x32_bf16 v[46:49], v[142:145], v[170:173], v[46:49]
	v_mfma_f32_16x16x32_bf16 v[38:41], v[134:137], v[180:183], v[38:41]
	v_mfma_f32_16x16x32_bf16 v[30:33], v[142:145], v[180:183], v[30:33]
	v_mfma_f32_16x16x32_bf16 v[22:25], v[134:137], v[188:191], v[22:25]
	v_mfma_f32_16x16x32_bf16 v[14:17], v[142:145], v[188:191], v[14:17]
	s_setprio 0
	s_barrier
	s_mov_b32 m0, s0
	v_lshl_add_u64 v[130:131], s[58:59], 0, v[150:151]
	global_load_lds_dwordx4 v[130:131], off
	v_lshl_add_u64 v[130:131], s[58:59], 0, v[146:147]
	s_mov_b32 m0, s1
	s_nop 0
	global_load_lds_dwordx4 v[130:131], off
	s_waitcnt vmcnt(6)
	s_barrier
	s_setprio 1
	v_mfma_f32_16x16x32_bf16 v[50:53], v[192:195], v[154:157], v[50:53]
	v_mfma_f32_16x16x32_bf16 v[42:45], v[200:203], v[154:157], v[42:45]
	v_mfma_f32_16x16x32_bf16 v[34:37], v[192:195], v[166:169], v[34:37]
	v_mfma_f32_16x16x32_bf16 v[26:29], v[200:203], v[166:169], v[26:29]
	v_mfma_f32_16x16x32_bf16 v[18:21], v[192:195], v[174:177], v[18:21]
	v_mfma_f32_16x16x32_bf16 v[10:13], v[200:203], v[174:177], v[10:13]
	v_mfma_f32_16x16x32_bf16 v[6:9], v[192:195], v[184:187], v[6:9]
	v_mfma_f32_16x16x32_bf16 v[2:5], v[200:203], v[184:187], v[2:5]
	v_mfma_f32_16x16x32_bf16 v[50:53], v[196:199], v[162:165], v[50:53]
	v_mfma_f32_16x16x32_bf16 v[42:45], v[204:207], v[162:165], v[42:45]
	v_mfma_f32_16x16x32_bf16 v[34:37], v[196:199], v[170:173], v[34:37]
	v_mfma_f32_16x16x32_bf16 v[26:29], v[204:207], v[170:173], v[26:29]
	v_mfma_f32_16x16x32_bf16 v[18:21], v[196:199], v[180:183], v[18:21]
	v_mfma_f32_16x16x32_bf16 v[10:13], v[204:207], v[180:183], v[10:13]
	v_mfma_f32_16x16x32_bf16 v[6:9], v[196:199], v[188:191], v[6:9]
	v_mfma_f32_16x16x32_bf16 v[2:5], v[204:207], v[188:191], v[2:5]
	s_setprio 0
	s_movk_i32 s5, 0x100
	s_andn2_b64 vcc, exec, s[28:29]
	s_mov_b64 s[58:59], -1
	s_mov_b64 s[28:29], 0
	s_barrier
	s_cbranch_vccz .LBB0_296
	s_cmp_ge_i32 s93, s31
	s_cselect_b32 s0, s44, 0
	s_add_i32 s0, s93, s0
	s_sub_i32 s1, s0, 32
	s_lshl_b32 s4, s4, 8
	s_ashr_i32 s1, s1, 3
	s_or_b32 s4, s4, s70
	v_mov_b32_e32 v130, v1
	v_mov_b32_e32 v161, v158
	s_mul_i32 s1, s1, 6
	s_cmp_gt_i32 s0, 31
	v_readlane_b32 s14, v255, 14
	v_lshl_add_u32 v154, v130, 2, s4
	s_cselect_b32 s4, s1, 0xc0
	s_ashr_i32 s5, s4, 31
	s_lshl_b64 s[4:5], s[4:5], 12
	v_readlane_b32 s15, v255, 15
	s_add_u32 s4, s14, s4
	v_ashrrev_i32_e32 v155, 31, v154
	s_addc_u32 s5, s15, s5
	v_lshlrev_b64 v[136:137], 2, v[154:155]
	v_lshl_add_u64 v[134:135], s[4:5], 0, v[136:137]
	v_add_co_u32_e32 v130, vcc, 0x2000, v134
	v_readlane_b32 s14, v254, 30
	s_nop 0
	v_addc_co_u32_e32 v131, vcc, 0, v135, vcc
	global_load_dwordx4 v[130:133], v[130:131], off
	v_readlane_b32 s15, v254, 31
	s_andn2_b64 vcc, exec, s[14:15]
	v_lshl_add_u64 v[156:157], s[6:7], 0, v[136:137]
	v_cndmask_b32_e64 v138, 0, 1, s[14:15]
	v_cmp_ne_u32_e64 s[4:5], 1, v138
	s_cbranch_vccnz .LBB0_299
	global_load_dwordx4 v[136:139], v[156:157], off
	s_waitcnt vmcnt(0)
	v_pk_mul_f32 v[132:133], v[132:133], v[138:139]
	v_pk_mul_f32 v[130:131], v[130:131], v[136:137]

; #define PG8_STAGE(bufoff, gbase, voff) do { _Pragma("unroll") for (int _i = 0; _i < 2; ++_i) \
;         __builtin_amdgcn_global_load_lds((const unsigned*)((const char*)(gbase) + (voff)[_i]), (LAS unsigned*)(lds + (bufoff) + ldsw + _i * 8192), 16, 0, 0); } while (0)
; #define PG8_LDA(dst, b, h) do { _Pragma("unroll") for (int m = 0; m < 4; ++m) _Pragma("unroll") for (int k = 0; k < 2; ++k) dst[m][k] = *(const LAS bf16x8*)(lds + PG8_SA(b, h) + aoff + m * 2048 + k * 1024); } while (0)
; #define PG8_LDB(dst, b, h) do { _Pragma("unroll") for (int n = 0; n < 2; ++n) _Pragma("unroll") for (int k = 0; k < 2; ++k) dst[n][k] = *(const LAS bf16x8*)(lds + PG8_SB(b, h) + boff + n * 2048 + k * 1024); } while (0)
; #define PG8_MMA(ai, bj, At, Bt) do { __builtin_amdgcn_s_setprio(1); _Pragma("unroll") for (int m = 0; m < 4; ++m) _Pragma("unroll") for (int n = 0; n < 2; ++n) _Pragma("unroll") for (int k = 0; k < 2; ++k) \
;         acc[ai][bj][m][n] = __builtin_amdgcn_mfma_f32_16x16x32_bf16(Bt[n][k], At[m][k], acc[ai][bj][m][n], 0, 0, 0); __builtin_amdgcn_s_setprio(0); } while (0)
; #define PG8_WAIT_V(n) asm volatile("s_waitcnt vmcnt(" #n ")" ::: "memory")
; #define PG8_WAIT_L(n) asm volatile("s_waitcnt lgkmcnt(" #n ")" ::: "memory")
; #define PG8_BAR __builtin_amdgcn_s_barrier()
; #define PG8_SCHED __builtin_amdgcn_sched_barrier(0)
; template <class Epi>
; __device__ __forceinline__ void gemm_phase(LAS unsigned char* lds, const Gemm g, const Epi& E) {
;     ...
;             PG8_LDB(B0, 0, 0); PG8_SCHED; PG8_LDA(At, 0, 0); PG8_STAGE(PG8_SA(1, 1), a1 + hstepA, voffA);
;             PG8_WAIT_L(8); PG8_BAR; PG8_WAIT_L(0); PG8_MMA(0, 0, At, B0); PG8_BAR; PG8_SCHED;
;             PG8_LDB(B1, 0, 1); PG8_STAGE(PG8_SB(0, 0), b2, voffB);
;             PG8_BAR; PG8_WAIT_L(0); PG8_MMA(0, 1, At, B1); PG8_BAR;
;             PG8_LDA(At, 0, 1); PG8_STAGE(PG8_SA(0, 0), a2, voffA);
;             PG8_BAR; PG8_WAIT_L(0); PG8_MMA(1, 0, At, B0); PG8_BAR; PG8_SCHED;
;             PG8_STAGE(PG8_SB(0, 1), b2 + hstepB, voffB);
;             PG8_WAIT_V(6); PG8_BAR; PG8_MMA(1, 1, At, B1); PG8_BAR;
.LBB0_331:
	s_add_u32 s60, s4, 0xfffc0080
	s_addc_u32 s61, s5, -1
	s_add_i32 s72, 0, 0x10000
	s_waitcnt vmcnt(0)
	v_add_u32_e32 v94, s72, v201
	ds_read_b128 v[74:77], v94
	ds_read_b128 v[82:85], v94 offset:1024
	ds_read_b128 v[86:89], v94 offset:2048
	ds_read_b128 v[94:97], v94 offset:3072
	s_cmp_eq_u32 s53, 12
	s_cselect_b32 s65, s29, s61
	s_cselect_b32 s64, s28, s60
	s_cselect_b32 s61, s59, s52
	s_cselect_b32 s60, s58, s15
	v_lshl_add_u64 v[192:193], s[4:5], 0, v[188:189]
	s_add_i32 m0, s24, 0xc000
	ds_read_b128 v[106:109], v202
	ds_read_b128 v[110:113], v202 offset:1024
	ds_read_b128 v[130:133], v202 offset:2048
	ds_read_b128 v[134:137], v202 offset:3072
	ds_read_b128 v[154:157], v202 offset:4096
	ds_read_b128 v[158:161], v202 offset:5120
	ds_read_b128 v[170:173], v202 offset:6144
	ds_read_b128 v[174:177], v202 offset:7168
	global_load_lds_dwordx4 v[192:193], off
	v_lshl_add_u64 v[192:193], s[4:5], 0, v[190:191]
	s_add_i32 m0, s24, 0xe000
	s_nop 0
	global_load_lds_dwordx4 v[192:193], off
	s_waitcnt lgkmcnt(8)
	s_barrier
	s_waitcnt lgkmcnt(0)
	s_setprio 1
	v_mfma_f32_16x16x32_bf16 v[166:169], v[74:77], v[106:109], v[166:169]
	v_mfma_f32_16x16x32_bf16 v[162:165], v[86:89], v[106:109], v[162:165]
	v_mfma_f32_16x16x32_bf16 v[142:145], v[74:77], v[130:133], v[142:145]
	v_mfma_f32_16x16x32_bf16 v[138:141], v[86:89], v[130:133], v[138:141]
	v_mfma_f32_16x16x32_bf16 v[118:121], v[74:77], v[154:157], v[118:121]
	v_mfma_f32_16x16x32_bf16 v[114:117], v[86:89], v[154:157], v[114:117]
	v_mfma_f32_16x16x32_bf16 v[90:93], v[74:77], v[170:173], v[90:93]
	v_mfma_f32_16x16x32_bf16 v[78:81], v[86:89], v[170:173], v[78:81]
	v_mfma_f32_16x16x32_bf16 v[166:169], v[82:85], v[110:113], v[166:169]
	v_mfma_f32_16x16x32_bf16 v[162:165], v[94:97], v[110:113], v[162:165]
	v_mfma_f32_16x16x32_bf16 v[142:145], v[82:85], v[134:137], v[142:145]
	v_mfma_f32_16x16x32_bf16 v[138:141], v[94:97], v[134:137], v[138:141]
	v_mfma_f32_16x16x32_bf16 v[118:121], v[82:85], v[158:161], v[118:121]
	v_mfma_f32_16x16x32_bf16 v[114:117], v[94:97], v[158:161], v[114:117]
	v_mfma_f32_16x16x32_bf16 v[90:93], v[82:85], v[174:177], v[90:93]
	v_mfma_f32_16x16x32_bf16 v[78:81], v[94:97], v[174:177], v[78:81]
	s_setprio 0
	s_barrier
	s_add_i32 s74, 0, 0x14000
	s_add_i32 s72, s72, s1
	v_add_u32_e32 v203, s74, v201
	v_lshl_add_u64 v[208:209], s[60:61], 0, v[184:185]
	s_mov_b32 m0, s72
	ds_read_b128 v[192:195], v203
	ds_read_b128 v[196:199], v203 offset:1024
	ds_read_b128 v[204:207], v203 offset:2048
	ds_read_b128 v[226:229], v203 offset:3072
	global_load_lds_dwordx4 v[208:209], off
	v_lshl_add_u64 v[234:235], s[60:61], 0, v[180:181]
	s_add_i32 m0, s72, 0x2000
	s_nop 0
	global_load_lds_dwordx4 v[234:235], off
	s_barrier
	s_waitcnt lgkmcnt(0)
	s_setprio 1
	v_mfma_f32_16x16x32_bf16 v[150:153], v[192:195], v[106:109], v[150:153]
	v_mfma_f32_16x16x32_bf16 v[106:109], v[204:207], v[106:109], v[146:149]
	v_mfma_f32_16x16x32_bf16 v[122:125], v[204:207], v[130:133], v[122:125]
	v_mfma_f32_16x16x32_bf16 v[102:105], v[192:195], v[154:157], v[102:105]
	v_mfma_f32_16x16x32_bf16 v[98:101], v[204:207], v[154:157], v[98:101]
	v_mfma_f32_16x16x32_bf16 v[70:73], v[192:195], v[170:173], v[70:73]
	v_mfma_f32_16x16x32_bf16 v[66:69], v[204:207], v[170:173], v[66:69]
	v_mfma_f32_16x16x32_bf16 v[150:153], v[196:199], v[110:113], v[150:153]
	v_mfma_f32_16x16x32_bf16 v[106:109], v[226:229], v[110:113], v[106:109]
	v_mfma_f32_16x16x32_bf16 v[110:113], v[192:195], v[130:133], v[126:129]
	v_mfma_f32_16x16x32_bf16 v[122:125], v[226:229], v[134:137], v[122:125]
	v_mfma_f32_16x16x32_bf16 v[102:105], v[196:199], v[158:161], v[102:105]
	v_mfma_f32_16x16x32_bf16 v[98:101], v[226:229], v[158:161], v[98:101]
	v_mfma_f32_16x16x32_bf16 v[70:73], v[196:199], v[174:177], v[70:73]
	v_mfma_f32_16x16x32_bf16 v[66:69], v[226:229], v[174:177], v[66:69]
	v_mfma_f32_16x16x32_bf16 v[110:113], v[196:199], v[134:137], v[110:113]
	s_setprio 0
	s_mov_b32 m0, s24
	v_lshl_add_u64 v[236:237], s[64:65], 0, v[186:187]
	s_barrier
	ds_read_b128 v[126:129], v202 offset:16384
	ds_read_b128 v[130:133], v202 offset:17408
	ds_read_b128 v[134:137], v202 offset:18432
	ds_read_b128 v[146:149], v202 offset:19456
	ds_read_b128 v[154:157], v202 offset:20480
	ds_read_b128 v[158:161], v202 offset:21504
	ds_read_b128 v[170:173], v202 offset:22528
	ds_read_b128 v[174:177], v202 offset:23552
	global_load_lds_dwordx4 v[236:237], off
	v_lshl_add_u64 v[238:239], s[64:65], 0, v[182:183]
	s_mov_b32 m0, s25
	s_nop 0
	global_load_lds_dwordx4 v[238:239], off
	s_barrier
	s_waitcnt lgkmcnt(0)
	s_setprio 1
	v_mfma_f32_16x16x32_bf16 v[62:65], v[74:77], v[126:129], v[62:65]
	v_mfma_f32_16x16x32_bf16 v[58:61], v[86:89], v[126:129], v[58:61]
	v_mfma_f32_16x16x32_bf16 v[46:49], v[74:77], v[134:137], v[46:49]
	v_mfma_f32_16x16x32_bf16 v[42:45], v[86:89], v[134:137], v[42:45]
	v_mfma_f32_16x16x32_bf16 v[30:33], v[74:77], v[154:157], v[30:33]
	v_mfma_f32_16x16x32_bf16 v[26:29], v[86:89], v[154:157], v[26:29]
	v_mfma_f32_16x16x32_bf16 v[14:17], v[74:77], v[170:173], v[14:17]
	v_mfma_f32_16x16x32_bf16 v[10:13], v[86:89], v[170:173], v[10:13]
	v_mfma_f32_16x16x32_bf16 v[62:65], v[82:85], v[130:133], v[62:65]
	v_mfma_f32_16x16x32_bf16 v[58:61], v[94:97], v[130:133], v[58:61]
	v_mfma_f32_16x16x32_bf16 v[46:49], v[82:85], v[146:149], v[46:49]
	v_mfma_f32_16x16x32_bf16 v[42:45], v[94:97], v[146:149], v[42:45]
	v_mfma_f32_16x16x32_bf16 v[30:33], v[82:85], v[158:161], v[30:33]
	v_mfma_f32_16x16x32_bf16 v[26:29], v[94:97], v[158:161], v[26:29]
	v_mfma_f32_16x16x32_bf16 v[14:17], v[82:85], v[174:177], v[14:17]
	v_mfma_f32_16x16x32_bf16 v[10:13], v[94:97], v[174:177], v[10:13]
	s_setprio 0
	s_barrier
; #define PG8_STAGE(bufoff, gbase, voff) do { _Pragma("unroll") for (int _i = 0; _i < 2; ++_i) \
;         __builtin_amdgcn_global_load_lds((const unsigned*)((const char*)(gbase) + (voff)[_i]), (LAS unsigned*)(lds + (bufoff) + ldsw + _i * 8192), 16, 0, 0); } while (0)
; #define PG8_LDA(dst, b, h) do { _Pragma("unroll") for (int m = 0; m < 4; ++m) _Pragma("unroll") for (int k = 0; k < 2; ++k) dst[m][k] = *(const LAS bf16x8*)(lds + PG8_SA(b, h) + aoff + m * 2048 + k * 1024); } while (0)
; #define PG8_LDB(dst, b, h) do { _Pragma("unroll") for (int n = 0; n < 2; ++n) _Pragma("unroll") for (int k = 0; k < 2; ++k) dst[n][k] = *(const LAS bf16x8*)(lds + PG8_SB(b, h) + boff + n * 2048 + k * 1024); } while (0)
; #define PG8_MMA(ai, bj, At, Bt) do { __builtin_amdgcn_s_setprio(1); _Pragma("unroll") for (int m = 0; m < 4; ++m) _Pragma("unroll") for (int n = 0; n < 2; ++n) _Pragma("unroll") for (int k = 0; k < 2; ++k) \
;         acc[ai][bj][m][n] = __builtin_amdgcn_mfma_f32_16x16x32_bf16(Bt[n][k], At[m][k], acc[ai][bj][m][n], 0, 0, 0); __builtin_amdgcn_s_setprio(0); } while (0)
; #define PG8_WAIT_V(n) asm volatile("s_waitcnt vmcnt(" #n ")" ::: "memory")
; #define PG8_WAIT_L(n) asm volatile("s_waitcnt lgkmcnt(" #n ")" ::: "memory")
; #define PG8_BAR __builtin_amdgcn_s_barrier()
; #define PG8_SCHED __builtin_amdgcn_sched_barrier(0)
; template <class Epi>
; __device__ __forceinline__ void gemm_phase(LAS unsigned char* lds, const Gemm g, const Epi& E) {
;     ...
;             PG8_BAR; PG8_WAIT_L(0); PG8_MMA(1, 0, At, B0); PG8_BAR; PG8_SCHED;
;             PG8_STAGE(PG8_SB(0, 1), b2 + hstepB, voffB);
;             PG8_WAIT_V(6); PG8_BAR; PG8_MMA(1, 1, At, B1); PG8_BAR;
;             PG8_LDB(B0, 1, 0); PG8_SCHED; PG8_LDA(At, 1, 0); PG8_STAGE(PG8_SA(0, 1), a2 + hstepA, voffA);
;             PG8_WAIT_L(8); PG8_BAR; PG8_WAIT_L(0); PG8_MMA(0, 0, At, B0); PG8_BAR; PG8_SCHED;
;             PG8_LDB(B1, 1, 1); PG8_STAGE(PG8_SB(1, 0), b3, voffB);
;             PG8_BAR; PG8_WAIT_L(0); PG8_MMA(0, 1, At, B1); PG8_BAR;
;             PG8_LDA(At, 1, 1); PG8_STAGE(PG8_SA(1, 0), a3, voffA);
	s_add_u32 s72, s60, 0x40000
	s_addc_u32 s73, s61, 0
	s_add_i32 s74, s74, s1
	v_lshl_add_u64 v[74:75], s[72:73], 0, v[184:185]
	s_mov_b32 m0, s74
	s_nop 0
	global_load_lds_dwordx4 v[74:75], off
	v_lshl_add_u64 v[74:75], s[72:73], 0, v[180:181]
	s_add_i32 m0, s74, 0x2000
	s_nop 0
	global_load_lds_dwordx4 v[74:75], off
	s_waitcnt vmcnt(6)
	s_barrier
	s_setprio 1
	v_mfma_f32_16x16x32_bf16 v[54:57], v[192:195], v[126:129], v[54:57]
	v_mfma_f32_16x16x32_bf16 v[50:53], v[204:207], v[126:129], v[50:53]
	v_mfma_f32_16x16x32_bf16 v[38:41], v[192:195], v[134:137], v[38:41]
	v_mfma_f32_16x16x32_bf16 v[34:37], v[204:207], v[134:137], v[34:37]
	v_mfma_f32_16x16x32_bf16 v[22:25], v[192:195], v[154:157], v[22:25]
	v_mfma_f32_16x16x32_bf16 v[18:21], v[204:207], v[154:157], v[18:21]
	v_mfma_f32_16x16x32_bf16 v[6:9], v[192:195], v[170:173], v[6:9]
	v_mfma_f32_16x16x32_bf16 v[2:5], v[204:207], v[170:173], v[2:5]
	v_mfma_f32_16x16x32_bf16 v[54:57], v[196:199], v[130:133], v[54:57]
	v_mfma_f32_16x16x32_bf16 v[50:53], v[226:229], v[130:133], v[50:53]
	v_mfma_f32_16x16x32_bf16 v[38:41], v[196:199], v[146:149], v[38:41]
	v_mfma_f32_16x16x32_bf16 v[34:37], v[226:229], v[146:149], v[34:37]
	v_mfma_f32_16x16x32_bf16 v[22:25], v[196:199], v[158:161], v[22:25]
	v_mfma_f32_16x16x32_bf16 v[18:21], v[226:229], v[158:161], v[18:21]
	v_mfma_f32_16x16x32_bf16 v[6:9], v[196:199], v[174:177], v[6:9]
	v_mfma_f32_16x16x32_bf16 v[2:5], v[226:229], v[174:177], v[2:5]
	s_setprio 0
	s_add_i32 s72, 0, 0x18000
	v_add_u32_e32 v94, s72, v201
	s_barrier
	ds_read_b128 v[74:77], v94
	ds_read_b128 v[82:85], v94 offset:1024
	ds_read_b128 v[86:89], v94 offset:2048
	ds_read_b128 v[94:97], v94 offset:3072
	s_add_u32 s64, s64, 0x40000
	s_addc_u32 s65, s65, 0
	s_mov_b32 m0, s31
	v_lshl_add_u64 v[146:147], s[64:65], 0, v[186:187]
	ds_read_b128 v[126:129], v202 offset:32768
	ds_read_b128 v[130:133], v202 offset:33792
	ds_read_b128 v[134:137], v202 offset:34816
	ds_read_b128 v[154:157], v202 offset:35840
	ds_read_b128 v[158:161], v202 offset:36864
	ds_read_b128 v[170:173], v202 offset:37888
	ds_read_b128 v[174:177], v202 offset:38912
	ds_read_b128 v[192:195], v202 offset:39936
	global_load_lds_dwordx4 v[146:147], off
	v_lshl_add_u64 v[146:147], s[64:65], 0, v[182:183]
	s_mov_b32 m0, s36
	s_nop 0
	global_load_lds_dwordx4 v[146:147], off
	s_waitcnt lgkmcnt(8)
	s_barrier
	s_waitcnt lgkmcnt(0)
	s_setprio 1
	v_mfma_f32_16x16x32_bf16 v[146:149], v[74:77], v[126:129], v[166:169]
	v_mfma_f32_16x16x32_bf16 v[166:169], v[82:85], v[130:133], v[146:149]
	v_mfma_f32_16x16x32_bf16 v[146:149], v[86:89], v[126:129], v[162:165]
	v_mfma_f32_16x16x32_bf16 v[142:145], v[74:77], v[134:137], v[142:145]
	v_mfma_f32_16x16x32_bf16 v[138:141], v[86:89], v[134:137], v[138:141]
	v_mfma_f32_16x16x32_bf16 v[118:121], v[74:77], v[158:161], v[118:121]
	v_mfma_f32_16x16x32_bf16 v[114:117], v[86:89], v[158:161], v[114:117]
	v_mfma_f32_16x16x32_bf16 v[90:93], v[74:77], v[174:177], v[90:93]
	v_mfma_f32_16x16x32_bf16 v[78:81], v[86:89], v[174:177], v[78:81]
	v_mfma_f32_16x16x32_bf16 v[162:165], v[94:97], v[130:133], v[146:149]
	v_mfma_f32_16x16x32_bf16 v[142:145], v[82:85], v[154:157], v[142:145]
	v_mfma_f32_16x16x32_bf16 v[138:141], v[94:97], v[154:157], v[138:141]
	v_mfma_f32_16x16x32_bf16 v[118:121], v[82:85], v[170:173], v[118:121]
	v_mfma_f32_16x16x32_bf16 v[114:117], v[94:97], v[170:173], v[114:117]
	v_mfma_f32_16x16x32_bf16 v[90:93], v[82:85], v[192:195], v[90:93]
	v_mfma_f32_16x16x32_bf16 v[78:81], v[94:97], v[192:195], v[78:81]
	s_setprio 0
	s_barrier
	s_add_i32 s64, 0, 0x1c000
	v_add_u32_e32 v146, s64, v201
	s_add_i32 s65, s72, s1
	ds_read_b128 v[196:199], v146
	ds_read_b128 v[204:207], v146 offset:1024
	ds_read_b128 v[226:229], v146 offset:2048
	ds_read_b128 v[230:233], v146 offset:3072
	v_lshl_add_u64 v[146:147], v[208:209], 0, s[86:87]
	s_mov_b32 m0, s65
	s_nop 0
	global_load_lds_dwordx4 v[146:147], off
	v_lshl_add_u64 v[146:147], v[234:235], 0, s[86:87]
	s_add_i32 m0, s65, 0x2000
	s_nop 0
	global_load_lds_dwordx4 v[146:147], off
	s_barrier
	s_waitcnt lgkmcnt(0)
	s_setprio 1
	v_mfma_f32_16x16x32_bf16 v[146:149], v[196:199], v[126:129], v[150:153]
	v_mfma_f32_16x16x32_bf16 v[106:109], v[226:229], v[126:129], v[106:109]
	v_mfma_f32_16x16x32_bf16 v[150:153], v[204:207], v[130:133], v[146:149]
	v_mfma_f32_16x16x32_bf16 v[146:149], v[230:233], v[130:133], v[106:109]
	v_mfma_f32_16x16x32_bf16 v[106:109], v[196:199], v[134:137], v[110:113]
	v_mfma_f32_16x16x32_bf16 v[126:129], v[204:207], v[154:157], v[106:109]
	v_mfma_f32_16x16x32_bf16 v[106:109], v[226:229], v[134:137], v[122:125]
	v_mfma_f32_16x16x32_bf16 v[102:105], v[196:199], v[158:161], v[102:105]
	v_mfma_f32_16x16x32_bf16 v[98:101], v[226:229], v[158:161], v[98:101]
	v_mfma_f32_16x16x32_bf16 v[70:73], v[196:199], v[174:177], v[70:73]
	v_mfma_f32_16x16x32_bf16 v[66:69], v[226:229], v[174:177], v[66:69]
	v_mfma_f32_16x16x32_bf16 v[122:125], v[230:233], v[154:157], v[106:109]
	v_mfma_f32_16x16x32_bf16 v[102:105], v[204:207], v[170:173], v[102:105]
	v_mfma_f32_16x16x32_bf16 v[98:101], v[230:233], v[170:173], v[98:101]
	v_mfma_f32_16x16x32_bf16 v[70:73], v[204:207], v[192:195], v[70:73]
	v_mfma_f32_16x16x32_bf16 v[66:69], v[230:233], v[192:195], v[66:69]
	s_setprio 0
	s_mov_b32 m0, s50
	v_lshl_add_u64 v[192:193], v[236:237], 0, s[86:87]
	s_barrier
; #define PG8_STAGE(bufoff, gbase, voff) do { _Pragma("unroll") for (int _i = 0; _i < 2; ++_i) \
;         __builtin_amdgcn_global_load_lds((const unsigned*)((const char*)(gbase) + (voff)[_i]), (LAS unsigned*)(lds + (bufoff) + ldsw + _i * 8192), 16, 0, 0); } while (0)
; #define PG8_LDA(dst, b, h) do { _Pragma("unroll") for (int m = 0; m < 4; ++m) _Pragma("unroll") for (int k = 0; k < 2; ++k) dst[m][k] = *(const LAS bf16x8*)(lds + PG8_SA(b, h) + aoff + m * 2048 + k * 1024); } while (0)
; #define PG8_MMA(ai, bj, At, Bt) do { __builtin_amdgcn_s_setprio(1); _Pragma("unroll") for (int m = 0; m < 4; ++m) _Pragma("unroll") for (int n = 0; n < 2; ++n) _Pragma("unroll") for (int k = 0; k < 2; ++k) \
;         acc[ai][bj][m][n] = __builtin_amdgcn_mfma_f32_16x16x32_bf16(Bt[n][k], At[m][k], acc[ai][bj][m][n], 0, 0, 0); __builtin_amdgcn_s_setprio(0); } while (0)
; #define PG8_WAIT_V(n) asm volatile("s_waitcnt vmcnt(" #n ")" ::: "memory")
; template <class Epi>
; __device__ __forceinline__ void gemm_phase(LAS unsigned char* lds, const Gemm g, const Epi& E) {
;     ...
;             PG8_LDA(At, 1, 1); PG8_STAGE(PG8_SA(1, 0), a3, voffA);
;             PG8_BAR; PG8_WAIT_L(0); PG8_MMA(1, 0, At, B0); PG8_BAR; PG8_SCHED;
;             PG8_STAGE(PG8_SB(1, 1), b3 + hstepB, voffB);
;             PG8_WAIT_V(6); PG8_BAR; PG8_MMA(1, 1, At, B1); PG8_BAR;
;     __device__ __forceinline__ void operator()(const AccT& acc, const Unit& u, int wr, int wc, int fr, int fq) const {
;     ...
;         const int gpm = mapA.src(u.pm);
;         const bool isq = u.pn < 4, isv = u.pn >= 8;
;         const bool lat = gpm >= 32 && !isv;
;         bf16_t* base = isq ? Q : (isv ? Vv + (size_t)(u.pn - 8) * 256 : Kk);
;         const int hh = isv ? 0 : (u.pn & 3);
;         const int ldo = isv ? 2048 : 1024;
;         const float osc = isq ? 0.0625f : 1.0f;
;         const int p0 = 16 * wc + 4 * fq;
;         f32x4 ctR[2][2], ctC[4][2];
;         if (lat) {
; #pragma unroll
;             for (int ai = 0; ai < 2; ++ai) { const int pr = ((gpm - 32) * 4 + 2 * ai + wr) & 31;
;                 ctR[ai][0] = *(const f32x4*)(cs + pr * 64 + p0); ctR[ai][1] = *(const f32x4*)(cs + pr * 64 + p0 + 2); }
; #pragma unroll
;             for (int m = 0; m < 4; ++m) { const int pc = m * 16 + fr;
;                 ctC[m][0] = *(const f32x4*)(cs + pc * 64 + p0); ctC[m][1] = *(const f32x4*)(cs + pc * 64 + p0 + 2); }
	ds_read_b128 v[106:109], v202 offset:49152
	ds_read_b128 v[110:113], v202 offset:50176
	ds_read_b128 v[130:133], v202 offset:51200
	ds_read_b128 v[134:137], v202 offset:52224
	ds_read_b128 v[154:157], v202 offset:53248
	ds_read_b128 v[158:161], v202 offset:54272
	ds_read_b128 v[170:173], v202 offset:55296
	ds_read_b128 v[174:177], v202 offset:56320
	global_load_lds_dwordx4 v[192:193], off
	v_lshl_add_u64 v[192:193], v[238:239], 0, s[86:87]
	s_mov_b32 m0, s66
	s_nop 0
	global_load_lds_dwordx4 v[192:193], off
	s_barrier
	s_waitcnt lgkmcnt(0)
	s_setprio 1
	v_mfma_f32_16x16x32_bf16 v[62:65], v[74:77], v[106:109], v[62:65]
	v_mfma_f32_16x16x32_bf16 v[58:61], v[86:89], v[106:109], v[58:61]
	v_mfma_f32_16x16x32_bf16 v[46:49], v[74:77], v[130:133], v[46:49]
	v_mfma_f32_16x16x32_bf16 v[42:45], v[86:89], v[130:133], v[42:45]
	v_mfma_f32_16x16x32_bf16 v[30:33], v[74:77], v[154:157], v[30:33]
	v_mfma_f32_16x16x32_bf16 v[26:29], v[86:89], v[154:157], v[26:29]
	v_mfma_f32_16x16x32_bf16 v[14:17], v[74:77], v[170:173], v[14:17]
	v_mfma_f32_16x16x32_bf16 v[10:13], v[86:89], v[170:173], v[10:13]
	v_mfma_f32_16x16x32_bf16 v[62:65], v[82:85], v[110:113], v[62:65]
	v_mfma_f32_16x16x32_bf16 v[58:61], v[94:97], v[110:113], v[58:61]
	v_mfma_f32_16x16x32_bf16 v[46:49], v[82:85], v[134:137], v[46:49]
	v_mfma_f32_16x16x32_bf16 v[42:45], v[94:97], v[134:137], v[42:45]
	v_mfma_f32_16x16x32_bf16 v[30:33], v[82:85], v[158:161], v[30:33]
	v_mfma_f32_16x16x32_bf16 v[26:29], v[94:97], v[158:161], v[26:29]
	v_mfma_f32_16x16x32_bf16 v[14:17], v[82:85], v[174:177], v[14:17]
	v_mfma_f32_16x16x32_bf16 v[10:13], v[94:97], v[174:177], v[10:13]
	s_setprio 0
	s_barrier
	s_add_u32 s60, s60, 0x40080
	s_addc_u32 s61, s61, 0
	s_add_i32 s64, s64, s1
	v_lshl_add_u64 v[74:75], s[60:61], 0, v[184:185]
	s_mov_b32 m0, s64
	s_nop 0
	global_load_lds_dwordx4 v[74:75], off
	v_lshl_add_u64 v[74:75], s[60:61], 0, v[180:181]
	s_add_i32 m0, s64, 0x2000
	s_nop 0
	global_load_lds_dwordx4 v[74:75], off
	s_waitcnt vmcnt(6)
	s_barrier
	s_setprio 1
	v_mfma_f32_16x16x32_bf16 v[54:57], v[196:199], v[106:109], v[54:57]
	v_mfma_f32_16x16x32_bf16 v[50:53], v[226:229], v[106:109], v[50:53]
	v_mfma_f32_16x16x32_bf16 v[38:41], v[196:199], v[130:133], v[38:41]
	v_mfma_f32_16x16x32_bf16 v[34:37], v[226:229], v[130:133], v[34:37]
	v_mfma_f32_16x16x32_bf16 v[22:25], v[196:199], v[154:157], v[22:25]
	v_mfma_f32_16x16x32_bf16 v[18:21], v[226:229], v[154:157], v[18:21]
	v_mfma_f32_16x16x32_bf16 v[6:9], v[196:199], v[170:173], v[6:9]
	v_mfma_f32_16x16x32_bf16 v[2:5], v[226:229], v[170:173], v[2:5]
	v_mfma_f32_16x16x32_bf16 v[54:57], v[204:207], v[110:113], v[54:57]
	v_mfma_f32_16x16x32_bf16 v[50:53], v[230:233], v[110:113], v[50:53]
	v_mfma_f32_16x16x32_bf16 v[38:41], v[204:207], v[134:137], v[38:41]
	v_mfma_f32_16x16x32_bf16 v[34:37], v[230:233], v[134:137], v[34:37]
	v_mfma_f32_16x16x32_bf16 v[22:25], v[204:207], v[158:161], v[22:25]
	v_mfma_f32_16x16x32_bf16 v[18:21], v[230:233], v[158:161], v[18:21]
	v_mfma_f32_16x16x32_bf16 v[6:9], v[204:207], v[174:177], v[6:9]
	v_mfma_f32_16x16x32_bf16 v[2:5], v[230:233], v[174:177], v[2:5]
	s_setprio 0
	s_add_i32 s53, s53, 2
	s_add_u32 s4, s4, 0x100
	s_addc_u32 s5, s5, 0
	s_add_u32 s15, s15, 0x100
	s_addc_u32 s52, s52, 0
	s_cmp_gt_u32 s53, 13
	s_barrier
	s_cbranch_scc0 .LBB0_331
	s_cmp_lt_i32 s10, 16
	s_cselect_b32 s4, s68, s18
	s_add_i32 s15, s10, s4
	s_cmp_lt_i32 s11, 8
	s_cselect_b64 s[60:61], -1, 0
	s_cmp_gt_i32 s15, 31
	s_cselect_b64 s[4:5], -1, 0
	s_and_b64 s[52:53], s[60:61], s[4:5]
	v_cndmask_b32_e64 v74, 0, 1, s[52:53]
	v_mov_b32_e32 v194, v200
	v_mov_b32_e32 v193, v1
	v_cmp_ne_u32_e64 s[4:5], 1, v74
	s_andn2_b64 vcc, exec, s[52:53]
	s_cbranch_vccnz .LBB0_334
	v_lshl_add_u32 v74, v193, 2, s67
	v_readlane_b32 s52, v254, 2
	s_lshl_b32 s15, s15, 8
	v_ashrrev_i32_e32 v75, 31, v74
	v_readlane_b32 s53, v254, 3
	s_add_i32 s15, s15, s44
	s_nop 0
	v_lshl_add_u64 v[74:75], v[74:75], 3, s[52:53]
	s_and_b32 s52, s15, 0x7c0
	s_addk_i32 s15, 0x80
	s_lshl_b32 s76, s52, 3
	s_and_b32 s15, s15, 0x7c0
	v_lshl_add_u64 v[76:77], v[74:75], 0, s[76:77]
	s_lshl_b32 s76, s15, 3
	global_load_dwordx4 v[170:173], v[76:77], off offset:16
	global_load_dwordx4 v[174:177], v[76:77], off
	v_lshl_add_u64 v[76:77], v[74:75], 0, s[76:77]
	global_load_dwordx4 v[86:89], v[76:77], off offset:16
	global_load_dwordx4 v[94:97], v[76:77], off
	v_lshlrev_b32_e32 v76, 6, v194
	v_ashrrev_i32_e32 v77, 31, v76
	v_lshl_add_u64 v[82:83], v[76:77], 3, v[74:75]
	global_load_dwordx4 v[154:157], v[82:83], off offset:16
	global_load_dwordx4 v[158:161], v[82:83], off
	v_add_u32_e32 v82, 0x400, v76
	v_ashrrev_i32_e32 v83, 31, v82
	v_lshl_add_u64 v[82:83], v[82:83], 3, v[74:75]
	global_load_dwordx4 v[130:133], v[82:83], off offset:16
	global_load_dwordx4 v[134:137], v[82:83], off
	v_add_u32_e32 v82, 0x800, v76
	v_ashrrev_i32_e32 v83, 31, v82
	v_add_u32_e32 v76, 0xc00, v76
	v_lshl_add_u64 v[82:83], v[82:83], 3, v[74:75]
	v_ashrrev_i32_e32 v77, 31, v76
	global_load_dwordx4 v[106:109], v[82:83], off offset:16
	global_load_dwordx4 v[110:113], v[82:83], off
	v_lshl_add_u64 v[82:83], v[76:77], 3, v[74:75]
	global_load_dwordx4 v[74:77], v[82:83], off offset:16
	s_nop 0
	global_load_dwordx4 v[82:85], v[82:83], off

; #define PG8_STAGE(bufoff, gbase, voff) do { _Pragma("unroll") for (int _i = 0; _i < 2; ++_i) \
;         __builtin_amdgcn_global_load_lds((const unsigned*)((const char*)(gbase) + (voff)[_i]), (LAS unsigned*)(lds + (bufoff) + ldsw + _i * 8192), 16, 0, 0); } while (0)
; #define PG8_LDA(dst, b, h) do { _Pragma("unroll") for (int m = 0; m < 4; ++m) _Pragma("unroll") for (int k = 0; k < 2; ++k) dst[m][k] = *(const LAS bf16x8*)(lds + PG8_SA(b, h) + aoff + m * 2048 + k * 1024); } while (0)
; #define PG8_LDB(dst, b, h) do { _Pragma("unroll") for (int n = 0; n < 2; ++n) _Pragma("unroll") for (int k = 0; k < 2; ++k) dst[n][k] = *(const LAS bf16x8*)(lds + PG8_SB(b, h) + boff + n * 2048 + k * 1024); } while (0)
; #define PG8_MMA(ai, bj, At, Bt) do { __builtin_amdgcn_s_setprio(1); _Pragma("unroll") for (int m = 0; m < 4; ++m) _Pragma("unroll") for (int n = 0; n < 2; ++n) _Pragma("unroll") for (int k = 0; k < 2; ++k) \
;         acc[ai][bj][m][n] = __builtin_amdgcn_mfma_f32_16x16x32_bf16(Bt[n][k], At[m][k], acc[ai][bj][m][n], 0, 0, 0); __builtin_amdgcn_s_setprio(0); } while (0)
; #define PG8_WAIT_V(n) asm volatile("s_waitcnt vmcnt(" #n ")" ::: "memory")
; #define PG8_WAIT_L(n) asm volatile("s_waitcnt lgkmcnt(" #n ")" ::: "memory")
; #define PG8_BAR __builtin_amdgcn_s_barrier()
; #define PG8_SCHED __builtin_amdgcn_sched_barrier(0)
; template <class Epi>
; __device__ __forceinline__ void gemm_phase(LAS unsigned char* lds, const Gemm g, const Epi& E) {
;     ...
;             PG8_LDB(B0, 0, 0); PG8_SCHED; PG8_LDA(At, 0, 0); PG8_STAGE(PG8_SA(1, 1), a1 + hstepA, voffA);
;             PG8_WAIT_L(8); PG8_BAR; PG8_WAIT_L(0); PG8_MMA(0, 0, At, B0); PG8_BAR; PG8_SCHED;
;             PG8_LDB(B1, 0, 1); PG8_STAGE(PG8_SB(0, 0), b2, voffB);
;             PG8_BAR; PG8_WAIT_L(0); PG8_MMA(0, 1, At, B1); PG8_BAR;
;             PG8_LDA(At, 0, 1); PG8_STAGE(PG8_SA(0, 0), a2, voffA);
;             PG8_BAR; PG8_WAIT_L(0); PG8_MMA(1, 0, At, B0); PG8_BAR; PG8_SCHED;
;             PG8_STAGE(PG8_SB(0, 1), b2 + hstepB, voffB);
;             PG8_WAIT_V(6); PG8_BAR; PG8_MMA(1, 1, At, B1); PG8_BAR;
.LBB0_475:
	s_add_u32 s16, s14, 0xfffc0080
	s_addc_u32 s17, s15, -1
	s_add_i32 s66, 0, 0x10000
	v_add_u32_e32 v86, s66, v226
	ds_read_b128 v[66:69], v86
	ds_read_b128 v[70:73], v86 offset:1024
	ds_read_b128 v[82:85], v86 offset:2048
	ds_read_b128 v[86:89], v86 offset:3072
	s_cmp_eq_u32 s65, 12
	s_cselect_b32 s29, s11, s17
	s_cselect_b32 s28, s10, s16
	s_cselect_b32 s17, s5, s53
	s_cselect_b32 s16, s4, s9
	v_lshl_add_u64 v[192:193], s[14:15], 0, v[174:175]
	s_add_i32 m0, s13, 0xc000
	ds_read_b128 v[146:149], v227
	ds_read_b128 v[150:153], v227 offset:1024
	ds_read_b128 v[154:157], v227 offset:2048
	ds_read_b128 v[158:161], v227 offset:3072
	ds_read_b128 v[162:165], v227 offset:4096
	ds_read_b128 v[180:183], v227 offset:5120
	ds_read_b128 v[184:187], v227 offset:6144
	ds_read_b128 v[188:191], v227 offset:7168
	global_load_lds_dwordx4 v[192:193], off
	v_lshl_add_u64 v[192:193], s[14:15], 0, v[176:177]
	s_add_i32 m0, s13, 0xe000
	s_nop 0
	global_load_lds_dwordx4 v[192:193], off
	s_waitcnt lgkmcnt(8)
	s_barrier
	s_waitcnt lgkmcnt(0)
	s_setprio 1
	v_mfma_f32_16x16x32_bf16 v[142:145], v[66:69], v[146:149], v[142:145]
	v_mfma_f32_16x16x32_bf16 v[138:141], v[82:85], v[146:149], v[138:141]
	v_mfma_f32_16x16x32_bf16 v[126:129], v[66:69], v[154:157], v[126:129]
	v_mfma_f32_16x16x32_bf16 v[122:125], v[82:85], v[154:157], v[122:125]
	v_mfma_f32_16x16x32_bf16 v[110:113], v[66:69], v[162:165], v[110:113]
	v_mfma_f32_16x16x32_bf16 v[106:109], v[82:85], v[162:165], v[106:109]
	v_mfma_f32_16x16x32_bf16 v[94:97], v[66:69], v[184:187], v[94:97]
	v_mfma_f32_16x16x32_bf16 v[90:93], v[82:85], v[184:187], v[90:93]
	v_mfma_f32_16x16x32_bf16 v[142:145], v[70:73], v[150:153], v[142:145]
	v_mfma_f32_16x16x32_bf16 v[138:141], v[86:89], v[150:153], v[138:141]
	v_mfma_f32_16x16x32_bf16 v[126:129], v[70:73], v[158:161], v[126:129]
	v_mfma_f32_16x16x32_bf16 v[122:125], v[86:89], v[158:161], v[122:125]
	v_mfma_f32_16x16x32_bf16 v[110:113], v[70:73], v[180:183], v[110:113]
	v_mfma_f32_16x16x32_bf16 v[106:109], v[86:89], v[180:183], v[106:109]
	v_mfma_f32_16x16x32_bf16 v[94:97], v[70:73], v[188:191], v[94:97]
	v_mfma_f32_16x16x32_bf16 v[90:93], v[86:89], v[188:191], v[90:93]
	s_setprio 0
	s_barrier
	s_add_i32 s68, 0, 0x14000
	s_add_i32 s66, s66, s18
	v_add_u32_e32 v204, s68, v226
	v_lshl_add_u64 v[208:209], s[16:17], 0, v[170:171]
	s_mov_b32 m0, s66
	ds_read_b128 v[192:195], v204
	ds_read_b128 v[196:199], v204 offset:1024
	ds_read_b128 v[200:203], v204 offset:2048
	ds_read_b128 v[204:207], v204 offset:3072
	global_load_lds_dwordx4 v[208:209], off
	v_lshl_add_u64 v[228:229], s[16:17], 0, v[166:167]
	s_add_i32 m0, s66, 0x2000
	s_nop 0
	global_load_lds_dwordx4 v[228:229], off
	s_barrier
	s_waitcnt lgkmcnt(0)
	s_setprio 1
	v_mfma_f32_16x16x32_bf16 v[134:137], v[192:195], v[146:149], v[134:137]
	v_mfma_f32_16x16x32_bf16 v[130:133], v[200:203], v[146:149], v[130:133]
	v_mfma_f32_16x16x32_bf16 v[118:121], v[192:195], v[154:157], v[118:121]
	v_mfma_f32_16x16x32_bf16 v[114:117], v[200:203], v[154:157], v[114:117]
	v_mfma_f32_16x16x32_bf16 v[102:105], v[192:195], v[162:165], v[102:105]
	v_mfma_f32_16x16x32_bf16 v[98:101], v[200:203], v[162:165], v[98:101]
	v_mfma_f32_16x16x32_bf16 v[78:81], v[192:195], v[184:187], v[78:81]
	v_mfma_f32_16x16x32_bf16 v[74:77], v[200:203], v[184:187], v[74:77]
	v_mfma_f32_16x16x32_bf16 v[134:137], v[196:199], v[150:153], v[134:137]
	v_mfma_f32_16x16x32_bf16 v[130:133], v[204:207], v[150:153], v[130:133]
	v_mfma_f32_16x16x32_bf16 v[118:121], v[196:199], v[158:161], v[118:121]
	v_mfma_f32_16x16x32_bf16 v[114:117], v[204:207], v[158:161], v[114:117]
	v_mfma_f32_16x16x32_bf16 v[102:105], v[196:199], v[180:183], v[102:105]
	v_mfma_f32_16x16x32_bf16 v[98:101], v[204:207], v[180:183], v[98:101]
	v_mfma_f32_16x16x32_bf16 v[78:81], v[196:199], v[188:191], v[78:81]
	v_mfma_f32_16x16x32_bf16 v[74:77], v[204:207], v[188:191], v[74:77]
	s_setprio 0
	s_mov_b32 m0, s13
	v_lshl_add_u64 v[230:231], s[28:29], 0, v[172:173]
	s_barrier
	ds_read_b128 v[146:149], v227 offset:16384
	ds_read_b128 v[150:153], v227 offset:17408
	ds_read_b128 v[154:157], v227 offset:18432
	ds_read_b128 v[158:161], v227 offset:19456
	ds_read_b128 v[162:165], v227 offset:20480
	ds_read_b128 v[180:183], v227 offset:21504
	ds_read_b128 v[184:187], v227 offset:22528
	ds_read_b128 v[188:191], v227 offset:23552
	global_load_lds_dwordx4 v[230:231], off
	v_lshl_add_u64 v[232:233], s[28:29], 0, v[168:169]
	s_mov_b32 m0, s31
	s_nop 0
	global_load_lds_dwordx4 v[232:233], off
	s_barrier
	s_waitcnt lgkmcnt(0)
	s_setprio 1
	v_mfma_f32_16x16x32_bf16 v[62:65], v[66:69], v[146:149], v[62:65]
	v_mfma_f32_16x16x32_bf16 v[58:61], v[82:85], v[146:149], v[58:61]
	v_mfma_f32_16x16x32_bf16 v[46:49], v[66:69], v[154:157], v[46:49]
	v_mfma_f32_16x16x32_bf16 v[42:45], v[82:85], v[154:157], v[42:45]
	v_mfma_f32_16x16x32_bf16 v[30:33], v[66:69], v[162:165], v[30:33]
	v_mfma_f32_16x16x32_bf16 v[26:29], v[82:85], v[162:165], v[26:29]
	v_mfma_f32_16x16x32_bf16 v[14:17], v[66:69], v[184:187], v[14:17]
	v_mfma_f32_16x16x32_bf16 v[10:13], v[82:85], v[184:187], v[10:13]
	v_mfma_f32_16x16x32_bf16 v[62:65], v[70:73], v[150:153], v[62:65]
	v_mfma_f32_16x16x32_bf16 v[58:61], v[86:89], v[150:153], v[58:61]
	v_mfma_f32_16x16x32_bf16 v[46:49], v[70:73], v[158:161], v[46:49]
	v_mfma_f32_16x16x32_bf16 v[42:45], v[86:89], v[158:161], v[42:45]
	v_mfma_f32_16x16x32_bf16 v[30:33], v[70:73], v[180:183], v[30:33]
	v_mfma_f32_16x16x32_bf16 v[26:29], v[86:89], v[180:183], v[26:29]
	v_mfma_f32_16x16x32_bf16 v[14:17], v[70:73], v[188:191], v[14:17]
	v_mfma_f32_16x16x32_bf16 v[10:13], v[86:89], v[188:191], v[10:13]
	s_setprio 0
	s_barrier
; #define PG8_STAGE(bufoff, gbase, voff) do { _Pragma("unroll") for (int _i = 0; _i < 2; ++_i) \
;         __builtin_amdgcn_global_load_lds((const unsigned*)((const char*)(gbase) + (voff)[_i]), (LAS unsigned*)(lds + (bufoff) + ldsw + _i * 8192), 16, 0, 0); } while (0)
; #define PG8_LDA(dst, b, h) do { _Pragma("unroll") for (int m = 0; m < 4; ++m) _Pragma("unroll") for (int k = 0; k < 2; ++k) dst[m][k] = *(const LAS bf16x8*)(lds + PG8_SA(b, h) + aoff + m * 2048 + k * 1024); } while (0)
; #define PG8_LDB(dst, b, h) do { _Pragma("unroll") for (int n = 0; n < 2; ++n) _Pragma("unroll") for (int k = 0; k < 2; ++k) dst[n][k] = *(const LAS bf16x8*)(lds + PG8_SB(b, h) + boff + n * 2048 + k * 1024); } while (0)
; #define PG8_MMA(ai, bj, At, Bt) do { __builtin_amdgcn_s_setprio(1); _Pragma("unroll") for (int m = 0; m < 4; ++m) _Pragma("unroll") for (int n = 0; n < 2; ++n) _Pragma("unroll") for (int k = 0; k < 2; ++k) \
;         acc[ai][bj][m][n] = __builtin_amdgcn_mfma_f32_16x16x32_bf16(Bt[n][k], At[m][k], acc[ai][bj][m][n], 0, 0, 0); __builtin_amdgcn_s_setprio(0); } while (0)
; #define PG8_WAIT_V(n) asm volatile("s_waitcnt vmcnt(" #n ")" ::: "memory")
; #define PG8_WAIT_L(n) asm volatile("s_waitcnt lgkmcnt(" #n ")" ::: "memory")
; #define PG8_BAR __builtin_amdgcn_s_barrier()
; #define PG8_SCHED __builtin_amdgcn_sched_barrier(0)
; template <class Epi>
; __device__ __forceinline__ void gemm_phase(LAS unsigned char* lds, const Gemm g, const Epi& E) {
;     ...
;             PG8_BAR; PG8_WAIT_L(0); PG8_MMA(1, 0, At, B0); PG8_BAR; PG8_SCHED;
;             PG8_STAGE(PG8_SB(0, 1), b2 + hstepB, voffB);
;             PG8_WAIT_V(6); PG8_BAR; PG8_MMA(1, 1, At, B1); PG8_BAR;
;             PG8_LDB(B0, 1, 0); PG8_SCHED; PG8_LDA(At, 1, 0); PG8_STAGE(PG8_SA(0, 1), a2 + hstepA, voffA);
;             PG8_WAIT_L(8); PG8_BAR; PG8_WAIT_L(0); PG8_MMA(0, 0, At, B0); PG8_BAR; PG8_SCHED;
;             PG8_LDB(B1, 1, 1); PG8_STAGE(PG8_SB(1, 0), b3, voffB);
;             PG8_BAR; PG8_WAIT_L(0); PG8_MMA(0, 1, At, B1); PG8_BAR;
;             PG8_LDA(At, 1, 1); PG8_STAGE(PG8_SA(1, 0), a3, voffA);
	s_add_u32 s66, s16, 0x40000
	s_addc_u32 s67, s17, 0
	s_add_i32 s68, s68, s18
	v_lshl_add_u64 v[66:67], s[66:67], 0, v[170:171]
	s_mov_b32 m0, s68
	s_nop 0
	global_load_lds_dwordx4 v[66:67], off
	v_lshl_add_u64 v[66:67], s[66:67], 0, v[166:167]
	s_add_i32 m0, s68, 0x2000
	s_nop 0
	global_load_lds_dwordx4 v[66:67], off
	s_waitcnt vmcnt(6)
	s_barrier
	s_setprio 1
	v_mfma_f32_16x16x32_bf16 v[54:57], v[192:195], v[146:149], v[54:57]
	v_mfma_f32_16x16x32_bf16 v[50:53], v[200:203], v[146:149], v[50:53]
	v_mfma_f32_16x16x32_bf16 v[38:41], v[192:195], v[154:157], v[38:41]
	v_mfma_f32_16x16x32_bf16 v[34:37], v[200:203], v[154:157], v[34:37]
	v_mfma_f32_16x16x32_bf16 v[22:25], v[192:195], v[162:165], v[22:25]
	v_mfma_f32_16x16x32_bf16 v[18:21], v[200:203], v[162:165], v[18:21]
	v_mfma_f32_16x16x32_bf16 v[6:9], v[192:195], v[184:187], v[6:9]
	v_mfma_f32_16x16x32_bf16 v[2:5], v[200:203], v[184:187], v[2:5]
	v_mfma_f32_16x16x32_bf16 v[54:57], v[196:199], v[150:153], v[54:57]
	v_mfma_f32_16x16x32_bf16 v[50:53], v[204:207], v[150:153], v[50:53]
	v_mfma_f32_16x16x32_bf16 v[38:41], v[196:199], v[158:161], v[38:41]
	v_mfma_f32_16x16x32_bf16 v[34:37], v[204:207], v[158:161], v[34:37]
	v_mfma_f32_16x16x32_bf16 v[22:25], v[196:199], v[180:183], v[22:25]
	v_mfma_f32_16x16x32_bf16 v[18:21], v[204:207], v[180:183], v[18:21]
	v_mfma_f32_16x16x32_bf16 v[6:9], v[196:199], v[188:191], v[6:9]
	v_mfma_f32_16x16x32_bf16 v[2:5], v[204:207], v[188:191], v[2:5]
	s_setprio 0
	s_add_i32 s66, 0, 0x18000
	v_add_u32_e32 v86, s66, v226
	s_barrier
	ds_read_b128 v[66:69], v86
	ds_read_b128 v[70:73], v86 offset:1024
	ds_read_b128 v[82:85], v86 offset:2048
	ds_read_b128 v[86:89], v86 offset:3072
	s_add_u32 s28, s28, 0x40000
	s_addc_u32 s29, s29, 0
	s_mov_b32 m0, s36
	v_lshl_add_u64 v[192:193], s[28:29], 0, v[172:173]
	ds_read_b128 v[146:149], v227 offset:32768
	ds_read_b128 v[150:153], v227 offset:33792
	ds_read_b128 v[154:157], v227 offset:34816
	ds_read_b128 v[158:161], v227 offset:35840
	ds_read_b128 v[162:165], v227 offset:36864
	ds_read_b128 v[180:183], v227 offset:37888
	ds_read_b128 v[184:187], v227 offset:38912
	ds_read_b128 v[188:191], v227 offset:39936
	global_load_lds_dwordx4 v[192:193], off
	v_lshl_add_u64 v[192:193], s[28:29], 0, v[168:169]
	s_mov_b32 m0, s44
	s_nop 0
	global_load_lds_dwordx4 v[192:193], off
	s_waitcnt lgkmcnt(8)
	s_barrier
	s_waitcnt lgkmcnt(0)
	s_setprio 1
	v_mfma_f32_16x16x32_bf16 v[142:145], v[66:69], v[146:149], v[142:145]
	v_mfma_f32_16x16x32_bf16 v[138:141], v[82:85], v[146:149], v[138:141]
	v_mfma_f32_16x16x32_bf16 v[126:129], v[66:69], v[154:157], v[126:129]
	v_mfma_f32_16x16x32_bf16 v[122:125], v[82:85], v[154:157], v[122:125]
	v_mfma_f32_16x16x32_bf16 v[110:113], v[66:69], v[162:165], v[110:113]
	v_mfma_f32_16x16x32_bf16 v[106:109], v[82:85], v[162:165], v[106:109]
	v_mfma_f32_16x16x32_bf16 v[94:97], v[66:69], v[184:187], v[94:97]
	v_mfma_f32_16x16x32_bf16 v[90:93], v[82:85], v[184:187], v[90:93]
	v_mfma_f32_16x16x32_bf16 v[142:145], v[70:73], v[150:153], v[142:145]
	v_mfma_f32_16x16x32_bf16 v[138:141], v[86:89], v[150:153], v[138:141]
	v_mfma_f32_16x16x32_bf16 v[126:129], v[70:73], v[158:161], v[126:129]
	v_mfma_f32_16x16x32_bf16 v[122:125], v[86:89], v[158:161], v[122:125]
	v_mfma_f32_16x16x32_bf16 v[110:113], v[70:73], v[180:183], v[110:113]
	v_mfma_f32_16x16x32_bf16 v[106:109], v[86:89], v[180:183], v[106:109]
	v_mfma_f32_16x16x32_bf16 v[94:97], v[70:73], v[188:191], v[94:97]
	v_mfma_f32_16x16x32_bf16 v[90:93], v[86:89], v[188:191], v[90:93]
	s_setprio 0
	s_barrier
	s_add_i32 s28, 0, 0x1c000
	s_add_i32 s29, s66, s18
	v_add_u32_e32 v204, s28, v226
	v_lshl_add_u64 v[208:209], v[208:209], 0, s[86:87]
	s_mov_b32 m0, s29
	ds_read_b128 v[192:195], v204
	ds_read_b128 v[196:199], v204 offset:1024
	ds_read_b128 v[200:203], v204 offset:2048
	ds_read_b128 v[204:207], v204 offset:3072
	global_load_lds_dwordx4 v[208:209], off
	v_lshl_add_u64 v[208:209], v[228:229], 0, s[86:87]
	s_add_i32 m0, s29, 0x2000
	s_nop 0
	global_load_lds_dwordx4 v[208:209], off
	s_barrier
	s_waitcnt lgkmcnt(0)
	s_setprio 1
	v_mfma_f32_16x16x32_bf16 v[134:137], v[192:195], v[146:149], v[134:137]
	v_mfma_f32_16x16x32_bf16 v[130:133], v[200:203], v[146:149], v[130:133]
	v_mfma_f32_16x16x32_bf16 v[118:121], v[192:195], v[154:157], v[118:121]
	v_mfma_f32_16x16x32_bf16 v[114:117], v[200:203], v[154:157], v[114:117]
	v_mfma_f32_16x16x32_bf16 v[102:105], v[192:195], v[162:165], v[102:105]
	v_mfma_f32_16x16x32_bf16 v[98:101], v[200:203], v[162:165], v[98:101]
	v_mfma_f32_16x16x32_bf16 v[78:81], v[192:195], v[184:187], v[78:81]
	v_mfma_f32_16x16x32_bf16 v[74:77], v[200:203], v[184:187], v[74:77]
	v_mfma_f32_16x16x32_bf16 v[134:137], v[196:199], v[150:153], v[134:137]
	v_mfma_f32_16x16x32_bf16 v[130:133], v[204:207], v[150:153], v[130:133]
	v_mfma_f32_16x16x32_bf16 v[118:121], v[196:199], v[158:161], v[118:121]
	v_mfma_f32_16x16x32_bf16 v[114:117], v[204:207], v[158:161], v[114:117]
	v_mfma_f32_16x16x32_bf16 v[102:105], v[196:199], v[180:183], v[102:105]
	v_mfma_f32_16x16x32_bf16 v[98:101], v[204:207], v[180:183], v[98:101]
	v_mfma_f32_16x16x32_bf16 v[78:81], v[196:199], v[188:191], v[78:81]
	v_mfma_f32_16x16x32_bf16 v[74:77], v[204:207], v[188:191], v[74:77]
	s_setprio 0
	s_mov_b32 m0, s59
	v_lshl_add_u64 v[208:209], v[230:231], 0, s[86:87]
	s_barrier
	ds_read_b128 v[146:149], v227 offset:49152
	ds_read_b128 v[150:153], v227 offset:50176
	ds_read_b128 v[154:157], v227 offset:51200
	ds_read_b128 v[158:161], v227 offset:52224
	ds_read_b128 v[162:165], v227 offset:53248
	ds_read_b128 v[180:183], v227 offset:54272
	ds_read_b128 v[184:187], v227 offset:55296
	ds_read_b128 v[188:191], v227 offset:56320
	global_load_lds_dwordx4 v[208:209], off
	v_lshl_add_u64 v[208:209], v[232:233], 0, s[86:87]
	s_mov_b32 m0, s60
	s_nop 0
	global_load_lds_dwordx4 v[208:209], off
	s_barrier
; #define PG8_STAGE(bufoff, gbase, voff) do { _Pragma("unroll") for (int _i = 0; _i < 2; ++_i) \
;         __builtin_amdgcn_global_load_lds((const unsigned*)((const char*)(gbase) + (voff)[_i]), (LAS unsigned*)(lds + (bufoff) + ldsw + _i * 8192), 16, 0, 0); } while (0)
; #define PG8_LDA(dst, b, h) do { _Pragma("unroll") for (int m = 0; m < 4; ++m) _Pragma("unroll") for (int k = 0; k < 2; ++k) dst[m][k] = *(const LAS bf16x8*)(lds + PG8_SA(b, h) + aoff + m * 2048 + k * 1024); } while (0)
; #define PG8_MMA(ai, bj, At, Bt) do { __builtin_amdgcn_s_setprio(1); _Pragma("unroll") for (int m = 0; m < 4; ++m) _Pragma("unroll") for (int n = 0; n < 2; ++n) _Pragma("unroll") for (int k = 0; k < 2; ++k) \
;         acc[ai][bj][m][n] = __builtin_amdgcn_mfma_f32_16x16x32_bf16(Bt[n][k], At[m][k], acc[ai][bj][m][n], 0, 0, 0); __builtin_amdgcn_s_setprio(0); } while (0)
; #define PG8_WAIT_V(n) asm volatile("s_waitcnt vmcnt(" #n ")" ::: "memory")
; #define PG8_WAIT_L(n) asm volatile("s_waitcnt lgkmcnt(" #n ")" ::: "memory")
; template <class Epi>
; __device__ __forceinline__ void gemm_phase(LAS unsigned char* lds, const Gemm g, const Epi& E) {
;     ...
;             PG8_LDA(At, 1, 1); PG8_STAGE(PG8_SA(1, 0), a3, voffA);
;             PG8_BAR; PG8_WAIT_L(0); PG8_MMA(1, 0, At, B0); PG8_BAR; PG8_SCHED;
;             PG8_STAGE(PG8_SB(1, 1), b3 + hstepB, voffB);
;             PG8_WAIT_V(6); PG8_BAR; PG8_MMA(1, 1, At, B1); PG8_BAR;
;     __device__ __forceinline__ void operator()(const AccT& acc, const Unit& u, int wr, int wc, int fr, int fq) const {
;     ...
;         const int row0 = mapA.src(u.pm) * 256 + wr * 64 + fr, col0 = u.pn * 256 + wc * 32 + 8 * fq;
;         const int hd = u.pn >> 1;
;         f32x4 gw[2][2]; f32x2 st[2][4];
; #pragma unroll
;         for (int bj = 0; bj < 2; ++bj) { gw[bj][0] = *(const f32x4*)(gnw + col0 + bj * 128); gw[bj][1] = *(const f32x4*)(gnw + col0 + bj * 128 + 4); }
; #pragma unroll
;         for (int ai = 0; ai < 2; ++ai)
; #pragma unroll
;             for (int m = 0; m < 4; ++m) st[ai][m] = ST[(size_t)(row0 + ai * 128 + m * 16) * 4 + hd];
; #pragma unroll
;         for (int ai = 0; ai < 2; ++ai) {
;             u32x4 yv[4][2];
; #pragma unroll
;             for (int m = 0; m < 4; ++m)
; #pragma unroll
;                 for (int bj = 0; bj < 2; ++bj) yv[m][bj] = *(const u32x4*)(Y + (size_t)(row0 + ai * 128 + m * 16) * 2048 + col0 + bj * 128);
	s_waitcnt lgkmcnt(0)
	s_setprio 1
	v_mfma_f32_16x16x32_bf16 v[62:65], v[66:69], v[146:149], v[62:65]
	v_mfma_f32_16x16x32_bf16 v[58:61], v[82:85], v[146:149], v[58:61]
	v_mfma_f32_16x16x32_bf16 v[46:49], v[66:69], v[154:157], v[46:49]
	v_mfma_f32_16x16x32_bf16 v[42:45], v[82:85], v[154:157], v[42:45]
	v_mfma_f32_16x16x32_bf16 v[30:33], v[66:69], v[162:165], v[30:33]
	v_mfma_f32_16x16x32_bf16 v[26:29], v[82:85], v[162:165], v[26:29]
	v_mfma_f32_16x16x32_bf16 v[14:17], v[66:69], v[184:187], v[14:17]
	v_mfma_f32_16x16x32_bf16 v[10:13], v[82:85], v[184:187], v[10:13]
	v_mfma_f32_16x16x32_bf16 v[62:65], v[70:73], v[150:153], v[62:65]
	v_mfma_f32_16x16x32_bf16 v[58:61], v[86:89], v[150:153], v[58:61]
	v_mfma_f32_16x16x32_bf16 v[46:49], v[70:73], v[158:161], v[46:49]
	v_mfma_f32_16x16x32_bf16 v[42:45], v[86:89], v[158:161], v[42:45]
	v_mfma_f32_16x16x32_bf16 v[30:33], v[70:73], v[180:183], v[30:33]
	v_mfma_f32_16x16x32_bf16 v[26:29], v[86:89], v[180:183], v[26:29]
	v_mfma_f32_16x16x32_bf16 v[14:17], v[70:73], v[188:191], v[14:17]
	v_mfma_f32_16x16x32_bf16 v[10:13], v[86:89], v[188:191], v[10:13]
	s_setprio 0
	s_barrier
	s_add_u32 s16, s16, 0x40080
	s_addc_u32 s17, s17, 0
	s_add_i32 s28, s28, s18
	v_lshl_add_u64 v[66:67], s[16:17], 0, v[170:171]
	s_mov_b32 m0, s28
	s_nop 0
	global_load_lds_dwordx4 v[66:67], off
	v_lshl_add_u64 v[66:67], s[16:17], 0, v[166:167]
	s_add_i32 m0, s28, 0x2000
	s_nop 0
	global_load_lds_dwordx4 v[66:67], off
	s_waitcnt vmcnt(6)
	s_barrier
	s_setprio 1
	v_mfma_f32_16x16x32_bf16 v[54:57], v[192:195], v[146:149], v[54:57]
	v_mfma_f32_16x16x32_bf16 v[50:53], v[200:203], v[146:149], v[50:53]
	v_mfma_f32_16x16x32_bf16 v[38:41], v[192:195], v[154:157], v[38:41]
	v_mfma_f32_16x16x32_bf16 v[34:37], v[200:203], v[154:157], v[34:37]
	v_mfma_f32_16x16x32_bf16 v[22:25], v[192:195], v[162:165], v[22:25]
	v_mfma_f32_16x16x32_bf16 v[18:21], v[200:203], v[162:165], v[18:21]
	v_mfma_f32_16x16x32_bf16 v[6:9], v[192:195], v[184:187], v[6:9]
	v_mfma_f32_16x16x32_bf16 v[2:5], v[200:203], v[184:187], v[2:5]
	v_mfma_f32_16x16x32_bf16 v[54:57], v[196:199], v[150:153], v[54:57]
	v_mfma_f32_16x16x32_bf16 v[50:53], v[204:207], v[150:153], v[50:53]
	v_mfma_f32_16x16x32_bf16 v[38:41], v[196:199], v[158:161], v[38:41]
	v_mfma_f32_16x16x32_bf16 v[34:37], v[204:207], v[158:161], v[34:37]
	v_mfma_f32_16x16x32_bf16 v[22:25], v[196:199], v[180:183], v[22:25]
	v_mfma_f32_16x16x32_bf16 v[18:21], v[204:207], v[180:183], v[18:21]
	v_mfma_f32_16x16x32_bf16 v[6:9], v[196:199], v[188:191], v[6:9]
	v_mfma_f32_16x16x32_bf16 v[2:5], v[204:207], v[188:191], v[2:5]
	s_setprio 0
	s_add_i32 s65, s65, 2
	s_add_u32 s14, s14, 0x100
	s_addc_u32 s15, s15, 0
	s_add_u32 s9, s9, 0x100
	s_addc_u32 s53, s53, 0
	s_cmp_gt_u32 s65, 13
	s_barrier
	s_cbranch_scc0 .LBB0_475
	v_readlane_b32 s9, v255, 27
	s_cmp_ge_i32 s52, s9
	s_cselect_b32 s9, s25, 0
	s_lshl_b32 s14, s12, 8
	v_mov_b32_e32 v148, v225
	v_mov_b32_e32 v66, v1
	s_add_i32 s9, s52, s9
	s_or_b32 s14, s14, s58
	s_lshl_b32 s9, s9, 8
	v_lshl_add_u32 v146, v66, 3, s14
	s_ashr_i32 s14, s12, 1
	s_add_i32 s9, s9, s50
	s_ashr_i32 s15, s14, 31
	v_add_u32_e32 v148, s9, v148
	s_lshl_b64 s[14:15], s[14:15], 3
	s_add_u32 s14, s26, s14
	v_ashrrev_i32_e32 v149, 31, v148
	v_add_u32_e32 v152, 16, v148
	v_add_u32_e32 v156, 32, v148
	v_add_u32_e32 v202, 48, v148
	v_ashrrev_i32_e32 v147, 31, v146
	s_addc_u32 s15, s27, s15
	v_lshlrev_b64 v[150:151], 5, v[148:149]
	v_ashrrev_i32_e32 v153, 31, v152
	v_ashrrev_i32_e32 v157, 31, v156
	v_ashrrev_i32_e32 v203, 31, v202
	v_add_u32_e32 v190, 0x80, v148
	v_lshl_add_u64 v[70:71], v[146:147], 2, s[6:7]
	v_lshl_add_u64 v[150:151], s[14:15], 0, v[150:151]
	v_lshlrev_b64 v[154:155], 5, v[152:153]
	v_lshlrev_b64 v[158:159], 5, v[156:157]
	v_lshlrev_b64 v[160:161], 5, v[202:203]
	v_ashrrev_i32_e32 v191, 31, v190
	v_add_u32_e32 v192, 0x90, v148
	v_add_u32_e32 v194, 0xa0, v148
	v_add_u32_e32 v196, 0xb0, v148
	v_lshlrev_b64 v[182:183], 1, v[146:147]
	global_load_dwordx4 v[82:85], v[70:71], off offset:16
	global_load_dwordx4 v[86:89], v[70:71], off
	global_load_dwordx4 v[66:69], v[70:71], off offset:528
	s_nop 0
	global_load_dwordx4 v[70:73], v[70:71], off offset:512
	v_lshl_add_u64 v[154:155], s[14:15], 0, v[154:155]
	v_lshl_add_u64 v[158:159], s[14:15], 0, v[158:159]
	v_lshl_add_u64 v[160:161], s[14:15], 0, v[160:161]
	global_load_dwordx2 v[240:241], v[150:151], off
	global_load_dwordx2 v[208:209], v[154:155], off
	global_load_dwordx2 v[204:205], v[158:159], off
	global_load_dwordx2 v[200:201], v[160:161], off
	v_lshlrev_b64 v[150:151], 5, v[190:191]
	v_ashrrev_i32_e32 v193, 31, v192
	v_ashrrev_i32_e32 v195, 31, v194
	v_ashrrev_i32_e32 v197, 31, v196
	v_lshl_add_u64 v[198:199], s[38:39], 0, v[182:183]
	v_lshlrev_b64 v[242:243], 12, v[148:149]
	v_lshl_add_u64 v[150:151], s[14:15], 0, v[150:151]
	v_lshlrev_b64 v[154:155], 5, v[192:193]
	v_lshlrev_b64 v[158:159], 5, v[194:195]
	v_lshlrev_b64 v[160:161], 5, v[196:197]
	v_lshl_add_u64 v[146:147], v[198:199], 0, v[242:243]
	v_lshlrev_b64 v[244:245], 12, v[152:153]
	v_lshl_add_u64 v[154:155], s[14:15], 0, v[154:155]
	v_lshl_add_u64 v[158:159], s[14:15], 0, v[158:159]
	v_lshl_add_u64 v[160:161], s[14:15], 0, v[160:161]
	global_load_dwordx2 v[188:189], v[150:151], off
	global_load_dwordx2 v[186:187], v[154:155], off
	global_load_dwordx2 v[184:185], v[158:159], off
	global_load_dwordx2 v[180:181], v[160:161], off
	global_load_dwordx4 v[228:231], v[146:147], off
	global_load_dwordx4 v[232:235], v[146:147], off offset:256
	v_lshl_add_u64 v[146:147], v[198:199], 0, v[244:245]
	v_lshlrev_b64 v[206:207], 12, v[156:157]
	global_load_dwordx4 v[236:239], v[146:147], off
	global_load_dwordx4 v[162:165], v[146:147], off offset:256
	v_lshl_add_u64 v[146:147], v[198:199], 0, v[206:207]
	v_lshlrev_b64 v[202:203], 12, v[202:203]
	global_load_dwordx4 v[158:161], v[146:147], off
	global_load_dwordx4 v[154:157], v[146:147], off offset:256
	v_lshl_add_u64 v[146:147], v[198:199], 0, v[202:203]
	global_load_dwordx4 v[150:153], v[146:147], off
	s_nop 0
	global_load_dwordx4 v[146:149], v[146:147], off offset:256
	s_waitcnt vmcnt(0)
; __device__ __forceinline__ unsigned cvt_pk_bf16(float lo, float hi) { unsigned r; asm("v_cvt_pk_bf16_f32 %0, %1, %2" : "=v"(r) : "v"(lo), "v"(hi)); return r; }
; __device__ __forceinline__ float bf_lo(unsigned u) { return __uint_as_float(u << 16); }
; __device__ __forceinline__ float bf_hi(unsigned u) { return __uint_as_float(u & 0xffff0000u); }
;     __device__ __forceinline__ void operator()(const AccT& acc, const Unit& u, int wr, int wc, int fr, int fq) const {
;     ...
; #pragma unroll
;             for (int m = 0; m < 4; ++m) { bf16_t* rowp = A2 + (size_t)(row0 + ai * 128 + m * 16) * 2048 + col0;
;                 const float mu = st[ai][m][0], rs = st[ai][m][1];
; #pragma unroll
;                 for (int bj = 0; bj < 2; ++bj) { const f32x4 v0 = acc[ai][bj][m][0], v1 = acc[ai][bj][m][1]; const u32x4 yw = yv[m][bj];
;                     const f32x4 y0 = (f32x4){bf_lo(yw.x), bf_hi(yw.x), bf_lo(yw.y), bf_hi(yw.y)}, y1 = (f32x4){bf_lo(yw.z), bf_hi(yw.z), bf_lo(yw.w), bf_hi(yw.w)};
;                     const f32x4 n0 = (y0 - mu) * rs * gw[bj][0], n1 = (y1 - mu) * rs * gw[bj][1];
;                     const f32x4 s0 = silu4(v0) * n0, s1 = silu4(v1) * n1;
;                     u32x4 w; w.x = cvt_pk_bf16(s0[0], s0[1]); w.y = cvt_pk_bf16(s0[2], s0[3]); w.z = cvt_pk_bf16(s1[0], s1[1]); w.w = cvt_pk_bf16(s1[2], s1[3]);
;                     *(u32x4*)(rowp + bj * 128) = w; } }
	v_lshlrev_b32_e32 v246, 16, v228
	v_and_b32_e32 v228, 0xffff0000, v228
	v_lshlrev_b32_e32 v247, 16, v229
	v_and_b32_e32 v248, 0xffff0000, v229
	v_lshlrev_b32_e32 v249, 16, v230
	v_and_b32_e32 v250, 0xffff0000, v230
	v_lshlrev_b32_e32 v251, 16, v231
	v_and_b32_e32 v252, 0xffff0000, v231
	v_sub_f32_e32 v229, v228, v240
	v_sub_f32_e32 v228, v246, v240
	v_sub_f32_e32 v231, v248, v240
	v_sub_f32_e32 v230, v247, v240
	v_sub_f32_e32 v247, v250, v240
	v_sub_f32_e32 v246, v249, v240
	v_sub_f32_e32 v249, v252, v240
	v_sub_f32_e32 v248, v251, v240
	v_mul_f32_e32 v250, 0xbfb8aa3b, v142
	v_mul_f32_e32 v251, 0xbfb8aa3b, v143
	v_mul_f32_e32 v252, 0xbfb8aa3b, v144
	v_mul_f32_e32 v253, 0xbfb8aa3b, v145
	v_exp_f32_e32 v250, v250
	v_exp_f32_e32 v251, v251
	v_exp_f32_e32 v252, v252
	v_exp_f32_e32 v253, v253
	v_add_f32_e32 v250, 1.0, v250
	v_add_f32_e32 v251, 1.0, v251
	v_add_f32_e32 v252, 1.0, v252
	v_add_f32_e32 v253, 1.0, v253
	v_rcp_f32_e32 v250, v250
	v_rcp_f32_e32 v251, v251
	v_rcp_f32_e32 v252, v252
	v_rcp_f32_e32 v253, v253
	v_pk_mul_f32 v[228:229], v[240:241], v[228:229] op_sel:[1,0]
	v_pk_mul_f32 v[142:143], v[142:143], v[250:251]
	v_mul_f32_e32 v250, 0xbfb8aa3b, v138
	v_pk_mul_f32 v[144:145], v[144:145], v[252:253]
	v_mul_f32_e32 v251, 0xbfb8aa3b, v139
	v_mul_f32_e32 v252, 0xbfb8aa3b, v140
	v_mul_f32_e32 v253, 0xbfb8aa3b, v141
	v_exp_f32_e32 v250, v250
	v_exp_f32_e32 v251, v251
	v_exp_f32_e32 v252, v252
	v_exp_f32_e32 v253, v253
	v_add_f32_e32 v250, 1.0, v250
	v_add_f32_e32 v251, 1.0, v251
	v_add_f32_e32 v252, 1.0, v252
	v_add_f32_e32 v253, 1.0, v253
	v_rcp_f32_e32 v250, v250
	v_rcp_f32_e32 v251, v251
	v_rcp_f32_e32 v252, v252
	v_rcp_f32_e32 v253, v253
	v_pk_mul_f32 v[248:249], v[240:241], v[248:249] op_sel:[1,0]
	v_pk_mul_f32 v[246:247], v[240:241], v[246:247] op_sel:[1,0]
	v_pk_mul_f32 v[230:231], v[240:241], v[230:231] op_sel:[1,0]
	v_pk_mul_f32 v[228:229], v[86:87], v[228:229]
	v_pk_mul_f32 v[246:247], v[82:83], v[246:247]
	v_pk_mul_f32 v[248:249], v[84:85], v[248:249]
	v_pk_mul_f32 v[138:139], v[138:139], v[250:251]
	v_pk_mul_f32 v[140:141], v[140:141], v[252:253]
	v_pk_mul_f32 v[230:231], v[88:89], v[230:231]
	v_pk_mul_f32 v[142:143], v[142:143], v[228:229]
	v_pk_mul_f32 v[228:229], v[140:141], v[248:249]
	v_pk_mul_f32 v[140:141], v[138:139], v[246:247]
	v_pk_mul_f32 v[144:145], v[144:145], v[230:231]
	v_cvt_pk_bf16_f32 v140, v140, v141
	v_cvt_pk_bf16_f32 v141, v228, v229
	v_mul_f32_e32 v228, 0xbfb8aa3b, v134
	v_mul_f32_e32 v229, 0xbfb8aa3b, v135
	v_mul_f32_e32 v230, 0xbfb8aa3b, v136
	v_mul_f32_e32 v231, 0xbfb8aa3b, v137
	v_exp_f32_e32 v228, v228
	v_exp_f32_e32 v229, v229
	v_exp_f32_e32 v230, v230
	v_exp_f32_e32 v231, v231
	v_add_f32_e32 v228, 1.0, v228
	v_add_f32_e32 v229, 1.0, v229
	v_add_f32_e32 v230, 1.0, v230
	v_add_f32_e32 v231, 1.0, v231
	v_rcp_f32_e32 v228, v228
	v_rcp_f32_e32 v229, v229
	v_rcp_f32_e32 v230, v230
	v_rcp_f32_e32 v231, v231
	v_lshl_add_u64 v[242:243], s[34:35], 0, v[242:243]
	v_pk_mul_f32 v[134:135], v[134:135], v[228:229]
	v_mul_f32_e32 v228, 0xbfb8aa3b, v130
	v_pk_mul_f32 v[136:137], v[136:137], v[230:231]
	v_mul_f32_e32 v229, 0xbfb8aa3b, v131
	v_mul_f32_e32 v230, 0xbfb8aa3b, v132
	v_mul_f32_e32 v231, 0xbfb8aa3b, v133
	v_exp_f32_e32 v228, v228
	v_exp_f32_e32 v229, v229
	v_exp_f32_e32 v230, v230
	v_exp_f32_e32 v231, v231
	v_add_f32_e32 v228, 1.0, v228
	v_add_f32_e32 v229, 1.0, v229
	v_add_f32_e32 v230, 1.0, v230
	v_add_f32_e32 v231, 1.0, v231
	v_lshl_add_u64 v[242:243], v[242:243], 0, v[182:183]
	v_cvt_pk_bf16_f32 v138, v142, v143
	v_cvt_pk_bf16_f32 v139, v144, v145
	v_rcp_f32_e32 v228, v228
	v_rcp_f32_e32 v229, v229
	v_rcp_f32_e32 v230, v230
	v_rcp_f32_e32 v231, v231
	global_store_dwordx4 v[242:243], v[138:141], off
	v_lshlrev_b32_e32 v142, 16, v234
	v_and_b32_e32 v143, 0xffff0000, v234
	v_lshlrev_b32_e32 v138, 16, v232
	v_and_b32_e32 v139, 0xffff0000, v232
	v_lshlrev_b32_e32 v140, 16, v233
	v_and_b32_e32 v141, 0xffff0000, v233
	v_lshlrev_b32_e32 v144, 16, v235
	v_and_b32_e32 v145, 0xffff0000, v235
	v_sub_f32_e32 v139, v139, v240
	v_sub_f32_e32 v138, v138, v240
	v_sub_f32_e32 v141, v141, v240
	v_sub_f32_e32 v140, v140, v240
	v_sub_f32_e32 v143, v143, v240
	v_sub_f32_e32 v142, v142, v240
	v_sub_f32_e32 v145, v145, v240
	v_sub_f32_e32 v144, v144, v240
	v_pk_mul_f32 v[140:141], v[240:241], v[140:141] op_sel:[1,0]
	v_pk_mul_f32 v[138:139], v[240:241], v[138:139] op_sel:[1,0]
	v_pk_mul_f32 v[144:145], v[240:241], v[144:145] op_sel:[1,0]
	v_pk_mul_f32 v[142:143], v[240:241], v[142:143] op_sel:[1,0]
	v_pk_mul_f32 v[138:139], v[70:71], v[138:139]
	v_pk_mul_f32 v[140:141], v[72:73], v[140:141]
	v_pk_mul_f32 v[142:143], v[66:67], v[142:143]
	v_pk_mul_f32 v[144:145], v[68:69], v[144:145]
	v_pk_mul_f32 v[130:131], v[130:131], v[228:229]
	v_pk_mul_f32 v[132:133], v[132:133], v[230:231]
	v_pk_mul_f32 v[136:137], v[136:137], v[140:141]
	v_pk_mul_f32 v[134:135], v[134:135], v[138:139]
	v_pk_mul_f32 v[138:139], v[132:133], v[144:145]
	v_pk_mul_f32 v[132:133], v[130:131], v[142:143]
	v_mul_f32_e32 v140, 0xbfb8aa3b, v126
	v_mul_f32_e32 v141, 0xbfb8aa3b, v127
	v_mul_f32_e32 v142, 0xbfb8aa3b, v128
	v_mul_f32_e32 v143, 0xbfb8aa3b, v129
	v_exp_f32_e32 v140, v140
	v_exp_f32_e32 v141, v141
	v_exp_f32_e32 v142, v142
	v_exp_f32_e32 v143, v143
	v_add_f32_e32 v140, 1.0, v140
	v_add_f32_e32 v141, 1.0, v141
	v_add_f32_e32 v142, 1.0, v142
	v_add_f32_e32 v143, 1.0, v143
	v_rcp_f32_e32 v140, v140
	v_rcp_f32_e32 v141, v141
	v_rcp_f32_e32 v142, v142
	v_rcp_f32_e32 v143, v143
	v_cvt_pk_bf16_f32 v132, v132, v133
	v_pk_mul_f32 v[126:127], v[126:127], v[140:141]
	v_mul_f32_e32 v140, 0xbfb8aa3b, v122
	v_pk_mul_f32 v[128:129], v[128:129], v[142:143]
; __device__ __forceinline__ unsigned cvt_pk_bf16(float lo, float hi) { unsigned r; asm("v_cvt_pk_bf16_f32 %0, %1, %2" : "=v"(r) : "v"(lo), "v"(hi)); return r; }
; __device__ __forceinline__ float bf_lo(unsigned u) { return __uint_as_float(u << 16); }
; __device__ __forceinline__ float bf_hi(unsigned u) { return __uint_as_float(u & 0xffff0000u); }
;     __device__ __forceinline__ void operator()(const AccT& acc, const Unit& u, int wr, int wc, int fr, int fq) const {
;     ...
; #pragma unroll
;             for (int m = 0; m < 4; ++m) { bf16_t* rowp = A2 + (size_t)(row0 + ai * 128 + m * 16) * 2048 + col0;
;                 const float mu = st[ai][m][0], rs = st[ai][m][1];
; #pragma unroll
;                 for (int bj = 0; bj < 2; ++bj) { const f32x4 v0 = acc[ai][bj][m][0], v1 = acc[ai][bj][m][1]; const u32x4 yw = yv[m][bj];
;                     const f32x4 y0 = (f32x4){bf_lo(yw.x), bf_hi(yw.x), bf_lo(yw.y), bf_hi(yw.y)}, y1 = (f32x4){bf_lo(yw.z), bf_hi(yw.z), bf_lo(yw.w), bf_hi(yw.w)};
;                     const f32x4 n0 = (y0 - mu) * rs * gw[bj][0], n1 = (y1 - mu) * rs * gw[bj][1];
;                     const f32x4 s0 = silu4(v0) * n0, s1 = silu4(v1) * n1;
;                     u32x4 w; w.x = cvt_pk_bf16(s0[0], s0[1]); w.y = cvt_pk_bf16(s0[2], s0[3]); w.z = cvt_pk_bf16(s1[0], s1[1]); w.w = cvt_pk_bf16(s1[2], s1[3]);
;                     *(u32x4*)(rowp + bj * 128) = w; } }
	v_mul_f32_e32 v141, 0xbfb8aa3b, v123
	v_mul_f32_e32 v142, 0xbfb8aa3b, v124
	v_mul_f32_e32 v143, 0xbfb8aa3b, v125
	v_exp_f32_e32 v140, v140
	v_exp_f32_e32 v141, v141
	v_exp_f32_e32 v142, v142
	v_exp_f32_e32 v143, v143
	v_add_f32_e32 v140, 1.0, v140
	v_add_f32_e32 v141, 1.0, v141
	v_add_f32_e32 v142, 1.0, v142
	v_add_f32_e32 v143, 1.0, v143
	v_cvt_pk_bf16_f32 v133, v138, v139
	v_rcp_f32_e32 v140, v140
	v_rcp_f32_e32 v141, v141
	v_rcp_f32_e32 v142, v142
	v_rcp_f32_e32 v143, v143
	v_cvt_pk_bf16_f32 v130, v134, v135
	v_cvt_pk_bf16_f32 v131, v136, v137
	global_store_dwordx4 v[242:243], v[130:133], off offset:256
	v_lshlrev_b32_e32 v136, 16, v238
	v_and_b32_e32 v137, 0xffff0000, v238
	v_lshlrev_b32_e32 v132, 16, v236
	v_and_b32_e32 v133, 0xffff0000, v236
	v_lshlrev_b32_e32 v138, 16, v239
	v_and_b32_e32 v139, 0xffff0000, v239
	v_lshlrev_b32_e32 v134, 16, v237
	v_and_b32_e32 v135, 0xffff0000, v237
	v_sub_f32_e32 v133, v133, v208
	v_sub_f32_e32 v132, v132, v208
	v_sub_f32_e32 v137, v137, v208
	v_sub_f32_e32 v136, v136, v208
	v_sub_f32_e32 v139, v139, v208
	v_sub_f32_e32 v138, v138, v208
	v_sub_f32_e32 v135, v135, v208
	v_sub_f32_e32 v134, v134, v208
	v_pk_mul_f32 v[132:133], v[208:209], v[132:133] op_sel:[1,0]
	v_pk_mul_f32 v[138:139], v[208:209], v[138:139] op_sel:[1,0]
	v_pk_mul_f32 v[136:137], v[208:209], v[136:137] op_sel:[1,0]
	v_pk_mul_f32 v[134:135], v[208:209], v[134:135] op_sel:[1,0]
	v_pk_mul_f32 v[132:133], v[86:87], v[132:133]
	v_pk_mul_f32 v[136:137], v[82:83], v[136:137]
	v_pk_mul_f32 v[138:139], v[84:85], v[138:139]
	v_pk_mul_f32 v[122:123], v[122:123], v[140:141]
	v_pk_mul_f32 v[124:125], v[124:125], v[142:143]
	v_pk_mul_f32 v[134:135], v[88:89], v[134:135]
	v_pk_mul_f32 v[126:127], v[126:127], v[132:133]
	v_pk_mul_f32 v[132:133], v[124:125], v[138:139]
	v_pk_mul_f32 v[124:125], v[122:123], v[136:137]
	v_pk_mul_f32 v[128:129], v[128:129], v[134:135]
	v_cvt_pk_bf16_f32 v124, v124, v125
	v_cvt_pk_bf16_f32 v125, v132, v133
	v_mul_f32_e32 v132, 0xbfb8aa3b, v118
	v_mul_f32_e32 v133, 0xbfb8aa3b, v119
	v_mul_f32_e32 v134, 0xbfb8aa3b, v120
	v_mul_f32_e32 v135, 0xbfb8aa3b, v121
	v_exp_f32_e32 v132, v132
	v_exp_f32_e32 v133, v133
	v_exp_f32_e32 v134, v134
	v_exp_f32_e32 v135, v135
	v_add_f32_e32 v132, 1.0, v132
	v_add_f32_e32 v133, 1.0, v133
	v_add_f32_e32 v134, 1.0, v134
	v_add_f32_e32 v135, 1.0, v135
	v_rcp_f32_e32 v132, v132
	v_rcp_f32_e32 v133, v133
	v_rcp_f32_e32 v134, v134
	v_rcp_f32_e32 v135, v135
	v_lshl_add_u64 v[130:131], s[34:35], 0, v[244:245]
	v_pk_mul_f32 v[118:119], v[118:119], v[132:133]
	v_mul_f32_e32 v132, 0xbfb8aa3b, v114
	v_pk_mul_f32 v[120:121], v[120:121], v[134:135]
	v_mul_f32_e32 v133, 0xbfb8aa3b, v115
	v_mul_f32_e32 v134, 0xbfb8aa3b, v116
	v_mul_f32_e32 v135, 0xbfb8aa3b, v117
	v_exp_f32_e32 v132, v132
	v_exp_f32_e32 v133, v133
	v_exp_f32_e32 v134, v134
	v_exp_f32_e32 v135, v135
	v_add_f32_e32 v132, 1.0, v132
	v_add_f32_e32 v133, 1.0, v133
	v_add_f32_e32 v134, 1.0, v134
	v_add_f32_e32 v135, 1.0, v135
	v_lshl_add_u64 v[130:131], v[130:131], 0, v[182:183]
	v_cvt_pk_bf16_f32 v122, v126, v127
	v_cvt_pk_bf16_f32 v123, v128, v129
	v_rcp_f32_e32 v132, v132
	v_rcp_f32_e32 v133, v133
	v_rcp_f32_e32 v134, v134
	v_rcp_f32_e32 v135, v135
	global_store_dwordx4 v[130:131], v[122:125], off
	v_lshlrev_b32_e32 v126, 16, v164
	v_and_b32_e32 v127, 0xffff0000, v164
	v_lshlrev_b32_e32 v122, 16, v162
	v_and_b32_e32 v123, 0xffff0000, v162
	v_lshlrev_b32_e32 v124, 16, v163
	v_and_b32_e32 v125, 0xffff0000, v163
	v_lshlrev_b32_e32 v128, 16, v165
	v_and_b32_e32 v129, 0xffff0000, v165
	v_sub_f32_e32 v123, v123, v208
	v_sub_f32_e32 v122, v122, v208
	v_sub_f32_e32 v125, v125, v208
	v_sub_f32_e32 v124, v124, v208
	v_sub_f32_e32 v127, v127, v208
	v_sub_f32_e32 v126, v126, v208
	v_sub_f32_e32 v129, v129, v208
	v_sub_f32_e32 v128, v128, v208
	v_pk_mul_f32 v[124:125], v[208:209], v[124:125] op_sel:[1,0]
	v_pk_mul_f32 v[122:123], v[208:209], v[122:123] op_sel:[1,0]
	v_pk_mul_f32 v[128:129], v[208:209], v[128:129] op_sel:[1,0]
	v_pk_mul_f32 v[126:127], v[208:209], v[126:127] op_sel:[1,0]
	v_pk_mul_f32 v[122:123], v[70:71], v[122:123]
	v_pk_mul_f32 v[124:125], v[72:73], v[124:125]
	v_pk_mul_f32 v[126:127], v[66:67], v[126:127]
	v_pk_mul_f32 v[128:129], v[68:69], v[128:129]
	v_pk_mul_f32 v[114:115], v[114:115], v[132:133]
	v_pk_mul_f32 v[116:117], v[116:117], v[134:135]
	v_pk_mul_f32 v[120:121], v[120:121], v[124:125]
	v_pk_mul_f32 v[118:119], v[118:119], v[122:123]
	v_pk_mul_f32 v[122:123], v[116:117], v[128:129]
	v_pk_mul_f32 v[116:117], v[114:115], v[126:127]
	v_mul_f32_e32 v124, 0xbfb8aa3b, v110
	v_mul_f32_e32 v125, 0xbfb8aa3b, v111
	v_mul_f32_e32 v126, 0xbfb8aa3b, v112
	v_mul_f32_e32 v127, 0xbfb8aa3b, v113
	v_exp_f32_e32 v124, v124
	v_exp_f32_e32 v125, v125
	v_exp_f32_e32 v126, v126
	v_exp_f32_e32 v127, v127
	v_add_f32_e32 v124, 1.0, v124
	v_add_f32_e32 v125, 1.0, v125
	v_add_f32_e32 v126, 1.0, v126
	v_add_f32_e32 v127, 1.0, v127
	v_rcp_f32_e32 v124, v124
	v_rcp_f32_e32 v125, v125
	v_rcp_f32_e32 v126, v126
	v_rcp_f32_e32 v127, v127
	v_cvt_pk_bf16_f32 v116, v116, v117
	v_pk_mul_f32 v[110:111], v[110:111], v[124:125]
	v_mul_f32_e32 v124, 0xbfb8aa3b, v106
	v_pk_mul_f32 v[112:113], v[112:113], v[126:127]
	v_mul_f32_e32 v125, 0xbfb8aa3b, v107
	v_mul_f32_e32 v126, 0xbfb8aa3b, v108
	v_mul_f32_e32 v127, 0xbfb8aa3b, v109
	v_exp_f32_e32 v124, v124
	v_exp_f32_e32 v125, v125
	v_exp_f32_e32 v126, v126
	v_exp_f32_e32 v127, v127
	v_add_f32_e32 v124, 1.0, v124
	v_add_f32_e32 v125, 1.0, v125
	v_add_f32_e32 v126, 1.0, v126
	v_add_f32_e32 v127, 1.0, v127
	v_cvt_pk_bf16_f32 v117, v122, v123
	v_rcp_f32_e32 v124, v124
	v_rcp_f32_e32 v125, v125
	v_rcp_f32_e32 v126, v126
; __device__ __forceinline__ unsigned cvt_pk_bf16(float lo, float hi) { unsigned r; asm("v_cvt_pk_bf16_f32 %0, %1, %2" : "=v"(r) : "v"(lo), "v"(hi)); return r; }
; __device__ __forceinline__ float bf_lo(unsigned u) { return __uint_as_float(u << 16); }
; __device__ __forceinline__ float bf_hi(unsigned u) { return __uint_as_float(u & 0xffff0000u); }
;     __device__ __forceinline__ void operator()(const AccT& acc, const Unit& u, int wr, int wc, int fr, int fq) const {
;     ...
; #pragma unroll
;             for (int m = 0; m < 4; ++m) { bf16_t* rowp = A2 + (size_t)(row0 + ai * 128 + m * 16) * 2048 + col0;
;                 const float mu = st[ai][m][0], rs = st[ai][m][1];
; #pragma unroll
;                 for (int bj = 0; bj < 2; ++bj) { const f32x4 v0 = acc[ai][bj][m][0], v1 = acc[ai][bj][m][1]; const u32x4 yw = yv[m][bj];
;                     const f32x4 y0 = (f32x4){bf_lo(yw.x), bf_hi(yw.x), bf_lo(yw.y), bf_hi(yw.y)}, y1 = (f32x4){bf_lo(yw.z), bf_hi(yw.z), bf_lo(yw.w), bf_hi(yw.w)};
;                     const f32x4 n0 = (y0 - mu) * rs * gw[bj][0], n1 = (y1 - mu) * rs * gw[bj][1];
;                     const f32x4 s0 = silu4(v0) * n0, s1 = silu4(v1) * n1;
;                     u32x4 w; w.x = cvt_pk_bf16(s0[0], s0[1]); w.y = cvt_pk_bf16(s0[2], s0[3]); w.z = cvt_pk_bf16(s1[0], s1[1]); w.w = cvt_pk_bf16(s1[2], s1[3]);
;                     *(u32x4*)(rowp + bj * 128) = w; } }
	v_rcp_f32_e32 v127, v127
	v_cvt_pk_bf16_f32 v114, v118, v119
	v_cvt_pk_bf16_f32 v115, v120, v121
	global_store_dwordx4 v[130:131], v[114:117], off offset:256
	v_lshlrev_b32_e32 v120, 16, v160
	v_and_b32_e32 v121, 0xffff0000, v160
	v_lshlrev_b32_e32 v116, 16, v158
	v_and_b32_e32 v117, 0xffff0000, v158
	v_lshlrev_b32_e32 v122, 16, v161
	v_and_b32_e32 v123, 0xffff0000, v161
	v_lshlrev_b32_e32 v118, 16, v159
	v_and_b32_e32 v119, 0xffff0000, v159
	v_sub_f32_e32 v117, v117, v204
	v_sub_f32_e32 v116, v116, v204
	v_sub_f32_e32 v121, v121, v204
	v_sub_f32_e32 v120, v120, v204
	v_sub_f32_e32 v123, v123, v204
	v_sub_f32_e32 v122, v122, v204
	v_sub_f32_e32 v119, v119, v204
	v_sub_f32_e32 v118, v118, v204
	v_pk_mul_f32 v[116:117], v[204:205], v[116:117] op_sel:[1,0]
	v_pk_mul_f32 v[122:123], v[204:205], v[122:123] op_sel:[1,0]
	v_pk_mul_f32 v[120:121], v[204:205], v[120:121] op_sel:[1,0]
	v_pk_mul_f32 v[118:119], v[204:205], v[118:119] op_sel:[1,0]
	v_pk_mul_f32 v[116:117], v[86:87], v[116:117]
	v_pk_mul_f32 v[120:121], v[82:83], v[120:121]
	v_pk_mul_f32 v[122:123], v[84:85], v[122:123]
	v_pk_mul_f32 v[106:107], v[106:107], v[124:125]
	v_pk_mul_f32 v[108:109], v[108:109], v[126:127]
	v_pk_mul_f32 v[118:119], v[88:89], v[118:119]
	v_pk_mul_f32 v[110:111], v[110:111], v[116:117]
	v_pk_mul_f32 v[116:117], v[108:109], v[122:123]
	v_pk_mul_f32 v[108:109], v[106:107], v[120:121]
	v_pk_mul_f32 v[112:113], v[112:113], v[118:119]
	v_cvt_pk_bf16_f32 v108, v108, v109
	v_cvt_pk_bf16_f32 v109, v116, v117
	v_mul_f32_e32 v116, 0xbfb8aa3b, v102
	v_mul_f32_e32 v117, 0xbfb8aa3b, v103
	v_mul_f32_e32 v118, 0xbfb8aa3b, v104
	v_mul_f32_e32 v119, 0xbfb8aa3b, v105
	v_exp_f32_e32 v116, v116
	v_exp_f32_e32 v117, v117
	v_exp_f32_e32 v118, v118
	v_exp_f32_e32 v119, v119
	v_add_f32_e32 v116, 1.0, v116
	v_add_f32_e32 v117, 1.0, v117
	v_add_f32_e32 v118, 1.0, v118
	v_add_f32_e32 v119, 1.0, v119
	v_rcp_f32_e32 v116, v116
	v_rcp_f32_e32 v117, v117
	v_rcp_f32_e32 v118, v118
	v_rcp_f32_e32 v119, v119
	v_lshl_add_u64 v[114:115], s[34:35], 0, v[206:207]
	v_pk_mul_f32 v[102:103], v[102:103], v[116:117]
	v_mul_f32_e32 v116, 0xbfb8aa3b, v98
	v_pk_mul_f32 v[104:105], v[104:105], v[118:119]
	v_mul_f32_e32 v117, 0xbfb8aa3b, v99
	v_mul_f32_e32 v118, 0xbfb8aa3b, v100
	v_mul_f32_e32 v119, 0xbfb8aa3b, v101
	v_exp_f32_e32 v116, v116
	v_exp_f32_e32 v117, v117
	v_exp_f32_e32 v118, v118
	v_exp_f32_e32 v119, v119
	v_add_f32_e32 v116, 1.0, v116
	v_add_f32_e32 v117, 1.0, v117
	v_add_f32_e32 v118, 1.0, v118
	v_add_f32_e32 v119, 1.0, v119
	v_lshl_add_u64 v[114:115], v[114:115], 0, v[182:183]
	v_cvt_pk_bf16_f32 v106, v110, v111
	v_cvt_pk_bf16_f32 v107, v112, v113
	v_rcp_f32_e32 v116, v116
	v_rcp_f32_e32 v117, v117
	v_rcp_f32_e32 v118, v118
	v_rcp_f32_e32 v119, v119
	global_store_dwordx4 v[114:115], v[106:109], off
	v_lshlrev_b32_e32 v110, 16, v156
	v_and_b32_e32 v111, 0xffff0000, v156
	v_lshlrev_b32_e32 v106, 16, v154
	v_and_b32_e32 v107, 0xffff0000, v154
	v_lshlrev_b32_e32 v108, 16, v155
	v_and_b32_e32 v109, 0xffff0000, v155
	v_lshlrev_b32_e32 v112, 16, v157
	v_and_b32_e32 v113, 0xffff0000, v157
	v_sub_f32_e32 v107, v107, v204
	v_sub_f32_e32 v106, v106, v204
	v_sub_f32_e32 v109, v109, v204
	v_sub_f32_e32 v108, v108, v204
	v_sub_f32_e32 v111, v111, v204
	v_sub_f32_e32 v110, v110, v204
	v_sub_f32_e32 v113, v113, v204
	v_sub_f32_e32 v112, v112, v204
	v_pk_mul_f32 v[108:109], v[204:205], v[108:109] op_sel:[1,0]
	v_pk_mul_f32 v[106:107], v[204:205], v[106:107] op_sel:[1,0]
	v_pk_mul_f32 v[112:113], v[204:205], v[112:113] op_sel:[1,0]
	v_pk_mul_f32 v[110:111], v[204:205], v[110:111] op_sel:[1,0]
	v_pk_mul_f32 v[106:107], v[70:71], v[106:107]
	v_pk_mul_f32 v[108:109], v[72:73], v[108:109]
	v_pk_mul_f32 v[110:111], v[66:67], v[110:111]
	v_pk_mul_f32 v[112:113], v[68:69], v[112:113]
	v_pk_mul_f32 v[98:99], v[98:99], v[116:117]
	v_pk_mul_f32 v[100:101], v[100:101], v[118:119]
	v_pk_mul_f32 v[104:105], v[104:105], v[108:109]
	v_pk_mul_f32 v[102:103], v[102:103], v[106:107]
	v_pk_mul_f32 v[106:107], v[100:101], v[112:113]
	v_pk_mul_f32 v[100:101], v[98:99], v[110:111]
	v_mul_f32_e32 v108, 0xbfb8aa3b, v94
	v_mul_f32_e32 v109, 0xbfb8aa3b, v95
	v_mul_f32_e32 v110, 0xbfb8aa3b, v96
	v_mul_f32_e32 v111, 0xbfb8aa3b, v97
	v_exp_f32_e32 v108, v108
	v_exp_f32_e32 v109, v109
	v_exp_f32_e32 v110, v110
	v_exp_f32_e32 v111, v111
	v_add_f32_e32 v108, 1.0, v108
	v_add_f32_e32 v109, 1.0, v109
	v_add_f32_e32 v110, 1.0, v110
	v_add_f32_e32 v111, 1.0, v111
	v_rcp_f32_e32 v108, v108
	v_rcp_f32_e32 v109, v109
	v_rcp_f32_e32 v110, v110
	v_rcp_f32_e32 v111, v111
	v_cvt_pk_bf16_f32 v100, v100, v101
	v_pk_mul_f32 v[94:95], v[94:95], v[108:109]
	v_mul_f32_e32 v108, 0xbfb8aa3b, v90
	v_pk_mul_f32 v[96:97], v[96:97], v[110:111]
	v_mul_f32_e32 v109, 0xbfb8aa3b, v91
	v_mul_f32_e32 v110, 0xbfb8aa3b, v92
	v_mul_f32_e32 v111, 0xbfb8aa3b, v93
	v_exp_f32_e32 v108, v108
	v_exp_f32_e32 v109, v109
	v_exp_f32_e32 v110, v110
	v_exp_f32_e32 v111, v111
	v_add_f32_e32 v108, 1.0, v108
	v_add_f32_e32 v109, 1.0, v109
	v_add_f32_e32 v110, 1.0, v110
	v_add_f32_e32 v111, 1.0, v111
	v_cvt_pk_bf16_f32 v101, v106, v107
	v_rcp_f32_e32 v108, v108
	v_rcp_f32_e32 v109, v109
	v_rcp_f32_e32 v110, v110
	v_rcp_f32_e32 v111, v111
	v_cvt_pk_bf16_f32 v98, v102, v103
	v_cvt_pk_bf16_f32 v99, v104, v105
	global_store_dwordx4 v[114:115], v[98:101], off offset:256
	v_lshlrev_b32_e32 v104, 16, v152
	v_and_b32_e32 v105, 0xffff0000, v152
	v_lshlrev_b32_e32 v100, 16, v150
	v_and_b32_e32 v101, 0xffff0000, v150
	v_lshlrev_b32_e32 v106, 16, v153
	v_and_b32_e32 v107, 0xffff0000, v153
	v_lshlrev_b32_e32 v102, 16, v151
	v_and_b32_e32 v103, 0xffff0000, v151
	v_sub_f32_e32 v101, v101, v200
; __device__ __forceinline__ unsigned cvt_pk_bf16(float lo, float hi) { unsigned r; asm("v_cvt_pk_bf16_f32 %0, %1, %2" : "=v"(r) : "v"(lo), "v"(hi)); return r; }
; __device__ __forceinline__ float bf_lo(unsigned u) { return __uint_as_float(u << 16); }
; __device__ __forceinline__ float bf_hi(unsigned u) { return __uint_as_float(u & 0xffff0000u); }
;     __device__ __forceinline__ void operator()(const AccT& acc, const Unit& u, int wr, int wc, int fr, int fq) const {
;     ...
;         for (int ai = 0; ai < 2; ++ai) {
;             u32x4 yv[4][2];
; #pragma unroll
;             for (int m = 0; m < 4; ++m)
; #pragma unroll
;                 for (int bj = 0; bj < 2; ++bj) yv[m][bj] = *(const u32x4*)(Y + (size_t)(row0 + ai * 128 + m * 16) * 2048 + col0 + bj * 128);
;             __builtin_amdgcn_sched_barrier(0);
; #pragma unroll
;             for (int m = 0; m < 4; ++m) { bf16_t* rowp = A2 + (size_t)(row0 + ai * 128 + m * 16) * 2048 + col0;
;                 const float mu = st[ai][m][0], rs = st[ai][m][1];
; #pragma unroll
;                 for (int bj = 0; bj < 2; ++bj) { const f32x4 v0 = acc[ai][bj][m][0], v1 = acc[ai][bj][m][1]; const u32x4 yw = yv[m][bj];
;                     const f32x4 y0 = (f32x4){bf_lo(yw.x), bf_hi(yw.x), bf_lo(yw.y), bf_hi(yw.y)}, y1 = (f32x4){bf_lo(yw.z), bf_hi(yw.z), bf_lo(yw.w), bf_hi(yw.w)};
;                     const f32x4 n0 = (y0 - mu) * rs * gw[bj][0], n1 = (y1 - mu) * rs * gw[bj][1];
;                     const f32x4 s0 = silu4(v0) * n0, s1 = silu4(v1) * n1;
;                     u32x4 w; w.x = cvt_pk_bf16(s0[0], s0[1]); w.y = cvt_pk_bf16(s0[2], s0[3]); w.z = cvt_pk_bf16(s1[0], s1[1]); w.w = cvt_pk_bf16(s1[2], s1[3]);
;                     *(u32x4*)(rowp + bj * 128) = w; } }
	v_sub_f32_e32 v100, v100, v200
	v_sub_f32_e32 v105, v105, v200
	v_sub_f32_e32 v104, v104, v200
	v_sub_f32_e32 v107, v107, v200
	v_sub_f32_e32 v106, v106, v200
	v_sub_f32_e32 v103, v103, v200
	v_sub_f32_e32 v102, v102, v200
	v_pk_mul_f32 v[100:101], v[200:201], v[100:101] op_sel:[1,0]
	v_pk_mul_f32 v[106:107], v[200:201], v[106:107] op_sel:[1,0]
	v_pk_mul_f32 v[104:105], v[200:201], v[104:105] op_sel:[1,0]
	v_pk_mul_f32 v[102:103], v[200:201], v[102:103] op_sel:[1,0]
	v_pk_mul_f32 v[100:101], v[86:87], v[100:101]
	v_pk_mul_f32 v[104:105], v[82:83], v[104:105]
	v_pk_mul_f32 v[106:107], v[84:85], v[106:107]
	v_pk_mul_f32 v[90:91], v[90:91], v[108:109]
	v_pk_mul_f32 v[92:93], v[92:93], v[110:111]
	v_pk_mul_f32 v[102:103], v[88:89], v[102:103]
	v_pk_mul_f32 v[94:95], v[94:95], v[100:101]
	v_pk_mul_f32 v[100:101], v[92:93], v[106:107]
	v_pk_mul_f32 v[92:93], v[90:91], v[104:105]
	v_pk_mul_f32 v[96:97], v[96:97], v[102:103]
	v_cvt_pk_bf16_f32 v92, v92, v93
	v_cvt_pk_bf16_f32 v93, v100, v101
	v_mul_f32_e32 v100, 0xbfb8aa3b, v78
	v_mul_f32_e32 v101, 0xbfb8aa3b, v79
	v_mul_f32_e32 v102, 0xbfb8aa3b, v80
	v_mul_f32_e32 v103, 0xbfb8aa3b, v81
	v_exp_f32_e32 v100, v100
	v_exp_f32_e32 v101, v101
	v_exp_f32_e32 v102, v102
	v_exp_f32_e32 v103, v103
	v_add_f32_e32 v100, 1.0, v100
	v_add_f32_e32 v101, 1.0, v101
	v_add_f32_e32 v102, 1.0, v102
	v_add_f32_e32 v103, 1.0, v103
	v_rcp_f32_e32 v100, v100
	v_rcp_f32_e32 v101, v101
	v_rcp_f32_e32 v102, v102
	v_rcp_f32_e32 v103, v103
	v_lshl_add_u64 v[98:99], s[34:35], 0, v[202:203]
	v_pk_mul_f32 v[78:79], v[78:79], v[100:101]
	v_mul_f32_e32 v100, 0xbfb8aa3b, v74
	v_pk_mul_f32 v[80:81], v[80:81], v[102:103]
	v_mul_f32_e32 v101, 0xbfb8aa3b, v75
	v_mul_f32_e32 v102, 0xbfb8aa3b, v76
	v_mul_f32_e32 v103, 0xbfb8aa3b, v77
	v_exp_f32_e32 v100, v100
	v_exp_f32_e32 v101, v101
	v_exp_f32_e32 v102, v102
	v_exp_f32_e32 v103, v103
	v_add_f32_e32 v100, 1.0, v100
	v_add_f32_e32 v101, 1.0, v101
	v_add_f32_e32 v102, 1.0, v102
	v_add_f32_e32 v103, 1.0, v103
	v_lshl_add_u64 v[98:99], v[98:99], 0, v[182:183]
	v_cvt_pk_bf16_f32 v90, v94, v95
	v_cvt_pk_bf16_f32 v91, v96, v97
	v_rcp_f32_e32 v100, v100
	v_rcp_f32_e32 v101, v101
	v_rcp_f32_e32 v102, v102
	v_rcp_f32_e32 v103, v103
	global_store_dwordx4 v[98:99], v[90:93], off
	v_lshlrev_b32_e32 v94, 16, v148
	v_and_b32_e32 v95, 0xffff0000, v148
	v_lshlrev_b32_e32 v90, 16, v146
	v_and_b32_e32 v91, 0xffff0000, v146
	v_lshlrev_b32_e32 v96, 16, v149
	v_and_b32_e32 v97, 0xffff0000, v149
	v_lshlrev_b32_e32 v92, 16, v147
	v_and_b32_e32 v93, 0xffff0000, v147
	v_sub_f32_e32 v91, v91, v200
	v_sub_f32_e32 v90, v90, v200
	v_sub_f32_e32 v95, v95, v200
	v_sub_f32_e32 v94, v94, v200
	v_sub_f32_e32 v97, v97, v200
	v_sub_f32_e32 v96, v96, v200
	v_sub_f32_e32 v93, v93, v200
	v_sub_f32_e32 v92, v92, v200
	v_pk_mul_f32 v[90:91], v[200:201], v[90:91] op_sel:[1,0]
	v_pk_mul_f32 v[96:97], v[200:201], v[96:97] op_sel:[1,0]
	v_pk_mul_f32 v[94:95], v[200:201], v[94:95] op_sel:[1,0]
	v_pk_mul_f32 v[92:93], v[200:201], v[92:93] op_sel:[1,0]
	v_pk_mul_f32 v[90:91], v[70:71], v[90:91]
	v_pk_mul_f32 v[94:95], v[66:67], v[94:95]
	v_pk_mul_f32 v[96:97], v[68:69], v[96:97]
	v_pk_mul_f32 v[74:75], v[74:75], v[100:101]
	v_pk_mul_f32 v[76:77], v[76:77], v[102:103]
	v_pk_mul_f32 v[92:93], v[72:73], v[92:93]
	v_pk_mul_f32 v[78:79], v[78:79], v[90:91]
	v_pk_mul_f32 v[90:91], v[76:77], v[96:97]
	v_pk_mul_f32 v[76:77], v[74:75], v[94:95]
	v_pk_mul_f32 v[80:81], v[80:81], v[92:93]
	v_cvt_pk_bf16_f32 v74, v78, v79
	v_cvt_pk_bf16_f32 v76, v76, v77
	v_cvt_pk_bf16_f32 v77, v90, v91
	s_nop 0
	v_cvt_pk_bf16_f32 v75, v80, v81
	global_store_dwordx4 v[98:99], v[74:77], off offset:256
	v_lshlrev_b64 v[118:119], 12, v[190:191]
	s_nop 0
	v_lshl_add_u64 v[74:75], v[198:199], 0, v[118:119]
	v_lshlrev_b64 v[120:121], 12, v[192:193]
	global_load_dwordx4 v[106:109], v[74:75], off
	global_load_dwordx4 v[110:113], v[74:75], off offset:256
	v_lshl_add_u64 v[74:75], v[198:199], 0, v[120:121]
	v_lshlrev_b64 v[104:105], 12, v[194:195]
	global_load_dwordx4 v[114:117], v[74:75], off
	global_load_dwordx4 v[98:101], v[74:75], off offset:256
	v_lshl_add_u64 v[74:75], v[198:199], 0, v[104:105]
	v_lshlrev_b64 v[102:103], 12, v[196:197]
	global_load_dwordx4 v[94:97], v[74:75], off
	global_load_dwordx4 v[90:93], v[74:75], off offset:256
	v_lshl_add_u64 v[74:75], v[198:199], 0, v[102:103]
	global_load_dwordx4 v[78:81], v[74:75], off
	s_nop 0
	global_load_dwordx4 v[74:77], v[74:75], off offset:256
	s_waitcnt vmcnt(0)
; __device__ __forceinline__ unsigned cvt_pk_bf16(float lo, float hi) { unsigned r; asm("v_cvt_pk_bf16_f32 %0, %1, %2" : "=v"(r) : "v"(lo), "v"(hi)); return r; }
; __device__ __forceinline__ float bf_lo(unsigned u) { return __uint_as_float(u << 16); }
; __device__ __forceinline__ float bf_hi(unsigned u) { return __uint_as_float(u & 0xffff0000u); }
;     __device__ __forceinline__ void operator()(const AccT& acc, const Unit& u, int wr, int wc, int fr, int fq) const {
;     ...
; #pragma unroll
;             for (int m = 0; m < 4; ++m) { bf16_t* rowp = A2 + (size_t)(row0 + ai * 128 + m * 16) * 2048 + col0;
;                 const float mu = st[ai][m][0], rs = st[ai][m][1];
; #pragma unroll
;                 for (int bj = 0; bj < 2; ++bj) { const f32x4 v0 = acc[ai][bj][m][0], v1 = acc[ai][bj][m][1]; const u32x4 yw = yv[m][bj];
;                     const f32x4 y0 = (f32x4){bf_lo(yw.x), bf_hi(yw.x), bf_lo(yw.y), bf_hi(yw.y)}, y1 = (f32x4){bf_lo(yw.z), bf_hi(yw.z), bf_lo(yw.w), bf_hi(yw.w)};
;                     const f32x4 n0 = (y0 - mu) * rs * gw[bj][0], n1 = (y1 - mu) * rs * gw[bj][1];
;                     const f32x4 s0 = silu4(v0) * n0, s1 = silu4(v1) * n1;
;                     u32x4 w; w.x = cvt_pk_bf16(s0[0], s0[1]); w.y = cvt_pk_bf16(s0[2], s0[3]); w.z = cvt_pk_bf16(s1[0], s1[1]); w.w = cvt_pk_bf16(s1[2], s1[3]);
;                     *(u32x4*)(rowp + bj * 128) = w; } }
	v_lshlrev_b32_e32 v122, 16, v106
	v_and_b32_e32 v106, 0xffff0000, v106
	v_lshlrev_b32_e32 v123, 16, v107
	v_and_b32_e32 v124, 0xffff0000, v107
	v_lshlrev_b32_e32 v125, 16, v108
	v_and_b32_e32 v126, 0xffff0000, v108
	v_lshlrev_b32_e32 v127, 16, v109
	v_and_b32_e32 v128, 0xffff0000, v109
	v_sub_f32_e32 v107, v106, v188
	v_sub_f32_e32 v106, v122, v188
	v_sub_f32_e32 v109, v124, v188
	v_sub_f32_e32 v108, v123, v188
	v_sub_f32_e32 v123, v126, v188
	v_sub_f32_e32 v122, v125, v188
	v_sub_f32_e32 v125, v128, v188
	v_sub_f32_e32 v124, v127, v188
	v_mul_f32_e32 v126, 0xbfb8aa3b, v62
	v_mul_f32_e32 v127, 0xbfb8aa3b, v63
	v_mul_f32_e32 v128, 0xbfb8aa3b, v64
	v_mul_f32_e32 v129, 0xbfb8aa3b, v65
	v_exp_f32_e32 v126, v126
	v_exp_f32_e32 v127, v127
	v_exp_f32_e32 v128, v128
	v_exp_f32_e32 v129, v129
	v_add_f32_e32 v126, 1.0, v126
	v_add_f32_e32 v127, 1.0, v127
	v_add_f32_e32 v128, 1.0, v128
	v_add_f32_e32 v129, 1.0, v129
	v_rcp_f32_e32 v126, v126
	v_rcp_f32_e32 v127, v127
	v_rcp_f32_e32 v128, v128
	v_rcp_f32_e32 v129, v129
	v_pk_mul_f32 v[106:107], v[188:189], v[106:107] op_sel:[1,0]
	v_pk_mul_f32 v[62:63], v[62:63], v[126:127]
	v_mul_f32_e32 v126, 0xbfb8aa3b, v58
	v_pk_mul_f32 v[64:65], v[64:65], v[128:129]
	v_mul_f32_e32 v127, 0xbfb8aa3b, v59
	v_mul_f32_e32 v128, 0xbfb8aa3b, v60
	v_mul_f32_e32 v129, 0xbfb8aa3b, v61
	v_exp_f32_e32 v126, v126
	v_exp_f32_e32 v127, v127
	v_exp_f32_e32 v128, v128
	v_exp_f32_e32 v129, v129
	v_add_f32_e32 v126, 1.0, v126
	v_add_f32_e32 v127, 1.0, v127
	v_add_f32_e32 v128, 1.0, v128
	v_add_f32_e32 v129, 1.0, v129
	v_rcp_f32_e32 v126, v126
	v_rcp_f32_e32 v127, v127
	v_rcp_f32_e32 v128, v128
	v_rcp_f32_e32 v129, v129
	v_pk_mul_f32 v[124:125], v[188:189], v[124:125] op_sel:[1,0]
	v_pk_mul_f32 v[122:123], v[188:189], v[122:123] op_sel:[1,0]
	v_pk_mul_f32 v[108:109], v[188:189], v[108:109] op_sel:[1,0]
	v_pk_mul_f32 v[106:107], v[86:87], v[106:107]
	v_pk_mul_f32 v[122:123], v[82:83], v[122:123]
	v_pk_mul_f32 v[124:125], v[84:85], v[124:125]
	v_pk_mul_f32 v[58:59], v[58:59], v[126:127]
	v_pk_mul_f32 v[60:61], v[60:61], v[128:129]
	v_pk_mul_f32 v[108:109], v[88:89], v[108:109]
	v_pk_mul_f32 v[62:63], v[62:63], v[106:107]
	v_pk_mul_f32 v[106:107], v[60:61], v[124:125]
	v_pk_mul_f32 v[60:61], v[58:59], v[122:123]
	v_pk_mul_f32 v[64:65], v[64:65], v[108:109]
	v_cvt_pk_bf16_f32 v60, v60, v61
	v_cvt_pk_bf16_f32 v61, v106, v107
	v_mul_f32_e32 v106, 0xbfb8aa3b, v54
	v_mul_f32_e32 v107, 0xbfb8aa3b, v55
	v_mul_f32_e32 v108, 0xbfb8aa3b, v56
	v_mul_f32_e32 v109, 0xbfb8aa3b, v57
	v_exp_f32_e32 v106, v106
	v_exp_f32_e32 v107, v107
	v_exp_f32_e32 v108, v108
	v_exp_f32_e32 v109, v109
	v_add_f32_e32 v106, 1.0, v106
	v_add_f32_e32 v107, 1.0, v107
	v_add_f32_e32 v108, 1.0, v108
	v_add_f32_e32 v109, 1.0, v109
	v_rcp_f32_e32 v106, v106
	v_rcp_f32_e32 v107, v107
	v_rcp_f32_e32 v108, v108
	v_rcp_f32_e32 v109, v109
	v_lshl_add_u64 v[118:119], s[34:35], 0, v[118:119]
	v_pk_mul_f32 v[54:55], v[54:55], v[106:107]
	v_mul_f32_e32 v106, 0xbfb8aa3b, v50
	v_pk_mul_f32 v[56:57], v[56:57], v[108:109]
	v_mul_f32_e32 v107, 0xbfb8aa3b, v51
	v_mul_f32_e32 v108, 0xbfb8aa3b, v52
	v_mul_f32_e32 v109, 0xbfb8aa3b, v53
	v_exp_f32_e32 v106, v106
	v_exp_f32_e32 v107, v107
	v_exp_f32_e32 v108, v108
	v_exp_f32_e32 v109, v109
	v_add_f32_e32 v106, 1.0, v106
	v_add_f32_e32 v107, 1.0, v107
	v_add_f32_e32 v108, 1.0, v108
	v_add_f32_e32 v109, 1.0, v109
	v_lshl_add_u64 v[118:119], v[118:119], 0, v[182:183]
	v_cvt_pk_bf16_f32 v58, v62, v63
	v_cvt_pk_bf16_f32 v59, v64, v65
	v_rcp_f32_e32 v106, v106
	v_rcp_f32_e32 v107, v107
	v_rcp_f32_e32 v108, v108
	v_rcp_f32_e32 v109, v109
	global_store_dwordx4 v[118:119], v[58:61], off
	v_lshlrev_b32_e32 v62, 16, v112
	v_and_b32_e32 v63, 0xffff0000, v112
	v_lshlrev_b32_e32 v58, 16, v110
	v_and_b32_e32 v59, 0xffff0000, v110
	v_lshlrev_b32_e32 v60, 16, v111
	v_and_b32_e32 v61, 0xffff0000, v111
	v_lshlrev_b32_e32 v64, 16, v113
	v_and_b32_e32 v65, 0xffff0000, v113
	v_sub_f32_e32 v59, v59, v188
	v_sub_f32_e32 v58, v58, v188
	v_sub_f32_e32 v61, v61, v188
	v_sub_f32_e32 v60, v60, v188
	v_sub_f32_e32 v63, v63, v188
	v_sub_f32_e32 v62, v62, v188
	v_sub_f32_e32 v65, v65, v188
	v_sub_f32_e32 v64, v64, v188
	v_pk_mul_f32 v[60:61], v[188:189], v[60:61] op_sel:[1,0]
	v_pk_mul_f32 v[58:59], v[188:189], v[58:59] op_sel:[1,0]
	v_pk_mul_f32 v[64:65], v[188:189], v[64:65] op_sel:[1,0]
	v_pk_mul_f32 v[62:63], v[188:189], v[62:63] op_sel:[1,0]
	v_pk_mul_f32 v[58:59], v[70:71], v[58:59]
	v_pk_mul_f32 v[60:61], v[72:73], v[60:61]
	v_pk_mul_f32 v[62:63], v[66:67], v[62:63]
	v_pk_mul_f32 v[64:65], v[68:69], v[64:65]
	v_pk_mul_f32 v[50:51], v[50:51], v[106:107]
	v_pk_mul_f32 v[52:53], v[52:53], v[108:109]
	v_pk_mul_f32 v[56:57], v[56:57], v[60:61]
	v_pk_mul_f32 v[54:55], v[54:55], v[58:59]
	v_pk_mul_f32 v[58:59], v[52:53], v[64:65]
	v_pk_mul_f32 v[52:53], v[50:51], v[62:63]
	v_mul_f32_e32 v60, 0xbfb8aa3b, v46
	v_mul_f32_e32 v61, 0xbfb8aa3b, v47
	v_mul_f32_e32 v62, 0xbfb8aa3b, v48
	v_mul_f32_e32 v63, 0xbfb8aa3b, v49
	v_exp_f32_e32 v60, v60
	v_exp_f32_e32 v61, v61
	v_exp_f32_e32 v62, v62
	v_exp_f32_e32 v63, v63
	v_add_f32_e32 v60, 1.0, v60
	v_add_f32_e32 v61, 1.0, v61
	v_add_f32_e32 v62, 1.0, v62
	v_add_f32_e32 v63, 1.0, v63
	v_rcp_f32_e32 v60, v60
	v_rcp_f32_e32 v61, v61
	v_rcp_f32_e32 v62, v62
	v_rcp_f32_e32 v63, v63
	v_cvt_pk_bf16_f32 v52, v52, v53
	v_pk_mul_f32 v[46:47], v[46:47], v[60:61]
	v_mul_f32_e32 v60, 0xbfb8aa3b, v42
	v_pk_mul_f32 v[48:49], v[48:49], v[62:63]
	v_mul_f32_e32 v61, 0xbfb8aa3b, v43
	v_mul_f32_e32 v62, 0xbfb8aa3b, v44
	v_mul_f32_e32 v63, 0xbfb8aa3b, v45
	v_exp_f32_e32 v60, v60
	v_exp_f32_e32 v61, v61
	v_exp_f32_e32 v62, v62
	v_exp_f32_e32 v63, v63
; __device__ __forceinline__ unsigned cvt_pk_bf16(float lo, float hi) { unsigned r; asm("v_cvt_pk_bf16_f32 %0, %1, %2" : "=v"(r) : "v"(lo), "v"(hi)); return r; }
; __device__ __forceinline__ float bf_lo(unsigned u) { return __uint_as_float(u << 16); }
; __device__ __forceinline__ float bf_hi(unsigned u) { return __uint_as_float(u & 0xffff0000u); }
;     __device__ __forceinline__ void operator()(const AccT& acc, const Unit& u, int wr, int wc, int fr, int fq) const {
;     ...
; #pragma unroll
;             for (int m = 0; m < 4; ++m) { bf16_t* rowp = A2 + (size_t)(row0 + ai * 128 + m * 16) * 2048 + col0;
;                 const float mu = st[ai][m][0], rs = st[ai][m][1];
; #pragma unroll
;                 for (int bj = 0; bj < 2; ++bj) { const f32x4 v0 = acc[ai][bj][m][0], v1 = acc[ai][bj][m][1]; const u32x4 yw = yv[m][bj];
;                     const f32x4 y0 = (f32x4){bf_lo(yw.x), bf_hi(yw.x), bf_lo(yw.y), bf_hi(yw.y)}, y1 = (f32x4){bf_lo(yw.z), bf_hi(yw.z), bf_lo(yw.w), bf_hi(yw.w)};
;                     const f32x4 n0 = (y0 - mu) * rs * gw[bj][0], n1 = (y1 - mu) * rs * gw[bj][1];
;                     const f32x4 s0 = silu4(v0) * n0, s1 = silu4(v1) * n1;
;                     u32x4 w; w.x = cvt_pk_bf16(s0[0], s0[1]); w.y = cvt_pk_bf16(s0[2], s0[3]); w.z = cvt_pk_bf16(s1[0], s1[1]); w.w = cvt_pk_bf16(s1[2], s1[3]);
;                     *(u32x4*)(rowp + bj * 128) = w; } }
	v_add_f32_e32 v60, 1.0, v60
	v_add_f32_e32 v61, 1.0, v61
	v_add_f32_e32 v62, 1.0, v62
	v_add_f32_e32 v63, 1.0, v63
	v_cvt_pk_bf16_f32 v53, v58, v59
	v_rcp_f32_e32 v60, v60
	v_rcp_f32_e32 v61, v61
	v_rcp_f32_e32 v62, v62
	v_rcp_f32_e32 v63, v63
	v_cvt_pk_bf16_f32 v50, v54, v55
	v_cvt_pk_bf16_f32 v51, v56, v57
	global_store_dwordx4 v[118:119], v[50:53], off offset:256
	v_lshlrev_b32_e32 v56, 16, v116
	v_and_b32_e32 v57, 0xffff0000, v116
	v_lshlrev_b32_e32 v52, 16, v114
	v_and_b32_e32 v53, 0xffff0000, v114
	v_lshlrev_b32_e32 v58, 16, v117
	v_and_b32_e32 v59, 0xffff0000, v117
	v_lshlrev_b32_e32 v54, 16, v115
	v_and_b32_e32 v55, 0xffff0000, v115
	v_sub_f32_e32 v53, v53, v186
	v_sub_f32_e32 v52, v52, v186
	v_sub_f32_e32 v57, v57, v186
	v_sub_f32_e32 v56, v56, v186
	v_sub_f32_e32 v59, v59, v186
	v_sub_f32_e32 v58, v58, v186
	v_sub_f32_e32 v55, v55, v186
	v_sub_f32_e32 v54, v54, v186
	v_pk_mul_f32 v[52:53], v[186:187], v[52:53] op_sel:[1,0]
	v_pk_mul_f32 v[58:59], v[186:187], v[58:59] op_sel:[1,0]
	v_pk_mul_f32 v[56:57], v[186:187], v[56:57] op_sel:[1,0]
	v_pk_mul_f32 v[54:55], v[186:187], v[54:55] op_sel:[1,0]
	v_pk_mul_f32 v[52:53], v[86:87], v[52:53]
	v_pk_mul_f32 v[56:57], v[82:83], v[56:57]
	v_pk_mul_f32 v[58:59], v[84:85], v[58:59]
	v_pk_mul_f32 v[42:43], v[42:43], v[60:61]
	v_pk_mul_f32 v[44:45], v[44:45], v[62:63]
	v_pk_mul_f32 v[54:55], v[88:89], v[54:55]
	v_pk_mul_f32 v[46:47], v[46:47], v[52:53]
	v_pk_mul_f32 v[52:53], v[44:45], v[58:59]
	v_pk_mul_f32 v[44:45], v[42:43], v[56:57]
	v_pk_mul_f32 v[48:49], v[48:49], v[54:55]
	v_cvt_pk_bf16_f32 v44, v44, v45
	v_cvt_pk_bf16_f32 v45, v52, v53
	v_mul_f32_e32 v52, 0xbfb8aa3b, v38
	v_mul_f32_e32 v53, 0xbfb8aa3b, v39
	v_mul_f32_e32 v54, 0xbfb8aa3b, v40
	v_mul_f32_e32 v55, 0xbfb8aa3b, v41
	v_exp_f32_e32 v52, v52
	v_exp_f32_e32 v53, v53
	v_exp_f32_e32 v54, v54
	v_exp_f32_e32 v55, v55
	v_add_f32_e32 v52, 1.0, v52
	v_add_f32_e32 v53, 1.0, v53
	v_add_f32_e32 v54, 1.0, v54
	v_add_f32_e32 v55, 1.0, v55
	v_rcp_f32_e32 v52, v52
	v_rcp_f32_e32 v53, v53
	v_rcp_f32_e32 v54, v54
	v_rcp_f32_e32 v55, v55
	v_lshl_add_u64 v[50:51], s[34:35], 0, v[120:121]
	v_pk_mul_f32 v[38:39], v[38:39], v[52:53]
	v_mul_f32_e32 v52, 0xbfb8aa3b, v34
	v_pk_mul_f32 v[40:41], v[40:41], v[54:55]
	v_mul_f32_e32 v53, 0xbfb8aa3b, v35
	v_mul_f32_e32 v54, 0xbfb8aa3b, v36
	v_mul_f32_e32 v55, 0xbfb8aa3b, v37
	v_exp_f32_e32 v52, v52
	v_exp_f32_e32 v53, v53
	v_exp_f32_e32 v54, v54
	v_exp_f32_e32 v55, v55
	v_add_f32_e32 v52, 1.0, v52
	v_add_f32_e32 v53, 1.0, v53
	v_add_f32_e32 v54, 1.0, v54
	v_add_f32_e32 v55, 1.0, v55
	v_lshl_add_u64 v[50:51], v[50:51], 0, v[182:183]
	v_cvt_pk_bf16_f32 v42, v46, v47
	v_cvt_pk_bf16_f32 v43, v48, v49
	v_rcp_f32_e32 v52, v52
	v_rcp_f32_e32 v53, v53
	v_rcp_f32_e32 v54, v54
	v_rcp_f32_e32 v55, v55
	global_store_dwordx4 v[50:51], v[42:45], off
	v_lshlrev_b32_e32 v46, 16, v100
	v_and_b32_e32 v47, 0xffff0000, v100
	v_lshlrev_b32_e32 v42, 16, v98
	v_and_b32_e32 v43, 0xffff0000, v98
	v_lshlrev_b32_e32 v44, 16, v99
	v_and_b32_e32 v45, 0xffff0000, v99
	v_lshlrev_b32_e32 v48, 16, v101
	v_and_b32_e32 v49, 0xffff0000, v101
	v_sub_f32_e32 v43, v43, v186
	v_sub_f32_e32 v42, v42, v186
	v_sub_f32_e32 v45, v45, v186
	v_sub_f32_e32 v44, v44, v186
	v_sub_f32_e32 v47, v47, v186
	v_sub_f32_e32 v46, v46, v186
	v_sub_f32_e32 v49, v49, v186
	v_sub_f32_e32 v48, v48, v186
	v_pk_mul_f32 v[44:45], v[186:187], v[44:45] op_sel:[1,0]
	v_pk_mul_f32 v[42:43], v[186:187], v[42:43] op_sel:[1,0]
	v_pk_mul_f32 v[48:49], v[186:187], v[48:49] op_sel:[1,0]
	v_pk_mul_f32 v[46:47], v[186:187], v[46:47] op_sel:[1,0]
	v_pk_mul_f32 v[42:43], v[70:71], v[42:43]
	v_pk_mul_f32 v[44:45], v[72:73], v[44:45]
	v_pk_mul_f32 v[46:47], v[66:67], v[46:47]
	v_pk_mul_f32 v[48:49], v[68:69], v[48:49]
	v_pk_mul_f32 v[34:35], v[34:35], v[52:53]
	v_pk_mul_f32 v[36:37], v[36:37], v[54:55]
	v_pk_mul_f32 v[40:41], v[40:41], v[44:45]
	v_pk_mul_f32 v[38:39], v[38:39], v[42:43]
	v_pk_mul_f32 v[42:43], v[36:37], v[48:49]
	v_pk_mul_f32 v[36:37], v[34:35], v[46:47]
	v_mul_f32_e32 v44, 0xbfb8aa3b, v30
	v_mul_f32_e32 v45, 0xbfb8aa3b, v31
	v_mul_f32_e32 v46, 0xbfb8aa3b, v32
	v_mul_f32_e32 v47, 0xbfb8aa3b, v33
	v_exp_f32_e32 v44, v44
	v_exp_f32_e32 v45, v45
	v_exp_f32_e32 v46, v46
	v_exp_f32_e32 v47, v47
	v_add_f32_e32 v44, 1.0, v44
	v_add_f32_e32 v45, 1.0, v45
	v_add_f32_e32 v46, 1.0, v46
	v_add_f32_e32 v47, 1.0, v47
	v_rcp_f32_e32 v44, v44
	v_rcp_f32_e32 v45, v45
	v_rcp_f32_e32 v46, v46
	v_rcp_f32_e32 v47, v47
	v_cvt_pk_bf16_f32 v36, v36, v37
	v_pk_mul_f32 v[30:31], v[30:31], v[44:45]
	v_mul_f32_e32 v44, 0xbfb8aa3b, v26
	v_pk_mul_f32 v[32:33], v[32:33], v[46:47]
	v_mul_f32_e32 v45, 0xbfb8aa3b, v27
	v_mul_f32_e32 v46, 0xbfb8aa3b, v28
	v_mul_f32_e32 v47, 0xbfb8aa3b, v29
	v_exp_f32_e32 v44, v44
	v_exp_f32_e32 v45, v45
	v_exp_f32_e32 v46, v46
	v_exp_f32_e32 v47, v47
	v_add_f32_e32 v44, 1.0, v44
	v_add_f32_e32 v45, 1.0, v45
	v_add_f32_e32 v46, 1.0, v46
	v_add_f32_e32 v47, 1.0, v47
	v_cvt_pk_bf16_f32 v37, v42, v43
	v_rcp_f32_e32 v44, v44
	v_rcp_f32_e32 v45, v45
	v_rcp_f32_e32 v46, v46
	v_rcp_f32_e32 v47, v47
	v_cvt_pk_bf16_f32 v34, v38, v39
	v_cvt_pk_bf16_f32 v35, v40, v41
	global_store_dwordx4 v[50:51], v[34:37], off offset:256
	v_lshlrev_b32_e32 v40, 16, v96
	v_and_b32_e32 v41, 0xffff0000, v96
	v_lshlrev_b32_e32 v36, 16, v94
	v_and_b32_e32 v37, 0xffff0000, v94
	v_lshlrev_b32_e32 v42, 16, v97
	v_and_b32_e32 v43, 0xffff0000, v97
	v_lshlrev_b32_e32 v38, 16, v95
	v_and_b32_e32 v39, 0xffff0000, v95
	v_sub_f32_e32 v37, v37, v184
	v_sub_f32_e32 v36, v36, v184
	v_sub_f32_e32 v41, v41, v184
	v_sub_f32_e32 v40, v40, v184
	v_sub_f32_e32 v43, v43, v184
	v_sub_f32_e32 v42, v42, v184
; __device__ __forceinline__ unsigned cvt_pk_bf16(float lo, float hi) { unsigned r; asm("v_cvt_pk_bf16_f32 %0, %1, %2" : "=v"(r) : "v"(lo), "v"(hi)); return r; }
; __device__ __forceinline__ float bf_lo(unsigned u) { return __uint_as_float(u << 16); }
; __device__ __forceinline__ float bf_hi(unsigned u) { return __uint_as_float(u & 0xffff0000u); }
;     __device__ __forceinline__ void operator()(const AccT& acc, const Unit& u, int wr, int wc, int fr, int fq) const {
;     ...
; #pragma unroll
;             for (int m = 0; m < 4; ++m) { bf16_t* rowp = A2 + (size_t)(row0 + ai * 128 + m * 16) * 2048 + col0;
;                 const float mu = st[ai][m][0], rs = st[ai][m][1];
; #pragma unroll
;                 for (int bj = 0; bj < 2; ++bj) { const f32x4 v0 = acc[ai][bj][m][0], v1 = acc[ai][bj][m][1]; const u32x4 yw = yv[m][bj];
;                     const f32x4 y0 = (f32x4){bf_lo(yw.x), bf_hi(yw.x), bf_lo(yw.y), bf_hi(yw.y)}, y1 = (f32x4){bf_lo(yw.z), bf_hi(yw.z), bf_lo(yw.w), bf_hi(yw.w)};
;                     const f32x4 n0 = (y0 - mu) * rs * gw[bj][0], n1 = (y1 - mu) * rs * gw[bj][1];
;                     const f32x4 s0 = silu4(v0) * n0, s1 = silu4(v1) * n1;
;                     u32x4 w; w.x = cvt_pk_bf16(s0[0], s0[1]); w.y = cvt_pk_bf16(s0[2], s0[3]); w.z = cvt_pk_bf16(s1[0], s1[1]); w.w = cvt_pk_bf16(s1[2], s1[3]);
;                     *(u32x4*)(rowp + bj * 128) = w; } }
	v_sub_f32_e32 v39, v39, v184
	v_sub_f32_e32 v38, v38, v184
	v_pk_mul_f32 v[36:37], v[184:185], v[36:37] op_sel:[1,0]
	v_pk_mul_f32 v[42:43], v[184:185], v[42:43] op_sel:[1,0]
	v_pk_mul_f32 v[40:41], v[184:185], v[40:41] op_sel:[1,0]
	v_pk_mul_f32 v[38:39], v[184:185], v[38:39] op_sel:[1,0]
	v_pk_mul_f32 v[36:37], v[86:87], v[36:37]
	v_pk_mul_f32 v[40:41], v[82:83], v[40:41]
	v_pk_mul_f32 v[42:43], v[84:85], v[42:43]
	v_pk_mul_f32 v[26:27], v[26:27], v[44:45]
	v_pk_mul_f32 v[28:29], v[28:29], v[46:47]
	v_pk_mul_f32 v[38:39], v[88:89], v[38:39]
	v_pk_mul_f32 v[30:31], v[30:31], v[36:37]
	v_pk_mul_f32 v[36:37], v[28:29], v[42:43]
	v_pk_mul_f32 v[28:29], v[26:27], v[40:41]
	v_pk_mul_f32 v[32:33], v[32:33], v[38:39]
	v_cvt_pk_bf16_f32 v28, v28, v29
	v_cvt_pk_bf16_f32 v29, v36, v37
	v_mul_f32_e32 v36, 0xbfb8aa3b, v22
	v_mul_f32_e32 v37, 0xbfb8aa3b, v23
	v_mul_f32_e32 v38, 0xbfb8aa3b, v24
	v_mul_f32_e32 v39, 0xbfb8aa3b, v25
	v_exp_f32_e32 v36, v36
	v_exp_f32_e32 v37, v37
	v_exp_f32_e32 v38, v38
	v_exp_f32_e32 v39, v39
	v_add_f32_e32 v36, 1.0, v36
	v_add_f32_e32 v37, 1.0, v37
	v_add_f32_e32 v38, 1.0, v38
	v_add_f32_e32 v39, 1.0, v39
	v_rcp_f32_e32 v36, v36
	v_rcp_f32_e32 v37, v37
	v_rcp_f32_e32 v38, v38
	v_rcp_f32_e32 v39, v39
	v_lshl_add_u64 v[34:35], s[34:35], 0, v[104:105]
	v_pk_mul_f32 v[22:23], v[22:23], v[36:37]
	v_mul_f32_e32 v36, 0xbfb8aa3b, v18
	v_pk_mul_f32 v[24:25], v[24:25], v[38:39]
	v_mul_f32_e32 v37, 0xbfb8aa3b, v19
	v_mul_f32_e32 v38, 0xbfb8aa3b, v20
	v_mul_f32_e32 v39, 0xbfb8aa3b, v21
	v_exp_f32_e32 v36, v36
	v_exp_f32_e32 v37, v37
	v_exp_f32_e32 v38, v38
	v_exp_f32_e32 v39, v39
	v_add_f32_e32 v36, 1.0, v36
	v_add_f32_e32 v37, 1.0, v37
	v_add_f32_e32 v38, 1.0, v38
	v_add_f32_e32 v39, 1.0, v39
	v_lshl_add_u64 v[34:35], v[34:35], 0, v[182:183]
	v_cvt_pk_bf16_f32 v26, v30, v31
	v_cvt_pk_bf16_f32 v27, v32, v33
	v_rcp_f32_e32 v36, v36
	v_rcp_f32_e32 v37, v37
	v_rcp_f32_e32 v38, v38
	v_rcp_f32_e32 v39, v39
	global_store_dwordx4 v[34:35], v[26:29], off
	v_lshlrev_b32_e32 v30, 16, v92
	v_and_b32_e32 v31, 0xffff0000, v92
	v_lshlrev_b32_e32 v26, 16, v90
	v_and_b32_e32 v27, 0xffff0000, v90
	v_lshlrev_b32_e32 v28, 16, v91
	v_and_b32_e32 v29, 0xffff0000, v91
	v_lshlrev_b32_e32 v32, 16, v93
	v_and_b32_e32 v33, 0xffff0000, v93
	v_sub_f32_e32 v27, v27, v184
	v_sub_f32_e32 v26, v26, v184
	v_sub_f32_e32 v29, v29, v184
	v_sub_f32_e32 v28, v28, v184
	v_sub_f32_e32 v31, v31, v184
	v_sub_f32_e32 v30, v30, v184
	v_sub_f32_e32 v33, v33, v184
	v_sub_f32_e32 v32, v32, v184
	v_pk_mul_f32 v[28:29], v[184:185], v[28:29] op_sel:[1,0]
	v_pk_mul_f32 v[26:27], v[184:185], v[26:27] op_sel:[1,0]
	v_pk_mul_f32 v[32:33], v[184:185], v[32:33] op_sel:[1,0]
	v_pk_mul_f32 v[30:31], v[184:185], v[30:31] op_sel:[1,0]
	v_pk_mul_f32 v[26:27], v[70:71], v[26:27]
	v_pk_mul_f32 v[28:29], v[72:73], v[28:29]
	v_pk_mul_f32 v[30:31], v[66:67], v[30:31]
	v_pk_mul_f32 v[32:33], v[68:69], v[32:33]
	v_pk_mul_f32 v[18:19], v[18:19], v[36:37]
	v_pk_mul_f32 v[20:21], v[20:21], v[38:39]
	v_pk_mul_f32 v[24:25], v[24:25], v[28:29]
	v_pk_mul_f32 v[22:23], v[22:23], v[26:27]
	v_pk_mul_f32 v[26:27], v[20:21], v[32:33]
	v_pk_mul_f32 v[20:21], v[18:19], v[30:31]
	v_mul_f32_e32 v28, 0xbfb8aa3b, v14
	v_mul_f32_e32 v29, 0xbfb8aa3b, v15
	v_mul_f32_e32 v30, 0xbfb8aa3b, v16
	v_mul_f32_e32 v31, 0xbfb8aa3b, v17
	v_exp_f32_e32 v28, v28
	v_exp_f32_e32 v29, v29
	v_exp_f32_e32 v30, v30
	v_exp_f32_e32 v31, v31
	v_add_f32_e32 v28, 1.0, v28
	v_add_f32_e32 v29, 1.0, v29
	v_add_f32_e32 v30, 1.0, v30
	v_add_f32_e32 v31, 1.0, v31
	v_rcp_f32_e32 v28, v28
	v_rcp_f32_e32 v29, v29
	v_rcp_f32_e32 v30, v30
	v_rcp_f32_e32 v31, v31
	v_cvt_pk_bf16_f32 v20, v20, v21
	v_pk_mul_f32 v[14:15], v[14:15], v[28:29]
	v_mul_f32_e32 v28, 0xbfb8aa3b, v10
	v_pk_mul_f32 v[16:17], v[16:17], v[30:31]
	v_mul_f32_e32 v29, 0xbfb8aa3b, v11
	v_mul_f32_e32 v30, 0xbfb8aa3b, v12
	v_mul_f32_e32 v31, 0xbfb8aa3b, v13
	v_exp_f32_e32 v28, v28
	v_exp_f32_e32 v29, v29
	v_exp_f32_e32 v30, v30
	v_exp_f32_e32 v31, v31
	v_add_f32_e32 v28, 1.0, v28
	v_add_f32_e32 v29, 1.0, v29
	v_add_f32_e32 v30, 1.0, v30
	v_add_f32_e32 v31, 1.0, v31
	v_cvt_pk_bf16_f32 v21, v26, v27
	v_rcp_f32_e32 v28, v28
	v_rcp_f32_e32 v29, v29
; __device__ __forceinline__ unsigned cvt_pk_bf16(float lo, float hi) { unsigned r; asm("v_cvt_pk_bf16_f32 %0, %1, %2" : "=v"(r) : "v"(lo), "v"(hi)); return r; }
; __device__ __forceinline__ float bf_lo(unsigned u) { return __uint_as_float(u << 16); }
; __device__ __forceinline__ float bf_hi(unsigned u) { return __uint_as_float(u & 0xffff0000u); }
; #define PG8_WAIT_V(n) asm volatile("s_waitcnt vmcnt(" #n ")" ::: "memory")
; #define PG8_BAR __builtin_amdgcn_s_barrier()
; template <class Epi>
; __device__ __forceinline__ void gemm_phase(LAS unsigned char* lds, const Gemm g, const Epi& E) {
;     ...
;         if (!has_next) break;
; #pragma unroll
;         for (int a = 0; a < 2; ++a)
; #pragma unroll
;             for (int b = 0; b < 2; ++b)
; #pragma unroll
;                 for (int m = 0; m < 4; ++m)
; #pragma unroll
;                     for (int n = 0; n < 2; ++n) acc[a][b][m][n] = (f32x4){0.f, 0.f, 0.f, 0.f};
;         cur = nxt; cA = nA; cB = nB; ++ui;
;     }
;     PG8_WAIT_V(0);
;     if (wr == 0) PG8_BAR;
;     PG8_BAR;
;     __device__ __forceinline__ void operator()(const AccT& acc, const Unit& u, int wr, int wc, int fr, int fq) const {
;     ...
; #pragma unroll
;             for (int m = 0; m < 4; ++m) { bf16_t* rowp = A2 + (size_t)(row0 + ai * 128 + m * 16) * 2048 + col0;
;                 const float mu = st[ai][m][0], rs = st[ai][m][1];
; #pragma unroll
;                 for (int bj = 0; bj < 2; ++bj) { const f32x4 v0 = acc[ai][bj][m][0], v1 = acc[ai][bj][m][1]; const u32x4 yw = yv[m][bj];
;                     const f32x4 y0 = (f32x4){bf_lo(yw.x), bf_hi(yw.x), bf_lo(yw.y), bf_hi(yw.y)}, y1 = (f32x4){bf_lo(yw.z), bf_hi(yw.z), bf_lo(yw.w), bf_hi(yw.w)};
;                     const f32x4 n0 = (y0 - mu) * rs * gw[bj][0], n1 = (y1 - mu) * rs * gw[bj][1];
;                     const f32x4 s0 = silu4(v0) * n0, s1 = silu4(v1) * n1;
;                     u32x4 w; w.x = cvt_pk_bf16(s0[0], s0[1]); w.y = cvt_pk_bf16(s0[2], s0[3]); w.z = cvt_pk_bf16(s1[0], s1[1]); w.w = cvt_pk_bf16(s1[2], s1[3]);
;                     *(u32x4*)(rowp + bj * 128) = w; } }
	v_rcp_f32_e32 v30, v30
	v_rcp_f32_e32 v31, v31
	v_cvt_pk_bf16_f32 v18, v22, v23
	v_cvt_pk_bf16_f32 v19, v24, v25
	global_store_dwordx4 v[34:35], v[18:21], off offset:256
	v_lshlrev_b32_e32 v24, 16, v80
	v_and_b32_e32 v25, 0xffff0000, v80
	v_lshlrev_b32_e32 v20, 16, v78
	v_and_b32_e32 v21, 0xffff0000, v78
	v_lshlrev_b32_e32 v26, 16, v81
	v_and_b32_e32 v27, 0xffff0000, v81
	v_lshlrev_b32_e32 v22, 16, v79
	v_and_b32_e32 v23, 0xffff0000, v79
	v_sub_f32_e32 v21, v21, v180
	v_sub_f32_e32 v20, v20, v180
	v_sub_f32_e32 v25, v25, v180
	v_sub_f32_e32 v24, v24, v180
	v_sub_f32_e32 v27, v27, v180
	v_sub_f32_e32 v26, v26, v180
	v_sub_f32_e32 v23, v23, v180
	v_sub_f32_e32 v22, v22, v180
	v_pk_mul_f32 v[20:21], v[180:181], v[20:21] op_sel:[1,0]
	v_pk_mul_f32 v[26:27], v[180:181], v[26:27] op_sel:[1,0]
	v_pk_mul_f32 v[24:25], v[180:181], v[24:25] op_sel:[1,0]
	v_pk_mul_f32 v[22:23], v[180:181], v[22:23] op_sel:[1,0]
	v_pk_mul_f32 v[20:21], v[86:87], v[20:21]
	v_pk_mul_f32 v[24:25], v[82:83], v[24:25]
	v_pk_mul_f32 v[26:27], v[84:85], v[26:27]
	v_pk_mul_f32 v[10:11], v[10:11], v[28:29]
	v_pk_mul_f32 v[12:13], v[12:13], v[30:31]
	v_pk_mul_f32 v[22:23], v[88:89], v[22:23]
	v_pk_mul_f32 v[14:15], v[14:15], v[20:21]
	v_pk_mul_f32 v[20:21], v[12:13], v[26:27]
	v_pk_mul_f32 v[12:13], v[10:11], v[24:25]
	v_pk_mul_f32 v[16:17], v[16:17], v[22:23]
	v_cvt_pk_bf16_f32 v12, v12, v13
	v_cvt_pk_bf16_f32 v13, v20, v21
	v_mul_f32_e32 v20, 0xbfb8aa3b, v6
	v_mul_f32_e32 v21, 0xbfb8aa3b, v7
	v_mul_f32_e32 v22, 0xbfb8aa3b, v8
	v_mul_f32_e32 v23, 0xbfb8aa3b, v9
	v_exp_f32_e32 v20, v20
	v_exp_f32_e32 v21, v21
	v_exp_f32_e32 v22, v22
	v_exp_f32_e32 v23, v23
	v_add_f32_e32 v20, 1.0, v20
	v_add_f32_e32 v21, 1.0, v21
	v_add_f32_e32 v22, 1.0, v22
	v_add_f32_e32 v23, 1.0, v23
	v_rcp_f32_e32 v20, v20
	v_rcp_f32_e32 v21, v21
	v_rcp_f32_e32 v22, v22
	v_rcp_f32_e32 v23, v23
	v_lshl_add_u64 v[18:19], s[34:35], 0, v[102:103]
	v_pk_mul_f32 v[6:7], v[6:7], v[20:21]
	v_mul_f32_e32 v20, 0xbfb8aa3b, v2
	v_pk_mul_f32 v[8:9], v[8:9], v[22:23]
	v_mul_f32_e32 v21, 0xbfb8aa3b, v3
	v_mul_f32_e32 v22, 0xbfb8aa3b, v4
	v_mul_f32_e32 v23, 0xbfb8aa3b, v5
	v_exp_f32_e32 v20, v20
	v_exp_f32_e32 v21, v21
	v_exp_f32_e32 v22, v22
	v_exp_f32_e32 v23, v23
	v_add_f32_e32 v20, 1.0, v20
	v_add_f32_e32 v21, 1.0, v21
	v_add_f32_e32 v22, 1.0, v22
	v_add_f32_e32 v23, 1.0, v23
	v_lshl_add_u64 v[18:19], v[18:19], 0, v[182:183]
	v_cvt_pk_bf16_f32 v10, v14, v15
	v_cvt_pk_bf16_f32 v11, v16, v17
	v_rcp_f32_e32 v20, v20
	v_rcp_f32_e32 v21, v21
	v_rcp_f32_e32 v22, v22
	v_rcp_f32_e32 v23, v23
	global_store_dwordx4 v[18:19], v[10:13], off
	v_lshlrev_b32_e32 v14, 16, v76
	v_and_b32_e32 v15, 0xffff0000, v76
	v_lshlrev_b32_e32 v10, 16, v74
	v_and_b32_e32 v11, 0xffff0000, v74
	v_lshlrev_b32_e32 v16, 16, v77
	v_and_b32_e32 v17, 0xffff0000, v77
	v_lshlrev_b32_e32 v12, 16, v75
	v_and_b32_e32 v13, 0xffff0000, v75
	v_sub_f32_e32 v11, v11, v180
	v_sub_f32_e32 v10, v10, v180
	v_sub_f32_e32 v15, v15, v180
	v_sub_f32_e32 v14, v14, v180
	v_sub_f32_e32 v17, v17, v180
	v_sub_f32_e32 v16, v16, v180
	v_sub_f32_e32 v13, v13, v180
	v_sub_f32_e32 v12, v12, v180
	v_pk_mul_f32 v[10:11], v[180:181], v[10:11] op_sel:[1,0]
	v_pk_mul_f32 v[16:17], v[180:181], v[16:17] op_sel:[1,0]
	v_pk_mul_f32 v[14:15], v[180:181], v[14:15] op_sel:[1,0]
	v_pk_mul_f32 v[12:13], v[180:181], v[12:13] op_sel:[1,0]
	v_pk_mul_f32 v[10:11], v[70:71], v[10:11]
	v_pk_mul_f32 v[14:15], v[66:67], v[14:15]
	v_pk_mul_f32 v[16:17], v[68:69], v[16:17]
	v_pk_mul_f32 v[2:3], v[2:3], v[20:21]
	v_pk_mul_f32 v[4:5], v[4:5], v[22:23]
	v_pk_mul_f32 v[12:13], v[72:73], v[12:13]
	v_pk_mul_f32 v[6:7], v[6:7], v[10:11]
	v_pk_mul_f32 v[10:11], v[4:5], v[16:17]
	v_pk_mul_f32 v[4:5], v[2:3], v[14:15]
	v_pk_mul_f32 v[8:9], v[8:9], v[12:13]
	v_cvt_pk_bf16_f32 v2, v6, v7
	v_cvt_pk_bf16_f32 v4, v4, v5
	v_cvt_pk_bf16_f32 v5, v10, v11
	s_nop 0
	v_cvt_pk_bf16_f32 v3, v8, v9
	global_store_dwordx4 v[18:19], v[2:5], off offset:256
	s_and_b64 vcc, exec, s[2:3]
	s_mov_b32 s12, s8
	s_mov_b32 s52, s64
	s_mov_b64 s[16:17], s[4:5]
	s_mov_b64 s[14:15], s[10:11]
	s_cbranch_vccz .LBB0_470
	s_waitcnt vmcnt(0)
	s_cmpk_gt_u32 s1, 0xff
	s_cbranch_scc1 .LBB0_479
	s_barrier

; #define PG8_STAGE(bufoff, gbase, voff) do { _Pragma("unroll") for (int _i = 0; _i < 2; ++_i) \
;         __builtin_amdgcn_global_load_lds((const unsigned*)((const char*)(gbase) + (voff)[_i]), (LAS unsigned*)(lds + (bufoff) + ldsw + _i * 8192), 16, 0, 0); } while (0)
; #define PG8_LDA(dst, b, h) do { _Pragma("unroll") for (int m = 0; m < 4; ++m) _Pragma("unroll") for (int k = 0; k < 2; ++k) dst[m][k] = *(const LAS bf16x8*)(lds + PG8_SA(b, h) + aoff + m * 2048 + k * 1024); } while (0)
; #define PG8_LDB(dst, b, h) do { _Pragma("unroll") for (int n = 0; n < 2; ++n) _Pragma("unroll") for (int k = 0; k < 2; ++k) dst[n][k] = *(const LAS bf16x8*)(lds + PG8_SB(b, h) + boff + n * 2048 + k * 1024); } while (0)
; #define PG8_MMA(ai, bj, At, Bt) do { __builtin_amdgcn_s_setprio(1); _Pragma("unroll") for (int m = 0; m < 4; ++m) _Pragma("unroll") for (int n = 0; n < 2; ++n) _Pragma("unroll") for (int k = 0; k < 2; ++k) \
;         acc[ai][bj][m][n] = __builtin_amdgcn_mfma_f32_16x16x32_bf16(Bt[n][k], At[m][k], acc[ai][bj][m][n], 0, 0, 0); __builtin_amdgcn_s_setprio(0); } while (0)
; #define PG8_WAIT_V(n) asm volatile("s_waitcnt vmcnt(" #n ")" ::: "memory")
; #define PG8_WAIT_L(n) asm volatile("s_waitcnt lgkmcnt(" #n ")" ::: "memory")
; #define PG8_BAR __builtin_amdgcn_s_barrier()
; #define PG8_SCHED __builtin_amdgcn_sched_barrier(0)
; template <class Epi>
; __device__ __forceinline__ void gemm_phase(LAS unsigned char* lds, const Gemm g, const Epi& E) {
;     ...
;             PG8_LDB(B0, 0, 0); PG8_SCHED; PG8_LDA(At, 0, 0); PG8_STAGE(PG8_SA(1, 1), a1 + hstepA, voffA);
;             PG8_WAIT_L(8); PG8_BAR; PG8_WAIT_L(0); PG8_MMA(0, 0, At, B0); PG8_BAR; PG8_SCHED;
;             PG8_LDB(B1, 0, 1); PG8_STAGE(PG8_SB(0, 0), b2, voffB);
;             PG8_BAR; PG8_WAIT_L(0); PG8_MMA(0, 1, At, B1); PG8_BAR;
;             PG8_LDA(At, 0, 1); PG8_STAGE(PG8_SA(0, 0), a2, voffA);
;             PG8_BAR; PG8_WAIT_L(0); PG8_MMA(1, 0, At, B0); PG8_BAR; PG8_SCHED;
;             PG8_STAGE(PG8_SB(0, 1), b2 + hstepB, voffB);
;             PG8_WAIT_V(6); PG8_BAR; PG8_MMA(1, 1, At, B1); PG8_BAR;
.LBB0_495:
	s_add_u32 s14, s12, 0xfff80080
	s_addc_u32 s15, s13, -1
	s_add_i32 s66, 0, 0x10000
	v_add_u32_e32 v142, s66, v159
	ds_read_b128 v[130:133], v142
	ds_read_b128 v[134:137], v142 offset:1024
	ds_read_b128 v[138:141], v142 offset:2048
	ds_read_b128 v[142:145], v142 offset:3072
	s_cmp_eq_u32 s65, 28
	s_cselect_b32 s17, s9, s15
	s_cselect_b32 s16, s8, s14
	s_cselect_b32 s15, s5, s64
	s_cselect_b32 s14, s4, s7
	v_lshl_add_u64 v[192:193], s[12:13], 0, v[150:151]
	s_add_i32 m0, s11, 0xc000
	ds_read_b128 v[154:157], v160
	ds_read_b128 v[162:165], v160 offset:1024
	ds_read_b128 v[166:169], v160 offset:2048
	ds_read_b128 v[170:173], v160 offset:3072
	ds_read_b128 v[174:177], v160 offset:4096
	ds_read_b128 v[180:183], v160 offset:5120
	ds_read_b128 v[184:187], v160 offset:6144
	ds_read_b128 v[188:191], v160 offset:7168
	global_load_lds_dwordx4 v[192:193], off
	v_lshl_add_u64 v[192:193], s[12:13], 0, v[152:153]
	s_add_i32 m0, s11, 0xe000
	s_nop 0
	global_load_lds_dwordx4 v[192:193], off
	s_waitcnt lgkmcnt(8)
	s_barrier
	s_waitcnt lgkmcnt(0)
	s_setprio 1
	v_mfma_f32_16x16x32_bf16 v[126:129], v[130:133], v[154:157], v[126:129]
	v_mfma_f32_16x16x32_bf16 v[122:125], v[138:141], v[154:157], v[122:125]
	v_mfma_f32_16x16x32_bf16 v[114:117], v[130:133], v[166:169], v[114:117]
	v_mfma_f32_16x16x32_bf16 v[106:109], v[138:141], v[166:169], v[106:109]
	v_mfma_f32_16x16x32_bf16 v[102:105], v[130:133], v[174:177], v[102:105]
	v_mfma_f32_16x16x32_bf16 v[90:93], v[138:141], v[174:177], v[90:93]
	v_mfma_f32_16x16x32_bf16 v[86:89], v[130:133], v[184:187], v[86:89]
	v_mfma_f32_16x16x32_bf16 v[74:77], v[138:141], v[184:187], v[74:77]
	v_mfma_f32_16x16x32_bf16 v[126:129], v[134:137], v[162:165], v[126:129]
	v_mfma_f32_16x16x32_bf16 v[122:125], v[142:145], v[162:165], v[122:125]
	v_mfma_f32_16x16x32_bf16 v[114:117], v[134:137], v[170:173], v[114:117]
	v_mfma_f32_16x16x32_bf16 v[106:109], v[142:145], v[170:173], v[106:109]
	v_mfma_f32_16x16x32_bf16 v[102:105], v[134:137], v[180:183], v[102:105]
	v_mfma_f32_16x16x32_bf16 v[90:93], v[142:145], v[180:183], v[90:93]
	v_mfma_f32_16x16x32_bf16 v[86:89], v[134:137], v[188:191], v[86:89]
	v_mfma_f32_16x16x32_bf16 v[74:77], v[142:145], v[188:191], v[74:77]
	s_setprio 0
	s_barrier
	s_add_i32 s68, 0, 0x14000
	s_add_i32 s66, s66, s25
	v_add_u32_e32 v161, s68, v159
	v_lshl_add_u64 v[208:209], s[14:15], 0, v[148:149]
	s_mov_b32 m0, s66
	ds_read_b128 v[192:195], v161
	ds_read_b128 v[196:199], v161 offset:1024
	ds_read_b128 v[200:203], v161 offset:2048
	ds_read_b128 v[204:207], v161 offset:3072
	global_load_lds_dwordx4 v[208:209], off
	v_lshl_add_u64 v[226:227], s[14:15], 0, v[146:147]
	s_add_i32 m0, s66, 0x2000
	s_nop 0
	global_load_lds_dwordx4 v[226:227], off
	s_barrier
	s_waitcnt lgkmcnt(0)
	s_setprio 1
	v_mfma_f32_16x16x32_bf16 v[118:121], v[192:195], v[154:157], v[118:121]
	v_mfma_f32_16x16x32_bf16 v[110:113], v[200:203], v[154:157], v[110:113]
	v_mfma_f32_16x16x32_bf16 v[98:101], v[192:195], v[166:169], v[98:101]
	v_mfma_f32_16x16x32_bf16 v[94:97], v[200:203], v[166:169], v[94:97]
	v_mfma_f32_16x16x32_bf16 v[82:85], v[192:195], v[174:177], v[82:85]
	v_mfma_f32_16x16x32_bf16 v[78:81], v[200:203], v[174:177], v[78:81]
	v_mfma_f32_16x16x32_bf16 v[70:73], v[192:195], v[184:187], v[70:73]
	v_mfma_f32_16x16x32_bf16 v[66:69], v[200:203], v[184:187], v[66:69]
	v_mfma_f32_16x16x32_bf16 v[118:121], v[196:199], v[162:165], v[118:121]
	v_mfma_f32_16x16x32_bf16 v[110:113], v[204:207], v[162:165], v[110:113]
	v_mfma_f32_16x16x32_bf16 v[98:101], v[196:199], v[170:173], v[98:101]
	v_mfma_f32_16x16x32_bf16 v[94:97], v[204:207], v[170:173], v[94:97]
	v_mfma_f32_16x16x32_bf16 v[82:85], v[196:199], v[180:183], v[82:85]
	v_mfma_f32_16x16x32_bf16 v[78:81], v[204:207], v[180:183], v[78:81]
	v_mfma_f32_16x16x32_bf16 v[70:73], v[196:199], v[188:191], v[70:73]
	v_mfma_f32_16x16x32_bf16 v[66:69], v[204:207], v[188:191], v[66:69]
	s_setprio 0
	s_mov_b32 m0, s11
	v_lshl_add_u64 v[228:229], s[16:17], 0, v[148:149]
	s_barrier
	ds_read_b128 v[154:157], v160 offset:16384
	ds_read_b128 v[162:165], v160 offset:17408
	ds_read_b128 v[166:169], v160 offset:18432
	ds_read_b128 v[170:173], v160 offset:19456
	ds_read_b128 v[174:177], v160 offset:20480
	ds_read_b128 v[180:183], v160 offset:21504
	ds_read_b128 v[184:187], v160 offset:22528
	ds_read_b128 v[188:191], v160 offset:23552
	global_load_lds_dwordx4 v[228:229], off
	v_lshl_add_u64 v[230:231], s[16:17], 0, v[146:147]
	s_mov_b32 m0, s31
	s_nop 0
	global_load_lds_dwordx4 v[230:231], off
	s_barrier
	s_waitcnt lgkmcnt(0)
	s_setprio 1
	v_mfma_f32_16x16x32_bf16 v[62:65], v[130:133], v[154:157], v[62:65]
	v_mfma_f32_16x16x32_bf16 v[58:61], v[138:141], v[154:157], v[58:61]
	v_mfma_f32_16x16x32_bf16 v[54:57], v[130:133], v[166:169], v[54:57]
	v_mfma_f32_16x16x32_bf16 v[42:45], v[138:141], v[166:169], v[42:45]
	v_mfma_f32_16x16x32_bf16 v[38:41], v[130:133], v[174:177], v[38:41]
	v_mfma_f32_16x16x32_bf16 v[26:29], v[138:141], v[174:177], v[26:29]
	v_mfma_f32_16x16x32_bf16 v[22:25], v[130:133], v[184:187], v[22:25]
	v_mfma_f32_16x16x32_bf16 v[10:13], v[138:141], v[184:187], v[10:13]
	v_mfma_f32_16x16x32_bf16 v[62:65], v[134:137], v[162:165], v[62:65]
	v_mfma_f32_16x16x32_bf16 v[58:61], v[142:145], v[162:165], v[58:61]
	v_mfma_f32_16x16x32_bf16 v[54:57], v[134:137], v[170:173], v[54:57]
	v_mfma_f32_16x16x32_bf16 v[42:45], v[142:145], v[170:173], v[42:45]
	v_mfma_f32_16x16x32_bf16 v[38:41], v[134:137], v[180:183], v[38:41]
	v_mfma_f32_16x16x32_bf16 v[26:29], v[142:145], v[180:183], v[26:29]
	v_mfma_f32_16x16x32_bf16 v[22:25], v[134:137], v[188:191], v[22:25]
	v_mfma_f32_16x16x32_bf16 v[10:13], v[142:145], v[188:191], v[10:13]
	s_setprio 0
	s_barrier
; #define PG8_STAGE(bufoff, gbase, voff) do { _Pragma("unroll") for (int _i = 0; _i < 2; ++_i) \
;         __builtin_amdgcn_global_load_lds((const unsigned*)((const char*)(gbase) + (voff)[_i]), (LAS unsigned*)(lds + (bufoff) + ldsw + _i * 8192), 16, 0, 0); } while (0)
; #define PG8_LDA(dst, b, h) do { _Pragma("unroll") for (int m = 0; m < 4; ++m) _Pragma("unroll") for (int k = 0; k < 2; ++k) dst[m][k] = *(const LAS bf16x8*)(lds + PG8_SA(b, h) + aoff + m * 2048 + k * 1024); } while (0)
; #define PG8_LDB(dst, b, h) do { _Pragma("unroll") for (int n = 0; n < 2; ++n) _Pragma("unroll") for (int k = 0; k < 2; ++k) dst[n][k] = *(const LAS bf16x8*)(lds + PG8_SB(b, h) + boff + n * 2048 + k * 1024); } while (0)
; #define PG8_MMA(ai, bj, At, Bt) do { __builtin_amdgcn_s_setprio(1); _Pragma("unroll") for (int m = 0; m < 4; ++m) _Pragma("unroll") for (int n = 0; n < 2; ++n) _Pragma("unroll") for (int k = 0; k < 2; ++k) \
;         acc[ai][bj][m][n] = __builtin_amdgcn_mfma_f32_16x16x32_bf16(Bt[n][k], At[m][k], acc[ai][bj][m][n], 0, 0, 0); __builtin_amdgcn_s_setprio(0); } while (0)
; #define PG8_WAIT_V(n) asm volatile("s_waitcnt vmcnt(" #n ")" ::: "memory")
; #define PG8_WAIT_L(n) asm volatile("s_waitcnt lgkmcnt(" #n ")" ::: "memory")
; #define PG8_BAR __builtin_amdgcn_s_barrier()
; #define PG8_SCHED __builtin_amdgcn_sched_barrier(0)
; template <class Epi>
; __device__ __forceinline__ void gemm_phase(LAS unsigned char* lds, const Gemm g, const Epi& E) {
;     ...
;             PG8_STAGE(PG8_SB(0, 1), b2 + hstepB, voffB);
;             PG8_WAIT_V(6); PG8_BAR; PG8_MMA(1, 1, At, B1); PG8_BAR;
;             PG8_LDB(B0, 1, 0); PG8_SCHED; PG8_LDA(At, 1, 0); PG8_STAGE(PG8_SA(0, 1), a2 + hstepA, voffA);
;             PG8_WAIT_L(8); PG8_BAR; PG8_WAIT_L(0); PG8_MMA(0, 0, At, B0); PG8_BAR; PG8_SCHED;
;             PG8_LDB(B1, 1, 1); PG8_STAGE(PG8_SB(1, 0), b3, voffB);
;             PG8_BAR; PG8_WAIT_L(0); PG8_MMA(0, 1, At, B1); PG8_BAR;
;             PG8_LDA(At, 1, 1); PG8_STAGE(PG8_SA(1, 0), a3, voffA);
;             PG8_BAR; PG8_WAIT_L(0); PG8_MMA(1, 0, At, B0); PG8_BAR; PG8_SCHED;
	s_add_u32 s66, s14, 0x80000
	s_addc_u32 s67, s15, 0
	s_add_i32 s68, s68, s25
	v_lshl_add_u64 v[130:131], s[66:67], 0, v[148:149]
	s_mov_b32 m0, s68
	s_nop 0
	global_load_lds_dwordx4 v[130:131], off
	v_lshl_add_u64 v[130:131], s[66:67], 0, v[146:147]
	s_add_i32 m0, s68, 0x2000
	s_nop 0
	global_load_lds_dwordx4 v[130:131], off
	s_waitcnt vmcnt(6)
	s_barrier
	s_setprio 1
	v_mfma_f32_16x16x32_bf16 v[50:53], v[192:195], v[154:157], v[50:53]
	v_mfma_f32_16x16x32_bf16 v[46:49], v[200:203], v[154:157], v[46:49]
	v_mfma_f32_16x16x32_bf16 v[34:37], v[192:195], v[166:169], v[34:37]
	v_mfma_f32_16x16x32_bf16 v[30:33], v[200:203], v[166:169], v[30:33]
	v_mfma_f32_16x16x32_bf16 v[18:21], v[192:195], v[174:177], v[18:21]
	v_mfma_f32_16x16x32_bf16 v[14:17], v[200:203], v[174:177], v[14:17]
	v_mfma_f32_16x16x32_bf16 v[6:9], v[192:195], v[184:187], v[6:9]
	v_mfma_f32_16x16x32_bf16 v[2:5], v[200:203], v[184:187], v[2:5]
	v_mfma_f32_16x16x32_bf16 v[50:53], v[196:199], v[162:165], v[50:53]
	v_mfma_f32_16x16x32_bf16 v[46:49], v[204:207], v[162:165], v[46:49]
	v_mfma_f32_16x16x32_bf16 v[34:37], v[196:199], v[170:173], v[34:37]
	v_mfma_f32_16x16x32_bf16 v[30:33], v[204:207], v[170:173], v[30:33]
	v_mfma_f32_16x16x32_bf16 v[18:21], v[196:199], v[180:183], v[18:21]
	v_mfma_f32_16x16x32_bf16 v[14:17], v[204:207], v[180:183], v[14:17]
	v_mfma_f32_16x16x32_bf16 v[6:9], v[196:199], v[188:191], v[6:9]
	v_mfma_f32_16x16x32_bf16 v[2:5], v[204:207], v[188:191], v[2:5]
	s_setprio 0
	s_add_i32 s66, 0, 0x18000
	v_add_u32_e32 v142, s66, v159
	s_barrier
	ds_read_b128 v[130:133], v142
	ds_read_b128 v[134:137], v142 offset:1024
	ds_read_b128 v[138:141], v142 offset:2048
	ds_read_b128 v[142:145], v142 offset:3072
	s_add_u32 s16, s16, 0x80000
	s_addc_u32 s17, s17, 0
	s_mov_b32 m0, s36
	v_lshl_add_u64 v[192:193], s[16:17], 0, v[148:149]
	ds_read_b128 v[154:157], v160 offset:32768
	ds_read_b128 v[162:165], v160 offset:33792
	ds_read_b128 v[166:169], v160 offset:34816
	ds_read_b128 v[170:173], v160 offset:35840
	ds_read_b128 v[174:177], v160 offset:36864
	ds_read_b128 v[180:183], v160 offset:37888
	ds_read_b128 v[184:187], v160 offset:38912
	ds_read_b128 v[188:191], v160 offset:39936
	global_load_lds_dwordx4 v[192:193], off
	v_lshl_add_u64 v[192:193], s[16:17], 0, v[146:147]
	s_mov_b32 m0, s44
	s_nop 0
	global_load_lds_dwordx4 v[192:193], off
	s_waitcnt lgkmcnt(8)
	s_barrier
	s_waitcnt lgkmcnt(0)
	s_setprio 1
	v_mfma_f32_16x16x32_bf16 v[126:129], v[130:133], v[154:157], v[126:129]
	v_mfma_f32_16x16x32_bf16 v[122:125], v[138:141], v[154:157], v[122:125]
	v_mfma_f32_16x16x32_bf16 v[114:117], v[130:133], v[166:169], v[114:117]
	v_mfma_f32_16x16x32_bf16 v[106:109], v[138:141], v[166:169], v[106:109]
	v_mfma_f32_16x16x32_bf16 v[102:105], v[130:133], v[174:177], v[102:105]
	v_mfma_f32_16x16x32_bf16 v[90:93], v[138:141], v[174:177], v[90:93]
	v_mfma_f32_16x16x32_bf16 v[86:89], v[130:133], v[184:187], v[86:89]
	v_mfma_f32_16x16x32_bf16 v[74:77], v[138:141], v[184:187], v[74:77]
	v_mfma_f32_16x16x32_bf16 v[126:129], v[134:137], v[162:165], v[126:129]
	v_mfma_f32_16x16x32_bf16 v[122:125], v[142:145], v[162:165], v[122:125]
	v_mfma_f32_16x16x32_bf16 v[114:117], v[134:137], v[170:173], v[114:117]
	v_mfma_f32_16x16x32_bf16 v[106:109], v[142:145], v[170:173], v[106:109]
	v_mfma_f32_16x16x32_bf16 v[102:105], v[134:137], v[180:183], v[102:105]
	v_mfma_f32_16x16x32_bf16 v[90:93], v[142:145], v[180:183], v[90:93]
	v_mfma_f32_16x16x32_bf16 v[86:89], v[134:137], v[188:191], v[86:89]
	v_mfma_f32_16x16x32_bf16 v[74:77], v[142:145], v[188:191], v[74:77]
	s_setprio 0
	s_barrier
	s_add_i32 s16, 0, 0x1c000
	s_add_i32 s17, s66, s25
	v_add_u32_e32 v161, s16, v159
	v_lshl_add_u64 v[208:209], v[208:209], 0, s[86:87]
	s_mov_b32 m0, s17
	ds_read_b128 v[192:195], v161
	ds_read_b128 v[196:199], v161 offset:1024
	ds_read_b128 v[200:203], v161 offset:2048
	ds_read_b128 v[204:207], v161 offset:3072
	global_load_lds_dwordx4 v[208:209], off
	v_lshl_add_u64 v[208:209], v[226:227], 0, s[86:87]
	s_add_i32 m0, s17, 0x2000
	s_nop 0
	global_load_lds_dwordx4 v[208:209], off
	s_barrier
	s_waitcnt lgkmcnt(0)
	s_setprio 1
	v_mfma_f32_16x16x32_bf16 v[118:121], v[192:195], v[154:157], v[118:121]
	v_mfma_f32_16x16x32_bf16 v[110:113], v[200:203], v[154:157], v[110:113]
	v_mfma_f32_16x16x32_bf16 v[98:101], v[192:195], v[166:169], v[98:101]
	v_mfma_f32_16x16x32_bf16 v[94:97], v[200:203], v[166:169], v[94:97]
	v_mfma_f32_16x16x32_bf16 v[82:85], v[192:195], v[174:177], v[82:85]
	v_mfma_f32_16x16x32_bf16 v[78:81], v[200:203], v[174:177], v[78:81]
	v_mfma_f32_16x16x32_bf16 v[70:73], v[192:195], v[184:187], v[70:73]
	v_mfma_f32_16x16x32_bf16 v[66:69], v[200:203], v[184:187], v[66:69]
	v_mfma_f32_16x16x32_bf16 v[118:121], v[196:199], v[162:165], v[118:121]
	v_mfma_f32_16x16x32_bf16 v[110:113], v[204:207], v[162:165], v[110:113]
	v_mfma_f32_16x16x32_bf16 v[98:101], v[196:199], v[170:173], v[98:101]
	v_mfma_f32_16x16x32_bf16 v[94:97], v[204:207], v[170:173], v[94:97]
	v_mfma_f32_16x16x32_bf16 v[82:85], v[196:199], v[180:183], v[82:85]
	v_mfma_f32_16x16x32_bf16 v[78:81], v[204:207], v[180:183], v[78:81]
	v_mfma_f32_16x16x32_bf16 v[70:73], v[196:199], v[188:191], v[70:73]
	v_mfma_f32_16x16x32_bf16 v[66:69], v[204:207], v[188:191], v[66:69]
	s_setprio 0
	s_mov_b32 m0, s53
	v_lshl_add_u64 v[208:209], v[228:229], 0, s[86:87]
	s_barrier
	ds_read_b128 v[154:157], v160 offset:49152
	ds_read_b128 v[162:165], v160 offset:50176
	ds_read_b128 v[166:169], v160 offset:51200
	ds_read_b128 v[170:173], v160 offset:52224
	ds_read_b128 v[174:177], v160 offset:53248
	ds_read_b128 v[180:183], v160 offset:54272
	ds_read_b128 v[184:187], v160 offset:55296
	ds_read_b128 v[188:191], v160 offset:56320
	global_load_lds_dwordx4 v[208:209], off
	v_lshl_add_u64 v[208:209], v[230:231], 0, s[86:87]
	s_mov_b32 m0, s58
	s_nop 0
	global_load_lds_dwordx4 v[208:209], off
	s_barrier
; #define PG8_STAGE(bufoff, gbase, voff) do { _Pragma("unroll") for (int _i = 0; _i < 2; ++_i) \
;         __builtin_amdgcn_global_load_lds((const unsigned*)((const char*)(gbase) + (voff)[_i]), (LAS unsigned*)(lds + (bufoff) + ldsw + _i * 8192), 16, 0, 0); } while (0)
; #define PG8_MMA(ai, bj, At, Bt) do { __builtin_amdgcn_s_setprio(1); _Pragma("unroll") for (int m = 0; m < 4; ++m) _Pragma("unroll") for (int n = 0; n < 2; ++n) _Pragma("unroll") for (int k = 0; k < 2; ++k) \
;         acc[ai][bj][m][n] = __builtin_amdgcn_mfma_f32_16x16x32_bf16(Bt[n][k], At[m][k], acc[ai][bj][m][n], 0, 0, 0); __builtin_amdgcn_s_setprio(0); } while (0)
; #define PG8_WAIT_V(n) asm volatile("s_waitcnt vmcnt(" #n ")" ::: "memory")
; #define PG8_WAIT_L(n) asm volatile("s_waitcnt lgkmcnt(" #n ")" ::: "memory")
; #define PG8_BAR __builtin_amdgcn_s_barrier()
; template <class Epi>
; __device__ __forceinline__ void gemm_phase(LAS unsigned char* lds, const Gemm g, const Epi& E) {
;     ...
;             PG8_BAR; PG8_WAIT_L(0); PG8_MMA(1, 0, At, B0); PG8_BAR; PG8_SCHED;
;             PG8_STAGE(PG8_SB(1, 1), b3 + hstepB, voffB);
;             PG8_WAIT_V(6); PG8_BAR; PG8_MMA(1, 1, At, B1); PG8_BAR;
;         }
;     __device__ __forceinline__ void operator()(const AccT& acc, const Unit& u, int wr, int wc, int fr, int fq) const {
;         asm volatile("" : "+v"(fr), "+v"(fq));
;         const int gpm = mapA.src(u.pm);
;         const int mb = gpm < 32 ? 32 : (gpm - 32) >> 3;
;         const int row0 = gpm * 256 + wr * 64 + fr, col0 = u.pn * 256 + wc * 32 + 4 * fq;
;         const float* gp = modl + ((size_t)mb * 6 + gi) * 1024;
;         f32x4 gv[2][2];
; #pragma unroll
;         for (int bj = 0; bj < 2; ++bj)
; #pragma unroll
;             for (int n = 0; n < 2; ++n) { gv[bj][n] = *(const f32x4*)(gp + col0 + bj * 128 + n * 16); if (scale) gv[bj][n] = gv[bj][n] * *(const f32x4*)(scale + col0 + bj * 128 + n * 16); }
;         const float* sbase = (gpm < 32 ? Xc : Xl) + (size_t)row0 * 1024 + col0;
; #pragma unroll
;         for (int ai = 0; ai < 2; ++ai) {
;             f32x4 xo[4][2][2];
; #pragma unroll
;             for (int m = 0; m < 4; ++m)
; #pragma unroll
;                 for (int bj = 0; bj < 2; ++bj)
; #pragma unroll
;                     for (int n = 0; n < 2; ++n) xo[m][bj][n] = *(const f32x4*)(sbase + (size_t)(ai * 128 + m * 16) * 1024 + bj * 128 + n * 16);
	s_waitcnt lgkmcnt(0)
	s_setprio 1
	v_mfma_f32_16x16x32_bf16 v[62:65], v[130:133], v[154:157], v[62:65]
	v_mfma_f32_16x16x32_bf16 v[58:61], v[138:141], v[154:157], v[58:61]
	v_mfma_f32_16x16x32_bf16 v[54:57], v[130:133], v[166:169], v[54:57]
	v_mfma_f32_16x16x32_bf16 v[42:45], v[138:141], v[166:169], v[42:45]
	v_mfma_f32_16x16x32_bf16 v[38:41], v[130:133], v[174:177], v[38:41]
	v_mfma_f32_16x16x32_bf16 v[26:29], v[138:141], v[174:177], v[26:29]
	v_mfma_f32_16x16x32_bf16 v[22:25], v[130:133], v[184:187], v[22:25]
	v_mfma_f32_16x16x32_bf16 v[10:13], v[138:141], v[184:187], v[10:13]
	v_mfma_f32_16x16x32_bf16 v[62:65], v[134:137], v[162:165], v[62:65]
	v_mfma_f32_16x16x32_bf16 v[58:61], v[142:145], v[162:165], v[58:61]
	v_mfma_f32_16x16x32_bf16 v[54:57], v[134:137], v[170:173], v[54:57]
	v_mfma_f32_16x16x32_bf16 v[42:45], v[142:145], v[170:173], v[42:45]
	v_mfma_f32_16x16x32_bf16 v[38:41], v[134:137], v[180:183], v[38:41]
	v_mfma_f32_16x16x32_bf16 v[26:29], v[142:145], v[180:183], v[26:29]
	v_mfma_f32_16x16x32_bf16 v[22:25], v[134:137], v[188:191], v[22:25]
	v_mfma_f32_16x16x32_bf16 v[10:13], v[142:145], v[188:191], v[10:13]
	s_setprio 0
	s_barrier
	s_add_u32 s14, s14, 0x80080
	s_addc_u32 s15, s15, 0
	s_add_i32 s16, s16, s25
	v_lshl_add_u64 v[130:131], s[14:15], 0, v[148:149]
	s_mov_b32 m0, s16
	s_nop 0
	global_load_lds_dwordx4 v[130:131], off
	v_lshl_add_u64 v[130:131], s[14:15], 0, v[146:147]
	s_add_i32 m0, s16, 0x2000
	s_nop 0
	global_load_lds_dwordx4 v[130:131], off
	s_waitcnt vmcnt(6)
	s_barrier
	s_setprio 1
	v_mfma_f32_16x16x32_bf16 v[50:53], v[192:195], v[154:157], v[50:53]
	v_mfma_f32_16x16x32_bf16 v[46:49], v[200:203], v[154:157], v[46:49]
	v_mfma_f32_16x16x32_bf16 v[34:37], v[192:195], v[166:169], v[34:37]
	v_mfma_f32_16x16x32_bf16 v[30:33], v[200:203], v[166:169], v[30:33]
	v_mfma_f32_16x16x32_bf16 v[18:21], v[192:195], v[174:177], v[18:21]
	v_mfma_f32_16x16x32_bf16 v[14:17], v[200:203], v[174:177], v[14:17]
	v_mfma_f32_16x16x32_bf16 v[6:9], v[192:195], v[184:187], v[6:9]
	v_mfma_f32_16x16x32_bf16 v[2:5], v[200:203], v[184:187], v[2:5]
	v_mfma_f32_16x16x32_bf16 v[50:53], v[196:199], v[162:165], v[50:53]
	v_mfma_f32_16x16x32_bf16 v[46:49], v[204:207], v[162:165], v[46:49]
	v_mfma_f32_16x16x32_bf16 v[34:37], v[196:199], v[170:173], v[34:37]
	v_mfma_f32_16x16x32_bf16 v[30:33], v[204:207], v[170:173], v[30:33]
	v_mfma_f32_16x16x32_bf16 v[18:21], v[196:199], v[180:183], v[18:21]
	v_mfma_f32_16x16x32_bf16 v[14:17], v[204:207], v[180:183], v[14:17]
	v_mfma_f32_16x16x32_bf16 v[6:9], v[196:199], v[188:191], v[6:9]
	v_mfma_f32_16x16x32_bf16 v[2:5], v[204:207], v[188:191], v[2:5]
	s_setprio 0
	s_add_i32 s65, s65, 2
	s_add_u32 s12, s12, 0x100
	s_addc_u32 s13, s13, 0
	s_add_u32 s7, s7, 0x100
	s_addc_u32 s64, s64, 0
	s_cmp_gt_u32 s65, 29
	s_barrier
	s_cbranch_scc0 .LBB0_495
	v_readlane_b32 s7, v255, 27
	s_cmp_ge_i32 s61, s7
	s_cselect_b32 s7, s29, 0
	s_add_i32 s7, s61, s7
	s_cmp_lt_i32 s7, 32
	v_mov_b32_e32 v156, v158
	v_mov_b32_e32 v130, v1
	s_cselect_b64 s[12:13], -1, 0
	s_sub_i32 s14, s7, 32
	s_lshl_b32 s10, s10, 8
	s_ashr_i32 s14, s14, 3
	s_or_b32 s10, s10, s52
	v_lshl_add_u32 v130, v130, 2, s10
	s_mul_i32 s10, s14, 6
	s_and_b64 s[14:15], s[12:13], exec
	s_cselect_b32 s14, 0xc0, s10
	s_ashr_i32 s15, s14, 31
	s_lshl_b64 s[14:15], s[14:15], 12
	s_add_u32 s14, s88, s14
	s_addc_u32 s15, s89, s15
	s_lshl_b32 s7, s7, 8
	s_add_i32 s7, s7, s50
	v_ashrrev_i32_e32 v131, 31, v130
	v_add_u32_e32 v156, s7, v156
	s_and_b64 s[12:13], s[12:13], exec
	v_readlane_b32 s7, v255, 16
	v_readlane_b32 s10, v255, 18
	v_lshlrev_b64 v[154:155], 2, v[130:131]
	s_cselect_b32 s13, s7, s10
	v_readlane_b32 s7, v255, 17
	v_readlane_b32 s10, v255, 19
	v_ashrrev_i32_e32 v157, 31, v156
	v_lshl_add_u64 v[130:131], s[14:15], 0, v[154:155]
	s_mov_b64 s[14:15], 0x2000
	s_cselect_b32 s12, s7, s10
	v_lshlrev_b64 v[208:209], 12, v[156:157]
	v_lshl_add_u64 v[132:133], v[130:131], 0, s[14:15]
	v_add_co_u32_e32 v130, vcc, s71, v130
	v_lshl_add_u64 v[156:157], s[12:13], 0, v[208:209]
	s_nop 0
	v_addc_co_u32_e32 v131, vcc, 0, v131, vcc
	v_lshl_add_u64 v[156:157], v[156:157], 0, v[154:155]
	v_add_co_u32_e32 v192, vcc, s45, v156
	global_load_dwordx4 v[138:141], v[132:133], off offset:64
	global_load_dwordx4 v[134:137], v[132:133], off offset:512
	global_load_dwordx4 v[142:145], v[130:131], off
	s_nop 0
	global_load_dwordx4 v[130:133], v[132:133], off offset:576
	v_addc_co_u32_e32 v193, vcc, 0, v157, vcc
	v_add_co_u32_e32 v226, vcc, s19, v156
	global_load_dwordx4 v[162:165], v[156:157], off
	global_load_dwordx4 v[166:169], v[156:157], off offset:64
	global_load_dwordx4 v[170:173], v[156:157], off offset:512
	global_load_dwordx4 v[174:177], v[156:157], off offset:576
	v_addc_co_u32_e32 v227, vcc, 0, v157, vcc
	v_add_co_u32_e32 v242, vcc, s69, v156
	global_load_dwordx4 v[180:183], v[192:193], off
	global_load_dwordx4 v[184:187], v[192:193], off offset:64
	global_load_dwordx4 v[188:191], v[192:193], off offset:512
	s_nop 0
	global_load_dwordx4 v[192:195], v[192:193], off offset:576
	v_addc_co_u32_e32 v243, vcc, 0, v157, vcc
	global_load_dwordx4 v[196:199], v[226:227], off
	global_load_dwordx4 v[200:203], v[226:227], off offset:64
	global_load_dwordx4 v[204:207], v[226:227], off offset:512
	s_nop 0
	global_load_dwordx4 v[226:229], v[226:227], off offset:576
	s_nop 0
	global_load_dwordx4 v[230:233], v[242:243], off
	global_load_dwordx4 v[234:237], v[242:243], off offset:64
	global_load_dwordx4 v[238:241], v[242:243], off offset:512
	s_nop 0
	global_load_dwordx4 v[242:245], v[242:243], off offset:576
	v_readlane_b32 s12, v254, 0
	v_readlane_b32 s13, v254, 1
	s_waitcnt vmcnt(0)
;     __device__ __forceinline__ void operator()(const AccT& acc, const Unit& u, int wr, int wc, int fr, int fq) const {
;     ...
; #pragma unroll
;         for (int ai = 0; ai < 2; ++ai) {
;             f32x4 xo[4][2][2];
; #pragma unroll
;             for (int m = 0; m < 4; ++m)
; #pragma unroll
;                 for (int bj = 0; bj < 2; ++bj)
; #pragma unroll
;                     for (int n = 0; n < 2; ++n) xo[m][bj][n] = *(const f32x4*)(sbase + (size_t)(ai * 128 + m * 16) * 1024 + bj * 128 + n * 16);
;             __builtin_amdgcn_sched_barrier(0);
; #pragma unroll
;             for (int m = 0; m < 4; ++m) { float* rowp = X + (size_t)(row0 + ai * 128 + m * 16) * 1024 + col0;
; #pragma unroll
;                 for (int bj = 0; bj < 2; ++bj)
; #pragma unroll
;                     for (int n = 0; n < 2; ++n) *(f32x4*)(rowp + bj * 128 + n * 16) = xo[m][bj][n] + gv[bj][n] * acc[ai][bj][m][n]; }
	v_pk_fma_f32 v[112:113], v[112:113], v[132:133], v[176:177]
	v_pk_fma_f32 v[110:111], v[110:111], v[130:131], v[174:175]
	v_lshl_add_u64 v[208:209], s[12:13], 0, v[208:209]
	v_lshl_add_u64 v[154:155], v[208:209], 0, v[154:155]
	v_pk_fma_f32 v[120:121], v[120:121], v[136:137], v[172:173]
	v_pk_fma_f32 v[118:119], v[118:119], v[134:135], v[170:171]
	global_store_dwordx4 v[154:155], v[110:113], off offset:576
	global_store_dwordx4 v[154:155], v[118:121], off offset:512
	v_pk_fma_f32 v[100:101], v[100:101], v[136:137], v[190:191]
	v_pk_fma_f32 v[110:111], v[114:115], v[142:143], v[180:181]
	v_add_co_u32_e32 v114, vcc, s45, v154
	v_lshl_add_u64 v[118:119], v[154:155], 0, s[84:85]
	s_nop 0
	v_addc_co_u32_e32 v115, vcc, 0, v155, vcc
	v_pk_fma_f32 v[98:99], v[98:99], v[134:135], v[188:189]
	global_store_dwordx4 v[118:119], v[98:101], off offset:512
	v_pk_fma_f32 v[84:85], v[84:85], v[136:137], v[206:207]
	v_pk_fma_f32 v[82:83], v[82:83], v[134:135], v[204:205]
	v_add_co_u32_e32 v100, vcc, s19, v154
	v_lshl_add_u64 v[98:99], v[154:155], 0, s[82:83]
	s_nop 0
	v_addc_co_u32_e32 v101, vcc, 0, v155, vcc
	v_pk_fma_f32 v[96:97], v[96:97], v[132:133], v[194:195]
	v_pk_fma_f32 v[94:95], v[94:95], v[130:131], v[192:193]
	global_store_dwordx4 v[98:99], v[82:85], off offset:512
	v_pk_fma_f32 v[80:81], v[80:81], v[132:133], v[228:229]
	v_pk_fma_f32 v[78:79], v[78:79], v[130:131], v[226:227]
	s_mov_b64 s[12:13], 0x30000
	v_add_co_u32_e32 v84, vcc, s69, v154
	v_pk_fma_f32 v[128:129], v[128:129], v[144:145], v[164:165]
	v_pk_fma_f32 v[126:127], v[126:127], v[142:143], v[162:163]
	v_pk_fma_f32 v[124:125], v[124:125], v[140:141], v[168:169]
	v_pk_fma_f32 v[122:123], v[122:123], v[138:139], v[166:167]
	v_pk_fma_f32 v[112:113], v[116:117], v[144:145], v[182:183]
	v_pk_fma_f32 v[108:109], v[108:109], v[140:141], v[186:187]
	v_pk_fma_f32 v[106:107], v[106:107], v[138:139], v[184:185]
	global_store_dwordx4 v[118:119], v[94:97], off offset:576
	v_pk_fma_f32 v[92:93], v[92:93], v[140:141], v[202:203]
	v_pk_fma_f32 v[90:91], v[90:91], v[138:139], v[200:201]
	v_pk_fma_f32 v[96:97], v[104:105], v[144:145], v[198:199]
	v_pk_fma_f32 v[94:95], v[102:103], v[142:143], v[196:197]
	global_store_dwordx4 v[98:99], v[78:81], off offset:576
	v_lshl_add_u64 v[82:83], v[154:155], 0, s[12:13]
	v_addc_co_u32_e32 v85, vcc, 0, v155, vcc
	v_pk_fma_f32 v[80:81], v[88:89], v[144:145], v[232:233]
	v_pk_fma_f32 v[78:79], v[86:87], v[142:143], v[230:231]
	v_pk_fma_f32 v[76:77], v[76:77], v[140:141], v[236:237]
	v_pk_fma_f32 v[74:75], v[74:75], v[138:139], v[234:235]
	v_pk_fma_f32 v[72:73], v[72:73], v[136:137], v[240:241]
	v_pk_fma_f32 v[70:71], v[70:71], v[134:135], v[238:239]
	v_pk_fma_f32 v[68:69], v[68:69], v[132:133], v[244:245]
	v_pk_fma_f32 v[66:67], v[66:67], v[130:131], v[242:243]
	global_store_dwordx4 v[154:155], v[126:129], off
	global_store_dwordx4 v[154:155], v[122:125], off offset:64
	global_store_dwordx4 v[114:115], v[110:113], off
	global_store_dwordx4 v[118:119], v[106:109], off offset:64
	global_store_dwordx4 v[100:101], v[94:97], off
	global_store_dwordx4 v[98:99], v[90:93], off offset:64
	global_store_dwordx4 v[84:85], v[78:81], off
	global_store_dwordx4 v[82:83], v[74:77], off offset:64
	global_store_dwordx4 v[82:83], v[70:73], off offset:512
	global_store_dwordx4 v[82:83], v[66:69], off offset:576
	s_mov_b32 s7, 0x80000
	v_add_co_u32_e32 v78, vcc, s7, v156
	s_mov_b32 s10, 0x90000
	s_nop 0
	v_addc_co_u32_e32 v79, vcc, 0, v157, vcc
	v_add_co_u32_e32 v94, vcc, s10, v156
	s_mov_b32 s12, 0xa0000
	s_nop 0
	v_addc_co_u32_e32 v95, vcc, 0, v157, vcc
	v_add_co_u32_e32 v110, vcc, s12, v156
	s_mov_b32 s13, 0xb0000
	s_nop 0
	v_addc_co_u32_e32 v111, vcc, 0, v157, vcc
	v_add_co_u32_e32 v126, vcc, s13, v156
	global_load_dwordx4 v[66:69], v[78:79], off
	global_load_dwordx4 v[70:73], v[78:79], off offset:64
	global_load_dwordx4 v[74:77], v[78:79], off offset:512
	s_nop 0
	global_load_dwordx4 v[78:81], v[78:79], off offset:576
	v_addc_co_u32_e32 v127, vcc, 0, v157, vcc
	global_load_dwordx4 v[82:85], v[94:95], off
	global_load_dwordx4 v[86:89], v[94:95], off offset:64
	global_load_dwordx4 v[90:93], v[94:95], off offset:512
	s_nop 0
	global_load_dwordx4 v[94:97], v[94:95], off offset:576
	s_nop 0
	global_load_dwordx4 v[98:101], v[110:111], off
	global_load_dwordx4 v[102:105], v[110:111], off offset:64
	global_load_dwordx4 v[106:109], v[110:111], off offset:512
	s_nop 0
	global_load_dwordx4 v[110:113], v[110:111], off offset:576
	s_nop 0
	global_load_dwordx4 v[114:117], v[126:127], off
	global_load_dwordx4 v[118:121], v[126:127], off offset:64
	global_load_dwordx4 v[122:125], v[126:127], off offset:512
	s_nop 0
	global_load_dwordx4 v[126:129], v[126:127], off offset:576
	s_mov_b64 s[14:15], 0x80000
	s_waitcnt vmcnt(0)
; #define PG8_WAIT_V(n) asm volatile("s_waitcnt vmcnt(" #n ")" ::: "memory")
; #define PG8_BAR __builtin_amdgcn_s_barrier()
; template <class Epi>
; __device__ __forceinline__ void gemm_phase(LAS unsigned char* lds, const Gemm g, const Epi& E) {
;     ...
;         if (!has_next) break;
; #pragma unroll
;         for (int a = 0; a < 2; ++a)
; #pragma unroll
;             for (int b = 0; b < 2; ++b)
; #pragma unroll
;                 for (int m = 0; m < 4; ++m)
; #pragma unroll
;                     for (int n = 0; n < 2; ++n) acc[a][b][m][n] = (f32x4){0.f, 0.f, 0.f, 0.f};
;         cur = nxt; cA = nA; cB = nB; ++ui;
;     }
;     PG8_WAIT_V(0);
;     if (wr == 0) PG8_BAR;
;     PG8_BAR;
;     __device__ __forceinline__ void operator()(const AccT& acc, const Unit& u, int wr, int wc, int fr, int fq) const {
;     ...
;             for (int m = 0; m < 4; ++m) { float* rowp = X + (size_t)(row0 + ai * 128 + m * 16) * 1024 + col0;
; #pragma unroll
;                 for (int bj = 0; bj < 2; ++bj)
; #pragma unroll
;                     for (int n = 0; n < 2; ++n) *(f32x4*)(rowp + bj * 128 + n * 16) = xo[m][bj][n] + gv[bj][n] * acc[ai][bj][m][n]; }
;             __builtin_amdgcn_sched_barrier(0);
	v_pk_fma_f32 v[62:63], v[62:63], v[142:143], v[66:67]
	v_add_co_u32_e32 v66, vcc, s7, v154
	v_lshl_add_u64 v[156:157], v[154:155], 0, s[14:15]
	s_nop 0
	v_addc_co_u32_e32 v67, vcc, 0, v155, vcc
	v_pk_fma_f32 v[52:53], v[52:53], v[136:137], v[76:77]
	v_pk_fma_f32 v[50:51], v[50:51], v[134:135], v[74:75]
	global_store_dwordx4 v[156:157], v[50:53], off offset:512
	s_mov_b64 s[14:15], 0x90000
	v_pk_fma_f32 v[36:37], v[36:37], v[136:137], v[92:93]
	v_add_co_u32_e32 v52, vcc, s10, v154
	v_lshl_add_u64 v[50:51], v[154:155], 0, s[14:15]
	s_nop 0
	v_addc_co_u32_e32 v53, vcc, 0, v155, vcc
	v_pk_fma_f32 v[34:35], v[34:35], v[134:135], v[90:91]
	global_store_dwordx4 v[50:51], v[34:37], off offset:512
	s_mov_b64 s[14:15], 0xa0000
	v_pk_fma_f32 v[20:21], v[20:21], v[136:137], v[108:109]
	v_add_co_u32_e32 v36, vcc, s12, v154
	v_lshl_add_u64 v[34:35], v[154:155], 0, s[14:15]
	s_nop 0
	v_addc_co_u32_e32 v37, vcc, 0, v155, vcc
	v_pk_fma_f32 v[18:19], v[18:19], v[134:135], v[106:107]
	v_pk_fma_f32 v[48:49], v[48:49], v[132:133], v[80:81]
	v_pk_fma_f32 v[46:47], v[46:47], v[130:131], v[78:79]
	v_pk_fma_f32 v[32:33], v[32:33], v[132:133], v[96:97]
	v_pk_fma_f32 v[30:31], v[30:31], v[130:131], v[94:95]
	global_store_dwordx4 v[34:35], v[18:21], off offset:512
	v_pk_fma_f32 v[16:17], v[16:17], v[132:133], v[112:113]
	v_pk_fma_f32 v[14:15], v[14:15], v[130:131], v[110:111]
	s_mov_b64 s[14:15], 0xb0000
	v_add_co_u32_e32 v20, vcc, s13, v154
	v_pk_fma_f32 v[64:65], v[64:65], v[144:145], v[68:69]
	v_pk_fma_f32 v[60:61], v[60:61], v[140:141], v[72:73]
	v_pk_fma_f32 v[58:59], v[58:59], v[138:139], v[70:71]
	global_store_dwordx4 v[156:157], v[46:49], off offset:576
	v_pk_fma_f32 v[44:45], v[44:45], v[140:141], v[88:89]
	v_pk_fma_f32 v[42:43], v[42:43], v[138:139], v[86:87]
	v_pk_fma_f32 v[48:49], v[56:57], v[144:145], v[84:85]
	v_pk_fma_f32 v[46:47], v[54:55], v[142:143], v[82:83]
	global_store_dwordx4 v[50:51], v[30:33], off offset:576
	v_pk_fma_f32 v[28:29], v[28:29], v[140:141], v[104:105]
	v_pk_fma_f32 v[26:27], v[26:27], v[138:139], v[102:103]
	v_pk_fma_f32 v[32:33], v[40:41], v[144:145], v[100:101]
	v_pk_fma_f32 v[30:31], v[38:39], v[142:143], v[98:99]
	global_store_dwordx4 v[34:35], v[14:17], off offset:576
	v_lshl_add_u64 v[18:19], v[154:155], 0, s[14:15]
	v_addc_co_u32_e32 v21, vcc, 0, v155, vcc
	v_pk_fma_f32 v[16:17], v[24:25], v[144:145], v[116:117]
	v_pk_fma_f32 v[14:15], v[22:23], v[142:143], v[114:115]
	v_pk_fma_f32 v[12:13], v[12:13], v[140:141], v[120:121]
	v_pk_fma_f32 v[10:11], v[10:11], v[138:139], v[118:119]
	v_pk_fma_f32 v[8:9], v[8:9], v[136:137], v[124:125]
	v_pk_fma_f32 v[6:7], v[6:7], v[134:135], v[122:123]
	v_pk_fma_f32 v[4:5], v[4:5], v[132:133], v[128:129]
	v_pk_fma_f32 v[2:3], v[2:3], v[130:131], v[126:127]
	global_store_dwordx4 v[66:67], v[62:65], off
	global_store_dwordx4 v[156:157], v[58:61], off offset:64
	global_store_dwordx4 v[52:53], v[46:49], off
	global_store_dwordx4 v[50:51], v[42:45], off offset:64
	global_store_dwordx4 v[36:37], v[30:33], off
	global_store_dwordx4 v[34:35], v[26:29], off offset:64
	global_store_dwordx4 v[20:21], v[14:17], off
	global_store_dwordx4 v[18:19], v[10:13], off offset:64
	global_store_dwordx4 v[18:19], v[6:9], off offset:512
	global_store_dwordx4 v[18:19], v[2:5], off offset:576
	s_and_b64 vcc, exec, s[2:3]
	s_mov_b32 s10, s6
	s_mov_b32 s61, s60
	s_mov_b64 s[14:15], s[4:5]
	s_mov_b64 s[12:13], s[8:9]
	s_cbranch_vccz .LBB0_490
	s_waitcnt vmcnt(0)
	s_cmpk_gt_u32 s1, 0xff
	s_cbranch_scc1 .LBB0_499
	s_barrier

; #define PG8_STAGE(bufoff, gbase, voff) do { _Pragma("unroll") for (int _i = 0; _i < 2; ++_i) \
;         __builtin_amdgcn_global_load_lds((const unsigned*)((const char*)(gbase) + (voff)[_i]), (LAS unsigned*)(lds + (bufoff) + ldsw + _i * 8192), 16, 0, 0); } while (0)
; #define PG8_LDA(dst, b, h) do { _Pragma("unroll") for (int m = 0; m < 4; ++m) _Pragma("unroll") for (int k = 0; k < 2; ++k) dst[m][k] = *(const LAS bf16x8*)(lds + PG8_SA(b, h) + aoff + m * 2048 + k * 1024); } while (0)
; #define PG8_LDB(dst, b, h) do { _Pragma("unroll") for (int n = 0; n < 2; ++n) _Pragma("unroll") for (int k = 0; k < 2; ++k) dst[n][k] = *(const LAS bf16x8*)(lds + PG8_SB(b, h) + boff + n * 2048 + k * 1024); } while (0)
; #define PG8_MMA(ai, bj, At, Bt) do { __builtin_amdgcn_s_setprio(1); _Pragma("unroll") for (int m = 0; m < 4; ++m) _Pragma("unroll") for (int n = 0; n < 2; ++n) _Pragma("unroll") for (int k = 0; k < 2; ++k) \
;         acc[ai][bj][m][n] = __builtin_amdgcn_mfma_f32_16x16x32_bf16(Bt[n][k], At[m][k], acc[ai][bj][m][n], 0, 0, 0); __builtin_amdgcn_s_setprio(0); } while (0)
; #define PG8_WAIT_L(n) asm volatile("s_waitcnt lgkmcnt(" #n ")" ::: "memory")
; #define PG8_BAR __builtin_amdgcn_s_barrier()
; #define PG8_SCHED __builtin_amdgcn_sched_barrier(0)
; template <class Epi>
; __device__ __forceinline__ void gemm_phase(LAS unsigned char* lds, const Gemm g, const Epi& E) {
;     ...
;         for (int t = 0; t < nt; t += 2) {
;             const bool last = (t == nt - 2);
;             const char* a1 = cA + (size_t)(t + 1) * kstep;
;             const char* a2 = last ? nA : cA + (size_t)(t + 2) * kstep; const char* b2 = last ? nB : cB + (size_t)(t + 2) * kstep;
;             const char* a3 = a2 + kstep; const char* b3 = b2 + kstep;
;             PG8_LDB(B0, 0, 0); PG8_SCHED; PG8_LDA(At, 0, 0); PG8_STAGE(PG8_SA(1, 1), a1 + hstepA, voffA);
;             PG8_WAIT_L(8); PG8_BAR; PG8_WAIT_L(0); PG8_MMA(0, 0, At, B0); PG8_BAR; PG8_SCHED;
;             PG8_LDB(B1, 0, 1); PG8_STAGE(PG8_SB(0, 0), b2, voffB);
;             PG8_BAR; PG8_WAIT_L(0); PG8_MMA(0, 1, At, B1); PG8_BAR;
;             PG8_LDA(At, 0, 1); PG8_STAGE(PG8_SA(0, 0), a2, voffA);
;             PG8_BAR; PG8_WAIT_L(0); PG8_MMA(1, 0, At, B0); PG8_BAR; PG8_SCHED;
.LBB0_525:
	s_add_u32 s14, s12, 0xfffc0080
	s_addc_u32 s15, s13, -1
	s_add_i32 s26, 0, 0x10000
	v_add_u32_e32 v149, s26, v147
	ds_read_b128 v[142:145], v149
	ds_read_b128 v[150:153], v149 offset:1024
	ds_read_b128 v[154:157], v149 offset:2048
	ds_read_b128 v[158:161], v149 offset:3072
	s_cmp_eq_u32 s66, 12
	s_cselect_b32 s17, s9, s15
	s_cselect_b32 s16, s8, s14
	s_cselect_b32 s15, s5, s65
	s_cselect_b32 s14, s4, s7
	v_lshl_add_u64 v[196:197], s[12:13], 0, v[138:139]
	s_add_i32 m0, s11, 0xc000
	ds_read_b128 v[162:165], v148
	ds_read_b128 v[166:169], v148 offset:1024
	ds_read_b128 v[170:173], v148 offset:2048
	ds_read_b128 v[174:177], v148 offset:3072
	ds_read_b128 v[180:183], v148 offset:4096
	ds_read_b128 v[184:187], v148 offset:5120
	ds_read_b128 v[188:191], v148 offset:6144
	ds_read_b128 v[192:195], v148 offset:7168
	global_load_lds_dwordx4 v[196:197], off
	v_lshl_add_u64 v[196:197], s[12:13], 0, v[140:141]
	s_add_i32 m0, s11, 0xe000
	s_nop 0
	global_load_lds_dwordx4 v[196:197], off
	s_waitcnt lgkmcnt(8)
	s_barrier
	s_waitcnt lgkmcnt(0)
	s_setprio 1
	v_mfma_f32_16x16x32_bf16 v[126:129], v[142:145], v[162:165], v[126:129]
	v_mfma_f32_16x16x32_bf16 v[118:121], v[154:157], v[162:165], v[118:121]
	v_mfma_f32_16x16x32_bf16 v[110:113], v[142:145], v[170:173], v[110:113]
	v_mfma_f32_16x16x32_bf16 v[102:105], v[154:157], v[170:173], v[102:105]
	v_mfma_f32_16x16x32_bf16 v[94:97], v[142:145], v[180:183], v[94:97]
	v_mfma_f32_16x16x32_bf16 v[86:89], v[154:157], v[180:183], v[86:89]
	v_mfma_f32_16x16x32_bf16 v[78:81], v[142:145], v[188:191], v[78:81]
	v_mfma_f32_16x16x32_bf16 v[70:73], v[154:157], v[188:191], v[70:73]
	v_mfma_f32_16x16x32_bf16 v[126:129], v[150:153], v[166:169], v[126:129]
	v_mfma_f32_16x16x32_bf16 v[118:121], v[158:161], v[166:169], v[118:121]
	v_mfma_f32_16x16x32_bf16 v[110:113], v[150:153], v[174:177], v[110:113]
	v_mfma_f32_16x16x32_bf16 v[102:105], v[158:161], v[174:177], v[102:105]
	v_mfma_f32_16x16x32_bf16 v[94:97], v[150:153], v[184:187], v[94:97]
	v_mfma_f32_16x16x32_bf16 v[86:89], v[158:161], v[184:187], v[86:89]
	v_mfma_f32_16x16x32_bf16 v[78:81], v[150:153], v[192:195], v[78:81]
	v_mfma_f32_16x16x32_bf16 v[70:73], v[158:161], v[192:195], v[70:73]
	s_setprio 0
	s_barrier
	s_add_i32 s27, 0, 0x14000
	s_add_i32 s26, s26, s25
	v_add_u32_e32 v149, s27, v147
	v_lshl_add_u64 v[208:209], s[14:15], 0, v[134:135]
	s_mov_b32 m0, s26
	ds_read_b128 v[196:199], v149
	ds_read_b128 v[200:203], v149 offset:1024
	ds_read_b128 v[204:207], v149 offset:2048
	ds_read_b128 v[226:229], v149 offset:3072
	global_load_lds_dwordx4 v[208:209], off
	v_lshl_add_u64 v[230:231], s[14:15], 0, v[130:131]
	s_add_i32 m0, s26, 0x2000
	s_nop 0
	global_load_lds_dwordx4 v[230:231], off
	s_barrier
	s_waitcnt lgkmcnt(0)
	s_setprio 1
	v_mfma_f32_16x16x32_bf16 v[122:125], v[196:199], v[162:165], v[122:125]
	v_mfma_f32_16x16x32_bf16 v[114:117], v[204:207], v[162:165], v[114:117]
	v_mfma_f32_16x16x32_bf16 v[106:109], v[196:199], v[170:173], v[106:109]
	v_mfma_f32_16x16x32_bf16 v[98:101], v[204:207], v[170:173], v[98:101]
	v_mfma_f32_16x16x32_bf16 v[90:93], v[196:199], v[180:183], v[90:93]
	v_mfma_f32_16x16x32_bf16 v[82:85], v[204:207], v[180:183], v[82:85]
	v_mfma_f32_16x16x32_bf16 v[74:77], v[196:199], v[188:191], v[74:77]
	v_mfma_f32_16x16x32_bf16 v[66:69], v[204:207], v[188:191], v[66:69]
	v_mfma_f32_16x16x32_bf16 v[122:125], v[200:203], v[166:169], v[122:125]
	v_mfma_f32_16x16x32_bf16 v[114:117], v[226:229], v[166:169], v[114:117]
	v_mfma_f32_16x16x32_bf16 v[106:109], v[200:203], v[174:177], v[106:109]
	v_mfma_f32_16x16x32_bf16 v[98:101], v[226:229], v[174:177], v[98:101]
	v_mfma_f32_16x16x32_bf16 v[90:93], v[200:203], v[184:187], v[90:93]
	v_mfma_f32_16x16x32_bf16 v[82:85], v[226:229], v[184:187], v[82:85]
	v_mfma_f32_16x16x32_bf16 v[74:77], v[200:203], v[192:195], v[74:77]
	v_mfma_f32_16x16x32_bf16 v[66:69], v[226:229], v[192:195], v[66:69]
	s_setprio 0
	s_mov_b32 m0, s11
	v_lshl_add_u64 v[232:233], s[16:17], 0, v[136:137]
	s_barrier
	ds_read_b128 v[162:165], v148 offset:16384
	ds_read_b128 v[166:169], v148 offset:17408
	ds_read_b128 v[170:173], v148 offset:18432
	ds_read_b128 v[174:177], v148 offset:19456
	ds_read_b128 v[180:183], v148 offset:20480
	ds_read_b128 v[184:187], v148 offset:21504
	ds_read_b128 v[188:191], v148 offset:22528
	ds_read_b128 v[192:195], v148 offset:23552
	global_load_lds_dwordx4 v[232:233], off
	v_lshl_add_u64 v[234:235], s[16:17], 0, v[132:133]
	s_mov_b32 m0, s36
	s_nop 0
	global_load_lds_dwordx4 v[234:235], off
	s_barrier
	s_waitcnt lgkmcnt(0)
	s_setprio 1
	v_mfma_f32_16x16x32_bf16 v[62:65], v[142:145], v[162:165], v[62:65]
	v_mfma_f32_16x16x32_bf16 v[54:57], v[154:157], v[162:165], v[54:57]
	v_mfma_f32_16x16x32_bf16 v[46:49], v[142:145], v[170:173], v[46:49]
	v_mfma_f32_16x16x32_bf16 v[38:41], v[154:157], v[170:173], v[38:41]
	v_mfma_f32_16x16x32_bf16 v[30:33], v[142:145], v[180:183], v[30:33]
	v_mfma_f32_16x16x32_bf16 v[22:25], v[154:157], v[180:183], v[22:25]
	v_mfma_f32_16x16x32_bf16 v[14:17], v[142:145], v[188:191], v[14:17]
	v_mfma_f32_16x16x32_bf16 v[6:9], v[154:157], v[188:191], v[6:9]
	v_mfma_f32_16x16x32_bf16 v[62:65], v[150:153], v[166:169], v[62:65]
	v_mfma_f32_16x16x32_bf16 v[54:57], v[158:161], v[166:169], v[54:57]
	v_mfma_f32_16x16x32_bf16 v[46:49], v[150:153], v[174:177], v[46:49]
	v_mfma_f32_16x16x32_bf16 v[38:41], v[158:161], v[174:177], v[38:41]
	v_mfma_f32_16x16x32_bf16 v[30:33], v[150:153], v[184:187], v[30:33]
	v_mfma_f32_16x16x32_bf16 v[22:25], v[158:161], v[184:187], v[22:25]
	v_mfma_f32_16x16x32_bf16 v[14:17], v[150:153], v[192:195], v[14:17]
	v_mfma_f32_16x16x32_bf16 v[6:9], v[158:161], v[192:195], v[6:9]
	s_setprio 0
	s_barrier
; #define PG8_STAGE(bufoff, gbase, voff) do { _Pragma("unroll") for (int _i = 0; _i < 2; ++_i) \
;         __builtin_amdgcn_global_load_lds((const unsigned*)((const char*)(gbase) + (voff)[_i]), (LAS unsigned*)(lds + (bufoff) + ldsw + _i * 8192), 16, 0, 0); } while (0)
; #define PG8_LDA(dst, b, h) do { _Pragma("unroll") for (int m = 0; m < 4; ++m) _Pragma("unroll") for (int k = 0; k < 2; ++k) dst[m][k] = *(const LAS bf16x8*)(lds + PG8_SA(b, h) + aoff + m * 2048 + k * 1024); } while (0)
; #define PG8_LDB(dst, b, h) do { _Pragma("unroll") for (int n = 0; n < 2; ++n) _Pragma("unroll") for (int k = 0; k < 2; ++k) dst[n][k] = *(const LAS bf16x8*)(lds + PG8_SB(b, h) + boff + n * 2048 + k * 1024); } while (0)
; #define PG8_MMA(ai, bj, At, Bt) do { __builtin_amdgcn_s_setprio(1); _Pragma("unroll") for (int m = 0; m < 4; ++m) _Pragma("unroll") for (int n = 0; n < 2; ++n) _Pragma("unroll") for (int k = 0; k < 2; ++k) \
;         acc[ai][bj][m][n] = __builtin_amdgcn_mfma_f32_16x16x32_bf16(Bt[n][k], At[m][k], acc[ai][bj][m][n], 0, 0, 0); __builtin_amdgcn_s_setprio(0); } while (0)
; #define PG8_WAIT_V(n) asm volatile("s_waitcnt vmcnt(" #n ")" ::: "memory")
; #define PG8_WAIT_L(n) asm volatile("s_waitcnt lgkmcnt(" #n ")" ::: "memory")
; #define PG8_BAR __builtin_amdgcn_s_barrier()
; #define PG8_SCHED __builtin_amdgcn_sched_barrier(0)
; template <class Epi>
; __device__ __forceinline__ void gemm_phase(LAS unsigned char* lds, const Gemm g, const Epi& E) {
;     ...
;             PG8_STAGE(PG8_SB(0, 1), b2 + hstepB, voffB);
;             PG8_WAIT_V(6); PG8_BAR; PG8_MMA(1, 1, At, B1); PG8_BAR;
;             PG8_LDB(B0, 1, 0); PG8_SCHED; PG8_LDA(At, 1, 0); PG8_STAGE(PG8_SA(0, 1), a2 + hstepA, voffA);
;             PG8_WAIT_L(8); PG8_BAR; PG8_WAIT_L(0); PG8_MMA(0, 0, At, B0); PG8_BAR; PG8_SCHED;
;             PG8_LDB(B1, 1, 1); PG8_STAGE(PG8_SB(1, 0), b3, voffB);
;             PG8_BAR; PG8_WAIT_L(0); PG8_MMA(0, 1, At, B1); PG8_BAR;
;             PG8_LDA(At, 1, 1); PG8_STAGE(PG8_SA(1, 0), a3, voffA);
	s_add_u32 s68, s14, 0x40000
	s_addc_u32 s69, s15, 0
	s_add_i32 s26, s27, s25
	v_lshl_add_u64 v[142:143], s[68:69], 0, v[134:135]
	s_mov_b32 m0, s26
	s_nop 0
	global_load_lds_dwordx4 v[142:143], off
	v_lshl_add_u64 v[142:143], s[68:69], 0, v[130:131]
	s_add_i32 m0, s26, 0x2000
	s_nop 0
	global_load_lds_dwordx4 v[142:143], off
	s_waitcnt vmcnt(6)
	s_barrier
	s_setprio 1
	v_mfma_f32_16x16x32_bf16 v[58:61], v[196:199], v[162:165], v[58:61]
	v_mfma_f32_16x16x32_bf16 v[50:53], v[204:207], v[162:165], v[50:53]
	v_mfma_f32_16x16x32_bf16 v[42:45], v[196:199], v[170:173], v[42:45]
	v_mfma_f32_16x16x32_bf16 v[34:37], v[204:207], v[170:173], v[34:37]
	v_mfma_f32_16x16x32_bf16 v[26:29], v[196:199], v[180:183], v[26:29]
	v_mfma_f32_16x16x32_bf16 v[18:21], v[204:207], v[180:183], v[18:21]
	v_mfma_f32_16x16x32_bf16 v[10:13], v[196:199], v[188:191], v[10:13]
	v_mfma_f32_16x16x32_bf16 v[2:5], v[204:207], v[188:191], v[2:5]
	v_mfma_f32_16x16x32_bf16 v[58:61], v[200:203], v[166:169], v[58:61]
	v_mfma_f32_16x16x32_bf16 v[50:53], v[226:229], v[166:169], v[50:53]
	v_mfma_f32_16x16x32_bf16 v[42:45], v[200:203], v[174:177], v[42:45]
	v_mfma_f32_16x16x32_bf16 v[34:37], v[226:229], v[174:177], v[34:37]
	v_mfma_f32_16x16x32_bf16 v[26:29], v[200:203], v[184:187], v[26:29]
	v_mfma_f32_16x16x32_bf16 v[18:21], v[226:229], v[184:187], v[18:21]
	v_mfma_f32_16x16x32_bf16 v[10:13], v[200:203], v[192:195], v[10:13]
	v_mfma_f32_16x16x32_bf16 v[2:5], v[226:229], v[192:195], v[2:5]
	s_setprio 0
	s_add_i32 s26, 0, 0x18000
	v_add_u32_e32 v149, s26, v147
	s_barrier
	ds_read_b128 v[142:145], v149
	ds_read_b128 v[150:153], v149 offset:1024
	ds_read_b128 v[154:157], v149 offset:2048
	ds_read_b128 v[158:161], v149 offset:3072
	s_add_u32 s16, s16, 0x40000
	s_addc_u32 s17, s17, 0
	s_mov_b32 m0, s44
	v_lshl_add_u64 v[196:197], s[16:17], 0, v[136:137]
	ds_read_b128 v[162:165], v148 offset:32768
	ds_read_b128 v[166:169], v148 offset:33792
	ds_read_b128 v[170:173], v148 offset:34816
	ds_read_b128 v[174:177], v148 offset:35840
	ds_read_b128 v[180:183], v148 offset:36864
	ds_read_b128 v[184:187], v148 offset:37888
	ds_read_b128 v[188:191], v148 offset:38912
	ds_read_b128 v[192:195], v148 offset:39936
	global_load_lds_dwordx4 v[196:197], off
	v_lshl_add_u64 v[196:197], s[16:17], 0, v[132:133]
	s_mov_b32 m0, s50
	s_nop 0
	global_load_lds_dwordx4 v[196:197], off
	s_waitcnt lgkmcnt(8)
	s_barrier
	s_waitcnt lgkmcnt(0)
	s_setprio 1
	v_mfma_f32_16x16x32_bf16 v[126:129], v[142:145], v[162:165], v[126:129]
	v_mfma_f32_16x16x32_bf16 v[118:121], v[154:157], v[162:165], v[118:121]
	v_mfma_f32_16x16x32_bf16 v[110:113], v[142:145], v[170:173], v[110:113]
	v_mfma_f32_16x16x32_bf16 v[102:105], v[154:157], v[170:173], v[102:105]
	v_mfma_f32_16x16x32_bf16 v[94:97], v[142:145], v[180:183], v[94:97]
	v_mfma_f32_16x16x32_bf16 v[86:89], v[154:157], v[180:183], v[86:89]
	v_mfma_f32_16x16x32_bf16 v[78:81], v[142:145], v[188:191], v[78:81]
	v_mfma_f32_16x16x32_bf16 v[70:73], v[154:157], v[188:191], v[70:73]
	v_mfma_f32_16x16x32_bf16 v[126:129], v[150:153], v[166:169], v[126:129]
	v_mfma_f32_16x16x32_bf16 v[118:121], v[158:161], v[166:169], v[118:121]
	v_mfma_f32_16x16x32_bf16 v[110:113], v[150:153], v[174:177], v[110:113]
	v_mfma_f32_16x16x32_bf16 v[102:105], v[158:161], v[174:177], v[102:105]
	v_mfma_f32_16x16x32_bf16 v[94:97], v[150:153], v[184:187], v[94:97]
	v_mfma_f32_16x16x32_bf16 v[86:89], v[158:161], v[184:187], v[86:89]
	v_mfma_f32_16x16x32_bf16 v[78:81], v[150:153], v[192:195], v[78:81]
	v_mfma_f32_16x16x32_bf16 v[70:73], v[158:161], v[192:195], v[70:73]
	s_setprio 0
	s_barrier
	s_add_i32 s16, 0, 0x1c000
	s_add_i32 s17, s26, s25
	v_add_u32_e32 v149, s16, v147
	v_lshl_add_u64 v[208:209], v[208:209], 0, s[86:87]
	s_mov_b32 m0, s17
	ds_read_b128 v[196:199], v149
	ds_read_b128 v[200:203], v149 offset:1024
	ds_read_b128 v[204:207], v149 offset:2048
	ds_read_b128 v[226:229], v149 offset:3072
	global_load_lds_dwordx4 v[208:209], off
	v_lshl_add_u64 v[208:209], v[230:231], 0, s[86:87]
	s_add_i32 m0, s17, 0x2000
	s_nop 0
	global_load_lds_dwordx4 v[208:209], off
	s_barrier
	s_waitcnt lgkmcnt(0)
	s_setprio 1
	v_mfma_f32_16x16x32_bf16 v[122:125], v[196:199], v[162:165], v[122:125]
	v_mfma_f32_16x16x32_bf16 v[114:117], v[204:207], v[162:165], v[114:117]
	v_mfma_f32_16x16x32_bf16 v[106:109], v[196:199], v[170:173], v[106:109]
	v_mfma_f32_16x16x32_bf16 v[98:101], v[204:207], v[170:173], v[98:101]
	v_mfma_f32_16x16x32_bf16 v[90:93], v[196:199], v[180:183], v[90:93]
	v_mfma_f32_16x16x32_bf16 v[82:85], v[204:207], v[180:183], v[82:85]
	v_mfma_f32_16x16x32_bf16 v[74:77], v[196:199], v[188:191], v[74:77]
	v_mfma_f32_16x16x32_bf16 v[66:69], v[204:207], v[188:191], v[66:69]
	v_mfma_f32_16x16x32_bf16 v[122:125], v[200:203], v[166:169], v[122:125]
	v_mfma_f32_16x16x32_bf16 v[114:117], v[226:229], v[166:169], v[114:117]
	v_mfma_f32_16x16x32_bf16 v[106:109], v[200:203], v[174:177], v[106:109]
	v_mfma_f32_16x16x32_bf16 v[98:101], v[226:229], v[174:177], v[98:101]
	v_mfma_f32_16x16x32_bf16 v[90:93], v[200:203], v[184:187], v[90:93]
	v_mfma_f32_16x16x32_bf16 v[82:85], v[226:229], v[184:187], v[82:85]
	v_mfma_f32_16x16x32_bf16 v[74:77], v[200:203], v[192:195], v[74:77]
	v_mfma_f32_16x16x32_bf16 v[66:69], v[226:229], v[192:195], v[66:69]
	s_setprio 0
	s_mov_b32 m0, s58
	v_lshl_add_u64 v[208:209], v[232:233], 0, s[86:87]
	s_barrier
	ds_read_b128 v[162:165], v148 offset:49152
	ds_read_b128 v[166:169], v148 offset:50176
	ds_read_b128 v[170:173], v148 offset:51200
	ds_read_b128 v[174:177], v148 offset:52224
	ds_read_b128 v[180:183], v148 offset:53248
	ds_read_b128 v[184:187], v148 offset:54272
	ds_read_b128 v[188:191], v148 offset:55296
	ds_read_b128 v[192:195], v148 offset:56320
	global_load_lds_dwordx4 v[208:209], off
	v_lshl_add_u64 v[208:209], v[234:235], 0, s[86:87]
	s_mov_b32 m0, s59
	s_nop 0
	global_load_lds_dwordx4 v[208:209], off
	s_barrier
; __device__ __forceinline__ unsigned cvt_pk_bf16(float lo, float hi) { unsigned r; asm("v_cvt_pk_bf16_f32 %0, %1, %2" : "=v"(r) : "v"(lo), "v"(hi)); return r; }
; #define PG8_STAGE(bufoff, gbase, voff) do { _Pragma("unroll") for (int _i = 0; _i < 2; ++_i) \
;         __builtin_amdgcn_global_load_lds((const unsigned*)((const char*)(gbase) + (voff)[_i]), (LAS unsigned*)(lds + (bufoff) + ldsw + _i * 8192), 16, 0, 0); } while (0)
; #define PG8_MMA(ai, bj, At, Bt) do { __builtin_amdgcn_s_setprio(1); _Pragma("unroll") for (int m = 0; m < 4; ++m) _Pragma("unroll") for (int n = 0; n < 2; ++n) _Pragma("unroll") for (int k = 0; k < 2; ++k) \
;         acc[ai][bj][m][n] = __builtin_amdgcn_mfma_f32_16x16x32_bf16(Bt[n][k], At[m][k], acc[ai][bj][m][n], 0, 0, 0); __builtin_amdgcn_s_setprio(0); } while (0)
; #define PG8_WAIT_V(n) asm volatile("s_waitcnt vmcnt(" #n ")" ::: "memory")
; #define PG8_WAIT_L(n) asm volatile("s_waitcnt lgkmcnt(" #n ")" ::: "memory")
; #define PG8_BAR __builtin_amdgcn_s_barrier()
; #define PG8_SCHED __builtin_amdgcn_sched_barrier(0)
; template <class Epi>
; __device__ __forceinline__ void gemm_phase(LAS unsigned char* lds, const Gemm g, const Epi& E) {
;     ...
;             PG8_BAR; PG8_WAIT_L(0); PG8_MMA(1, 0, At, B0); PG8_BAR; PG8_SCHED;
;             PG8_STAGE(PG8_SB(1, 1), b3 + hstepB, voffB);
;             PG8_WAIT_V(6); PG8_BAR; PG8_MMA(1, 1, At, B1); PG8_BAR;
;         }
;     __device__ __forceinline__ void operator()(const AccT& acc, const Unit& u, int wr, int wc, int fr, int fq) const {
;         asm volatile("" : "+v"(fr), "+v"(fq));
;         const int gpm = mapA.src(u.pm);
;         const int row0 = gpm * 256 + wr * 64 + fr, col0 = u.pn * 128 + wc * 32 + 8 * fq;
; #pragma unroll
;         for (int ai = 0; ai < 2; ++ai)
; #pragma unroll
;             for (int m = 0; m < 4; ++m) { bf16_t* rowp = U + (size_t)(row0 + ai * 128 + m * 16) * HID + col0;
;                 const f32x4 s0 = silu4(acc[ai][0][m][0]) * acc[ai][1][m][0], s1 = silu4(acc[ai][0][m][1]) * acc[ai][1][m][1];
;                 u32x4 w; w.x = cvt_pk_bf16(s0[0], s0[1]); w.y = cvt_pk_bf16(s0[2], s0[3]); w.z = cvt_pk_bf16(s1[0], s1[1]); w.w = cvt_pk_bf16(s1[2], s1[3]);
;                 *(u32x4*)rowp = w; }
	s_waitcnt lgkmcnt(0)
	s_setprio 1
	v_mfma_f32_16x16x32_bf16 v[62:65], v[142:145], v[162:165], v[62:65]
	v_mfma_f32_16x16x32_bf16 v[54:57], v[154:157], v[162:165], v[54:57]
	v_mfma_f32_16x16x32_bf16 v[46:49], v[142:145], v[170:173], v[46:49]
	v_mfma_f32_16x16x32_bf16 v[38:41], v[154:157], v[170:173], v[38:41]
	v_mfma_f32_16x16x32_bf16 v[30:33], v[142:145], v[180:183], v[30:33]
	v_mfma_f32_16x16x32_bf16 v[22:25], v[154:157], v[180:183], v[22:25]
	v_mfma_f32_16x16x32_bf16 v[14:17], v[142:145], v[188:191], v[14:17]
	v_mfma_f32_16x16x32_bf16 v[6:9], v[154:157], v[188:191], v[6:9]
	v_mfma_f32_16x16x32_bf16 v[62:65], v[150:153], v[166:169], v[62:65]
	v_mfma_f32_16x16x32_bf16 v[54:57], v[158:161], v[166:169], v[54:57]
	v_mfma_f32_16x16x32_bf16 v[46:49], v[150:153], v[174:177], v[46:49]
	v_mfma_f32_16x16x32_bf16 v[38:41], v[158:161], v[174:177], v[38:41]
	v_mfma_f32_16x16x32_bf16 v[30:33], v[150:153], v[184:187], v[30:33]
	v_mfma_f32_16x16x32_bf16 v[22:25], v[158:161], v[184:187], v[22:25]
	v_mfma_f32_16x16x32_bf16 v[14:17], v[150:153], v[192:195], v[14:17]
	v_mfma_f32_16x16x32_bf16 v[6:9], v[158:161], v[192:195], v[6:9]
	s_setprio 0
	s_barrier
	s_add_u32 s14, s14, 0x40080
	s_addc_u32 s15, s15, 0
	s_add_i32 s16, s16, s25
	v_lshl_add_u64 v[142:143], s[14:15], 0, v[134:135]
	s_mov_b32 m0, s16
	s_nop 0
	global_load_lds_dwordx4 v[142:143], off
	v_lshl_add_u64 v[142:143], s[14:15], 0, v[130:131]
	s_add_i32 m0, s16, 0x2000
	s_nop 0
	global_load_lds_dwordx4 v[142:143], off
	s_waitcnt vmcnt(6)
	s_barrier
	s_setprio 1
	v_mfma_f32_16x16x32_bf16 v[58:61], v[196:199], v[162:165], v[58:61]
	v_mfma_f32_16x16x32_bf16 v[50:53], v[204:207], v[162:165], v[50:53]
	v_mfma_f32_16x16x32_bf16 v[42:45], v[196:199], v[170:173], v[42:45]
	v_mfma_f32_16x16x32_bf16 v[34:37], v[204:207], v[170:173], v[34:37]
	v_mfma_f32_16x16x32_bf16 v[26:29], v[196:199], v[180:183], v[26:29]
	v_mfma_f32_16x16x32_bf16 v[18:21], v[204:207], v[180:183], v[18:21]
	v_mfma_f32_16x16x32_bf16 v[10:13], v[196:199], v[188:191], v[10:13]
	v_mfma_f32_16x16x32_bf16 v[2:5], v[204:207], v[188:191], v[2:5]
	v_mfma_f32_16x16x32_bf16 v[58:61], v[200:203], v[166:169], v[58:61]
	v_mfma_f32_16x16x32_bf16 v[50:53], v[226:229], v[166:169], v[50:53]
	v_mfma_f32_16x16x32_bf16 v[42:45], v[200:203], v[174:177], v[42:45]
	v_mfma_f32_16x16x32_bf16 v[34:37], v[226:229], v[174:177], v[34:37]
	v_mfma_f32_16x16x32_bf16 v[26:29], v[200:203], v[184:187], v[26:29]
	v_mfma_f32_16x16x32_bf16 v[18:21], v[226:229], v[184:187], v[18:21]
	v_mfma_f32_16x16x32_bf16 v[10:13], v[200:203], v[192:195], v[10:13]
	v_mfma_f32_16x16x32_bf16 v[2:5], v[226:229], v[192:195], v[2:5]
	s_setprio 0
	s_add_i32 s66, s66, 2
	s_add_u32 s12, s12, 0x100
	s_addc_u32 s13, s13, 0
	s_add_u32 s7, s7, 0x100
	s_addc_u32 s65, s65, 0
	s_cmp_gt_u32 s66, 13
	s_barrier
	s_cbranch_scc0 .LBB0_525
	v_mul_f32_e32 v152, 0xbfb8aa3b, v126
	v_mul_f32_e32 v153, 0xbfb8aa3b, v127
	v_mul_f32_e32 v154, 0xbfb8aa3b, v128
	v_mul_f32_e32 v155, 0xbfb8aa3b, v129
	v_exp_f32_e32 v152, v152
	v_exp_f32_e32 v153, v153
	v_exp_f32_e32 v154, v154
	v_exp_f32_e32 v155, v155
	v_add_f32_e32 v152, 1.0, v152
	v_add_f32_e32 v153, 1.0, v153
	v_add_f32_e32 v154, 1.0, v154
	v_add_f32_e32 v155, 1.0, v155
	v_rcp_f32_e32 v152, v152
	v_rcp_f32_e32 v153, v153
	v_rcp_f32_e32 v154, v154
	v_rcp_f32_e32 v155, v155
	v_readlane_b32 s7, v255, 27
	v_pk_mul_f32 v[126:127], v[126:127], v[152:153]
	s_cmp_ge_i32 s64, s7
	v_pk_mul_f32 v[128:129], v[128:129], v[154:155]
	v_pk_mul_f32 v[122:123], v[126:127], v[122:123]
	v_pk_mul_f32 v[124:125], v[128:129], v[124:125]
	v_mul_f32_e32 v126, 0xbfb8aa3b, v118
	v_mul_f32_e32 v127, 0xbfb8aa3b, v119
	v_mul_f32_e32 v128, 0xbfb8aa3b, v120
	v_mul_f32_e32 v129, 0xbfb8aa3b, v121
	v_exp_f32_e32 v126, v126
	v_exp_f32_e32 v127, v127
	v_exp_f32_e32 v128, v128
	v_exp_f32_e32 v129, v129
	v_add_f32_e32 v126, 1.0, v126
	v_add_f32_e32 v127, 1.0, v127
	v_add_f32_e32 v128, 1.0, v128
	v_add_f32_e32 v129, 1.0, v129
	s_cselect_b32 s7, s31, 0
	v_rcp_f32_e32 v126, v126
	v_rcp_f32_e32 v127, v127
	v_rcp_f32_e32 v128, v128
	v_rcp_f32_e32 v129, v129
	s_add_i32 s7, s64, s7
	s_lshl_b32 s10, s10, 7
	v_mov_b32_e32 v142, v146
	v_mov_b32_e32 v143, v1
	s_lshl_b32 s7, s7, 8
	s_or_b32 s10, s10, s53
	s_add_i32 s7, s7, s52
	v_lshl_add_u32 v144, v143, 3, s10
	v_add_u32_e32 v149, s7, v142
	v_ashrrev_i32_e32 v145, 31, v144
	v_mov_b64_e32 v[142:143], s[34:35]
	s_movk_i32 s7, 0x1600
	v_pk_mul_f32 v[118:119], v[118:119], v[126:127]
	v_pk_mul_f32 v[120:121], v[120:121], v[128:129]
	v_mad_i64_i32 v[150:151], s[12:13], v149, s7, v[142:143]
	v_lshlrev_b64 v[144:145], 1, v[144:145]
	v_pk_mul_f32 v[120:121], v[120:121], v[116:117]
	v_pk_mul_f32 v[116:117], v[118:119], v[114:115]
	v_lshl_add_u64 v[150:151], v[150:151], 0, v[144:145]
	v_cvt_pk_bf16_f32 v116, v116, v117
	v_cvt_pk_bf16_f32 v117, v120, v121
	v_cvt_pk_bf16_f32 v114, v122, v123
	v_cvt_pk_bf16_f32 v115, v124, v125
	global_store_dwordx4 v[150:151], v[114:117], off
	v_mul_f32_e32 v118, 0xbfb8aa3b, v112
	v_mul_f32_e32 v119, 0xbfb8aa3b, v113
	v_mul_f32_e32 v116, 0xbfb8aa3b, v110
	v_mul_f32_e32 v117, 0xbfb8aa3b, v111
	v_exp_f32_e32 v116, v116
	v_exp_f32_e32 v117, v117
	v_exp_f32_e32 v118, v118
	v_exp_f32_e32 v119, v119
	v_add_f32_e32 v116, 1.0, v116
	v_add_f32_e32 v117, 1.0, v117
	v_add_f32_e32 v118, 1.0, v118
	v_add_f32_e32 v119, 1.0, v119
	v_rcp_f32_e32 v116, v116
	v_rcp_f32_e32 v117, v117
	v_rcp_f32_e32 v118, v118
	v_rcp_f32_e32 v119, v119
	v_add_u32_e32 v114, 16, v149
	v_pk_mul_f32 v[110:111], v[110:111], v[116:117]
	v_mad_i64_i32 v[114:115], s[12:13], v114, s7, v[142:143]
	v_pk_mul_f32 v[112:113], v[112:113], v[118:119]
	v_pk_mul_f32 v[106:107], v[110:111], v[106:107]
; __device__ __forceinline__ unsigned cvt_pk_bf16(float lo, float hi) { unsigned r; asm("v_cvt_pk_bf16_f32 %0, %1, %2" : "=v"(r) : "v"(lo), "v"(hi)); return r; }
;     __device__ __forceinline__ void operator()(const AccT& acc, const Unit& u, int wr, int wc, int fr, int fq) const {
;     ...
;         for (int ai = 0; ai < 2; ++ai)
; #pragma unroll
;             for (int m = 0; m < 4; ++m) { bf16_t* rowp = U + (size_t)(row0 + ai * 128 + m * 16) * HID + col0;
;                 const f32x4 s0 = silu4(acc[ai][0][m][0]) * acc[ai][1][m][0], s1 = silu4(acc[ai][0][m][1]) * acc[ai][1][m][1];
;                 u32x4 w; w.x = cvt_pk_bf16(s0[0], s0[1]); w.y = cvt_pk_bf16(s0[2], s0[3]); w.z = cvt_pk_bf16(s1[0], s1[1]); w.w = cvt_pk_bf16(s1[2], s1[3]);
;                 *(u32x4*)rowp = w; }
	v_pk_mul_f32 v[108:109], v[112:113], v[108:109]
	v_mul_f32_e32 v110, 0xbfb8aa3b, v102
	v_mul_f32_e32 v111, 0xbfb8aa3b, v103
	v_mul_f32_e32 v112, 0xbfb8aa3b, v104
	v_mul_f32_e32 v113, 0xbfb8aa3b, v105
	v_exp_f32_e32 v110, v110
	v_exp_f32_e32 v111, v111
	v_exp_f32_e32 v112, v112
	v_exp_f32_e32 v113, v113
	v_add_f32_e32 v110, 1.0, v110
	v_add_f32_e32 v111, 1.0, v111
	v_add_f32_e32 v112, 1.0, v112
	v_add_f32_e32 v113, 1.0, v113
	v_rcp_f32_e32 v110, v110
	v_rcp_f32_e32 v111, v111
	v_rcp_f32_e32 v112, v112
	v_rcp_f32_e32 v113, v113
	v_lshl_add_u64 v[114:115], v[114:115], 0, v[144:145]
	v_pk_mul_f32 v[102:103], v[102:103], v[110:111]
	s_and_b64 vcc, exec, s[2:3]
	v_pk_mul_f32 v[104:105], v[104:105], v[112:113]
	s_mov_b32 s10, s6
	v_pk_mul_f32 v[104:105], v[104:105], v[100:101]
	v_pk_mul_f32 v[100:101], v[102:103], v[98:99]
	v_cvt_pk_bf16_f32 v98, v106, v107
	v_cvt_pk_bf16_f32 v99, v108, v109
	v_mul_f32_e32 v102, 0xbfb8aa3b, v96
	v_cvt_pk_bf16_f32 v100, v100, v101
	v_cvt_pk_bf16_f32 v101, v104, v105
	global_store_dwordx4 v[114:115], v[98:101], off
	v_mul_f32_e32 v103, 0xbfb8aa3b, v97
	v_exp_f32_e32 v102, v102
	v_mul_f32_e32 v100, 0xbfb8aa3b, v94
	v_mul_f32_e32 v101, 0xbfb8aa3b, v95
	v_exp_f32_e32 v100, v100
	v_exp_f32_e32 v101, v101
	v_exp_f32_e32 v103, v103
	v_add_f32_e32 v102, 1.0, v102
	v_add_f32_e32 v100, 1.0, v100
	v_add_f32_e32 v101, 1.0, v101
	v_add_f32_e32 v103, 1.0, v103
	v_rcp_f32_e32 v100, v100
	v_rcp_f32_e32 v101, v101
	v_rcp_f32_e32 v102, v102
	v_rcp_f32_e32 v103, v103
	v_add_u32_e32 v98, 32, v149
	v_pk_mul_f32 v[94:95], v[94:95], v[100:101]
	v_mad_i64_i32 v[98:99], s[12:13], v98, s7, v[142:143]
	v_pk_mul_f32 v[96:97], v[96:97], v[102:103]
	v_pk_mul_f32 v[90:91], v[94:95], v[90:91]
	v_pk_mul_f32 v[92:93], v[96:97], v[92:93]
	v_mul_f32_e32 v94, 0xbfb8aa3b, v86
	v_mul_f32_e32 v95, 0xbfb8aa3b, v87
	v_mul_f32_e32 v96, 0xbfb8aa3b, v88
	v_mul_f32_e32 v97, 0xbfb8aa3b, v89
	v_exp_f32_e32 v94, v94
	v_exp_f32_e32 v95, v95
	v_exp_f32_e32 v96, v96
	v_exp_f32_e32 v97, v97
	v_add_f32_e32 v94, 1.0, v94
	v_add_f32_e32 v95, 1.0, v95
	v_add_f32_e32 v96, 1.0, v96
	v_add_f32_e32 v97, 1.0, v97
	v_rcp_f32_e32 v94, v94
	v_rcp_f32_e32 v95, v95
	v_rcp_f32_e32 v96, v96
	v_rcp_f32_e32 v97, v97
	v_lshl_add_u64 v[98:99], v[98:99], 0, v[144:145]
	v_pk_mul_f32 v[86:87], v[86:87], v[94:95]
	s_mov_b32 s64, s61
	v_pk_mul_f32 v[88:89], v[88:89], v[96:97]
	s_mov_b64 s[14:15], s[4:5]
	v_pk_mul_f32 v[88:89], v[88:89], v[84:85]
	v_pk_mul_f32 v[84:85], v[86:87], v[82:83]
	v_cvt_pk_bf16_f32 v82, v90, v91
	v_cvt_pk_bf16_f32 v83, v92, v93
	v_mul_f32_e32 v86, 0xbfb8aa3b, v80
	v_cvt_pk_bf16_f32 v84, v84, v85
	v_cvt_pk_bf16_f32 v85, v88, v89
	global_store_dwordx4 v[98:99], v[82:85], off
	v_mul_f32_e32 v87, 0xbfb8aa3b, v81
	v_exp_f32_e32 v86, v86
	v_mul_f32_e32 v84, 0xbfb8aa3b, v78
	v_mul_f32_e32 v85, 0xbfb8aa3b, v79
	v_exp_f32_e32 v84, v84
	v_exp_f32_e32 v85, v85
	v_exp_f32_e32 v87, v87
	v_add_f32_e32 v86, 1.0, v86
	v_add_f32_e32 v84, 1.0, v84
	v_add_f32_e32 v85, 1.0, v85
	v_add_f32_e32 v87, 1.0, v87
	v_rcp_f32_e32 v84, v84
	v_rcp_f32_e32 v85, v85
	v_rcp_f32_e32 v86, v86
	v_rcp_f32_e32 v87, v87
	v_add_u32_e32 v82, 48, v149
	v_pk_mul_f32 v[78:79], v[78:79], v[84:85]
	v_mad_i64_i32 v[82:83], s[12:13], v82, s7, v[142:143]
	v_pk_mul_f32 v[80:81], v[80:81], v[86:87]
	v_pk_mul_f32 v[74:75], v[78:79], v[74:75]
	v_pk_mul_f32 v[76:77], v[80:81], v[76:77]
	v_mul_f32_e32 v78, 0xbfb8aa3b, v70
	v_mul_f32_e32 v79, 0xbfb8aa3b, v71
	v_mul_f32_e32 v80, 0xbfb8aa3b, v72
	v_mul_f32_e32 v81, 0xbfb8aa3b, v73
	v_exp_f32_e32 v78, v78
	v_exp_f32_e32 v79, v79
	v_exp_f32_e32 v80, v80
	v_exp_f32_e32 v81, v81
	v_add_f32_e32 v78, 1.0, v78
	v_add_f32_e32 v79, 1.0, v79
	v_add_f32_e32 v80, 1.0, v80
	v_add_f32_e32 v81, 1.0, v81
	v_rcp_f32_e32 v78, v78
	v_rcp_f32_e32 v79, v79
	v_rcp_f32_e32 v80, v80
	v_rcp_f32_e32 v81, v81
	v_lshl_add_u64 v[82:83], v[82:83], 0, v[144:145]
	v_pk_mul_f32 v[70:71], v[70:71], v[78:79]
	s_mov_b64 s[68:69], 0x1000
	v_pk_mul_f32 v[72:73], v[72:73], v[80:81]
	s_nop 0
	v_pk_mul_f32 v[72:73], v[72:73], v[68:69]
	v_pk_mul_f32 v[68:69], v[70:71], v[66:67]
	v_cvt_pk_bf16_f32 v66, v74, v75
	v_cvt_pk_bf16_f32 v67, v76, v77
	v_mul_f32_e32 v70, 0xbfb8aa3b, v64
	v_cvt_pk_bf16_f32 v68, v68, v69
	v_cvt_pk_bf16_f32 v69, v72, v73
	global_store_dwordx4 v[82:83], v[66:69], off
	v_mul_f32_e32 v71, 0xbfb8aa3b, v65
	v_exp_f32_e32 v70, v70
	v_mul_f32_e32 v68, 0xbfb8aa3b, v62
	v_mul_f32_e32 v69, 0xbfb8aa3b, v63
	v_exp_f32_e32 v68, v68
	v_exp_f32_e32 v69, v69
	v_exp_f32_e32 v71, v71
	v_add_f32_e32 v70, 1.0, v70
	v_add_f32_e32 v68, 1.0, v68
	v_add_f32_e32 v69, 1.0, v69
	v_add_f32_e32 v71, 1.0, v71
	v_rcp_f32_e32 v68, v68
	v_rcp_f32_e32 v69, v69
	v_rcp_f32_e32 v70, v70
	v_rcp_f32_e32 v71, v71
	v_add_u32_e32 v66, 0x80, v149
	v_pk_mul_f32 v[62:63], v[62:63], v[68:69]
	v_mad_i64_i32 v[66:67], s[12:13], v66, s7, v[142:143]
	v_pk_mul_f32 v[64:65], v[64:65], v[70:71]
	v_pk_mul_f32 v[58:59], v[62:63], v[58:59]
	v_pk_mul_f32 v[60:61], v[64:65], v[60:61]
	v_mul_f32_e32 v62, 0xbfb8aa3b, v54
	v_mul_f32_e32 v63, 0xbfb8aa3b, v55
	v_mul_f32_e32 v64, 0xbfb8aa3b, v56
	v_mul_f32_e32 v65, 0xbfb8aa3b, v57
	v_exp_f32_e32 v62, v62
	v_exp_f32_e32 v63, v63
	v_exp_f32_e32 v64, v64
	v_exp_f32_e32 v65, v65
	v_add_f32_e32 v62, 1.0, v62
	v_add_f32_e32 v63, 1.0, v63
	v_add_f32_e32 v64, 1.0, v64
	v_add_f32_e32 v65, 1.0, v65
; __device__ __forceinline__ unsigned cvt_pk_bf16(float lo, float hi) { unsigned r; asm("v_cvt_pk_bf16_f32 %0, %1, %2" : "=v"(r) : "v"(lo), "v"(hi)); return r; }
; #define PG8_WAIT_V(n) asm volatile("s_waitcnt vmcnt(" #n ")" ::: "memory")
; #define PG8_BAR __builtin_amdgcn_s_barrier()
; template <class Epi>
; __device__ __forceinline__ void gemm_phase(LAS unsigned char* lds, const Gemm g, const Epi& E) {
;     ...
;         if (!has_next) break;
; #pragma unroll
;         for (int a = 0; a < 2; ++a)
; #pragma unroll
;             for (int b = 0; b < 2; ++b)
; #pragma unroll
;                 for (int m = 0; m < 4; ++m)
; #pragma unroll
;                     for (int n = 0; n < 2; ++n) acc[a][b][m][n] = (f32x4){0.f, 0.f, 0.f, 0.f};
;         cur = nxt; cA = nA; cB = nB; ++ui;
;     }
;     PG8_WAIT_V(0);
;     if (wr == 0) PG8_BAR;
;     PG8_BAR;
;     __device__ __forceinline__ void operator()(const AccT& acc, const Unit& u, int wr, int wc, int fr, int fq) const {
;     ...
;         for (int ai = 0; ai < 2; ++ai)
; #pragma unroll
;             for (int m = 0; m < 4; ++m) { bf16_t* rowp = U + (size_t)(row0 + ai * 128 + m * 16) * HID + col0;
;                 const f32x4 s0 = silu4(acc[ai][0][m][0]) * acc[ai][1][m][0], s1 = silu4(acc[ai][0][m][1]) * acc[ai][1][m][1];
;                 u32x4 w; w.x = cvt_pk_bf16(s0[0], s0[1]); w.y = cvt_pk_bf16(s0[2], s0[3]); w.z = cvt_pk_bf16(s1[0], s1[1]); w.w = cvt_pk_bf16(s1[2], s1[3]);
;                 *(u32x4*)rowp = w; }
	v_rcp_f32_e32 v62, v62
	v_rcp_f32_e32 v63, v63
	v_rcp_f32_e32 v64, v64
	v_rcp_f32_e32 v65, v65
	v_lshl_add_u64 v[66:67], v[66:67], 0, v[144:145]
	v_pk_mul_f32 v[54:55], v[54:55], v[62:63]
	v_pk_mul_f32 v[56:57], v[56:57], v[64:65]
	s_nop 0
	v_pk_mul_f32 v[56:57], v[56:57], v[52:53]
	v_pk_mul_f32 v[52:53], v[54:55], v[50:51]
	v_cvt_pk_bf16_f32 v50, v58, v59
	v_cvt_pk_bf16_f32 v51, v60, v61
	v_mul_f32_e32 v54, 0xbfb8aa3b, v48
	v_cvt_pk_bf16_f32 v52, v52, v53
	v_cvt_pk_bf16_f32 v53, v56, v57
	global_store_dwordx4 v[66:67], v[50:53], off
	v_mul_f32_e32 v55, 0xbfb8aa3b, v49
	v_exp_f32_e32 v54, v54
	v_mul_f32_e32 v52, 0xbfb8aa3b, v46
	v_mul_f32_e32 v53, 0xbfb8aa3b, v47
	v_exp_f32_e32 v52, v52
	v_exp_f32_e32 v53, v53
	v_exp_f32_e32 v55, v55
	v_add_f32_e32 v54, 1.0, v54
	v_add_f32_e32 v52, 1.0, v52
	v_add_f32_e32 v53, 1.0, v53
	v_add_f32_e32 v55, 1.0, v55
	v_rcp_f32_e32 v52, v52
	v_rcp_f32_e32 v53, v53
	v_rcp_f32_e32 v54, v54
	v_rcp_f32_e32 v55, v55
	v_add_u32_e32 v50, 0x90, v149
	v_pk_mul_f32 v[46:47], v[46:47], v[52:53]
	v_mad_i64_i32 v[50:51], s[12:13], v50, s7, v[142:143]
	v_pk_mul_f32 v[48:49], v[48:49], v[54:55]
	v_pk_mul_f32 v[42:43], v[46:47], v[42:43]
	v_pk_mul_f32 v[44:45], v[48:49], v[44:45]
	v_mul_f32_e32 v46, 0xbfb8aa3b, v38
	v_mul_f32_e32 v47, 0xbfb8aa3b, v39
	v_mul_f32_e32 v48, 0xbfb8aa3b, v40
	v_mul_f32_e32 v49, 0xbfb8aa3b, v41
	v_exp_f32_e32 v46, v46
	v_exp_f32_e32 v47, v47
	v_exp_f32_e32 v48, v48
	v_exp_f32_e32 v49, v49
	v_add_f32_e32 v46, 1.0, v46
	v_add_f32_e32 v47, 1.0, v47
	v_add_f32_e32 v48, 1.0, v48
	v_add_f32_e32 v49, 1.0, v49
	v_rcp_f32_e32 v46, v46
	v_rcp_f32_e32 v47, v47
	v_rcp_f32_e32 v48, v48
	v_rcp_f32_e32 v49, v49
	v_lshl_add_u64 v[50:51], v[50:51], 0, v[144:145]
	v_pk_mul_f32 v[38:39], v[38:39], v[46:47]
	v_pk_mul_f32 v[40:41], v[40:41], v[48:49]
	s_nop 0
	v_pk_mul_f32 v[40:41], v[40:41], v[36:37]
	v_pk_mul_f32 v[36:37], v[38:39], v[34:35]
	v_cvt_pk_bf16_f32 v34, v42, v43
	v_cvt_pk_bf16_f32 v35, v44, v45
	v_mul_f32_e32 v38, 0xbfb8aa3b, v32
	v_cvt_pk_bf16_f32 v36, v36, v37
	v_cvt_pk_bf16_f32 v37, v40, v41
	global_store_dwordx4 v[50:51], v[34:37], off
	v_mul_f32_e32 v39, 0xbfb8aa3b, v33
	v_exp_f32_e32 v38, v38
	v_mul_f32_e32 v36, 0xbfb8aa3b, v30
	v_mul_f32_e32 v37, 0xbfb8aa3b, v31
	v_exp_f32_e32 v36, v36
	v_exp_f32_e32 v37, v37
	v_exp_f32_e32 v39, v39
	v_add_f32_e32 v38, 1.0, v38
	v_add_f32_e32 v36, 1.0, v36
	v_add_f32_e32 v37, 1.0, v37
	v_add_f32_e32 v39, 1.0, v39
	v_rcp_f32_e32 v36, v36
	v_rcp_f32_e32 v37, v37
	v_rcp_f32_e32 v38, v38
	v_rcp_f32_e32 v39, v39
	v_add_u32_e32 v34, 0xa0, v149
	v_pk_mul_f32 v[30:31], v[30:31], v[36:37]
	v_mad_i64_i32 v[34:35], s[12:13], v34, s7, v[142:143]
	v_pk_mul_f32 v[32:33], v[32:33], v[38:39]
	v_pk_mul_f32 v[26:27], v[30:31], v[26:27]
	v_pk_mul_f32 v[28:29], v[32:33], v[28:29]
	v_mul_f32_e32 v30, 0xbfb8aa3b, v22
	v_mul_f32_e32 v31, 0xbfb8aa3b, v23
	v_mul_f32_e32 v32, 0xbfb8aa3b, v24
	v_mul_f32_e32 v33, 0xbfb8aa3b, v25
	v_exp_f32_e32 v30, v30
	v_exp_f32_e32 v31, v31
	v_exp_f32_e32 v32, v32
	v_exp_f32_e32 v33, v33
	v_add_f32_e32 v30, 1.0, v30
	v_add_f32_e32 v31, 1.0, v31
	v_add_f32_e32 v32, 1.0, v32
	v_add_f32_e32 v33, 1.0, v33
	v_rcp_f32_e32 v30, v30
	v_rcp_f32_e32 v31, v31
	v_rcp_f32_e32 v32, v32
	v_rcp_f32_e32 v33, v33
	v_lshl_add_u64 v[34:35], v[34:35], 0, v[144:145]
	v_pk_mul_f32 v[22:23], v[22:23], v[30:31]
	v_pk_mul_f32 v[24:25], v[24:25], v[32:33]
	s_nop 0
	v_pk_mul_f32 v[24:25], v[24:25], v[20:21]
	v_pk_mul_f32 v[20:21], v[22:23], v[18:19]
	v_cvt_pk_bf16_f32 v18, v26, v27
	v_cvt_pk_bf16_f32 v19, v28, v29
	v_mul_f32_e32 v22, 0xbfb8aa3b, v16
	v_cvt_pk_bf16_f32 v20, v20, v21
	v_cvt_pk_bf16_f32 v21, v24, v25
	global_store_dwordx4 v[34:35], v[18:21], off
	v_mul_f32_e32 v23, 0xbfb8aa3b, v17
	v_exp_f32_e32 v22, v22
	v_mul_f32_e32 v20, 0xbfb8aa3b, v14
	v_mul_f32_e32 v21, 0xbfb8aa3b, v15
	v_exp_f32_e32 v20, v20
	v_exp_f32_e32 v21, v21
	v_exp_f32_e32 v23, v23
	v_add_f32_e32 v22, 1.0, v22
	v_add_f32_e32 v20, 1.0, v20
	v_add_f32_e32 v21, 1.0, v21
	v_add_f32_e32 v23, 1.0, v23
	v_rcp_f32_e32 v20, v20
	v_rcp_f32_e32 v21, v21
	v_rcp_f32_e32 v22, v22
	v_rcp_f32_e32 v23, v23
	v_add_u32_e32 v18, 0xb0, v149
	v_pk_mul_f32 v[14:15], v[14:15], v[20:21]
	v_mad_i64_i32 v[18:19], s[12:13], v18, s7, v[142:143]
	v_pk_mul_f32 v[16:17], v[16:17], v[22:23]
	v_pk_mul_f32 v[10:11], v[14:15], v[10:11]
	v_pk_mul_f32 v[12:13], v[16:17], v[12:13]
	v_mul_f32_e32 v14, 0xbfb8aa3b, v6
	v_mul_f32_e32 v15, 0xbfb8aa3b, v7
	v_mul_f32_e32 v16, 0xbfb8aa3b, v8
	v_mul_f32_e32 v17, 0xbfb8aa3b, v9
	v_exp_f32_e32 v14, v14
	v_exp_f32_e32 v15, v15
	v_exp_f32_e32 v16, v16
	v_exp_f32_e32 v17, v17
	v_add_f32_e32 v14, 1.0, v14
	v_add_f32_e32 v15, 1.0, v15
	v_add_f32_e32 v16, 1.0, v16
	v_add_f32_e32 v17, 1.0, v17
	v_rcp_f32_e32 v14, v14
	v_rcp_f32_e32 v15, v15
	v_rcp_f32_e32 v16, v16
	v_rcp_f32_e32 v17, v17
	v_lshl_add_u64 v[18:19], v[18:19], 0, v[144:145]
	v_pk_mul_f32 v[6:7], v[6:7], v[14:15]
	s_mov_b64 s[12:13], s[8:9]
	v_pk_mul_f32 v[8:9], v[8:9], v[16:17]
	s_nop 0
	v_pk_mul_f32 v[8:9], v[8:9], v[4:5]
	v_pk_mul_f32 v[4:5], v[6:7], v[2:3]
	v_cvt_pk_bf16_f32 v2, v10, v11
	v_cvt_pk_bf16_f32 v3, v12, v13
	s_nop 0
	v_cvt_pk_bf16_f32 v4, v4, v5
	v_cvt_pk_bf16_f32 v5, v8, v9
	global_store_dwordx4 v[18:19], v[2:5], off
	s_cbranch_vccz .LBB0_520
	s_waitcnt vmcnt(0)
	s_cmpk_gt_u32 s1, 0xff
	s_cbranch_scc1 .LBB0_529
	s_barrier

; #define PG8_STAGE(bufoff, gbase, voff) do { _Pragma("unroll") for (int _i = 0; _i < 2; ++_i) \
;         __builtin_amdgcn_global_load_lds((const unsigned*)((const char*)(gbase) + (voff)[_i]), (LAS unsigned*)(lds + (bufoff) + ldsw + _i * 8192), 16, 0, 0); } while (0)
; #define PG8_LDA(dst, b, h) do { _Pragma("unroll") for (int m = 0; m < 4; ++m) _Pragma("unroll") for (int k = 0; k < 2; ++k) dst[m][k] = *(const LAS bf16x8*)(lds + PG8_SA(b, h) + aoff + m * 2048 + k * 1024); } while (0)
; #define PG8_LDB(dst, b, h) do { _Pragma("unroll") for (int n = 0; n < 2; ++n) _Pragma("unroll") for (int k = 0; k < 2; ++k) dst[n][k] = *(const LAS bf16x8*)(lds + PG8_SB(b, h) + boff + n * 2048 + k * 1024); } while (0)
; #define PG8_MMA(ai, bj, At, Bt) do { __builtin_amdgcn_s_setprio(1); _Pragma("unroll") for (int m = 0; m < 4; ++m) _Pragma("unroll") for (int n = 0; n < 2; ++n) _Pragma("unroll") for (int k = 0; k < 2; ++k) \
;         acc[ai][bj][m][n] = __builtin_amdgcn_mfma_f32_16x16x32_bf16(Bt[n][k], At[m][k], acc[ai][bj][m][n], 0, 0, 0); __builtin_amdgcn_s_setprio(0); } while (0)
; #define PG8_WAIT_L(n) asm volatile("s_waitcnt lgkmcnt(" #n ")" ::: "memory")
; #define PG8_BAR __builtin_amdgcn_s_barrier()
; #define PG8_SCHED __builtin_amdgcn_sched_barrier(0)
; template <class Epi>
; __device__ __forceinline__ void gemm_phase(LAS unsigned char* lds, const Gemm g, const Epi& E) {
;     ...
;         for (int t = 0; t < nt; t += 2) {
;             const bool last = (t == nt - 2);
;             const char* a1 = cA + (size_t)(t + 1) * kstep;
;             const char* a2 = last ? nA : cA + (size_t)(t + 2) * kstep; const char* b2 = last ? nB : cB + (size_t)(t + 2) * kstep;
;             const char* a3 = a2 + kstep; const char* b3 = b2 + kstep;
;             PG8_LDB(B0, 0, 0); PG8_SCHED; PG8_LDA(At, 0, 0); PG8_STAGE(PG8_SA(1, 1), a1 + hstepA, voffA);
;             PG8_WAIT_L(8); PG8_BAR; PG8_WAIT_L(0); PG8_MMA(0, 0, At, B0); PG8_BAR; PG8_SCHED;
;             PG8_LDB(B1, 0, 1); PG8_STAGE(PG8_SB(0, 0), b2, voffB);
;             PG8_BAR; PG8_WAIT_L(0); PG8_MMA(0, 1, At, B1); PG8_BAR;
;             PG8_LDA(At, 0, 1); PG8_STAGE(PG8_SA(0, 0), a2, voffA);
;             PG8_BAR; PG8_WAIT_L(0); PG8_MMA(1, 0, At, B0); PG8_BAR; PG8_SCHED;
.LBB0_547:
	s_add_u32 s10, s8, 0x100
	s_addc_u32 s11, s9, 0
	s_add_i32 s26, 0, 0x10000
	v_add_u32_e32 v142, s26, v157
	ds_read_b128 v[130:133], v142
	ds_read_b128 v[134:137], v142 offset:1024
	ds_read_b128 v[138:141], v142 offset:2048
	ds_read_b128 v[142:145], v142 offset:3072
	s_cmp_eq_u32 s67, 40
	s_cselect_b32 s15, s5, s11
	s_cselect_b32 s14, s4, s10
	s_cselect_b32 s13, s7, s66
	s_cselect_b32 s12, s6, s65
	v_lshl_add_u64 v[154:155], s[8:9], 0, v[150:151]
	s_add_i32 m0, s29, 0xc000
	ds_read_b128 v[160:163], v158
	ds_read_b128 v[164:167], v158 offset:1024
	ds_read_b128 v[168:171], v158 offset:2048
	ds_read_b128 v[172:175], v158 offset:3072
	ds_read_b128 v[180:183], v158 offset:4096
	ds_read_b128 v[184:187], v158 offset:5120
	ds_read_b128 v[188:191], v158 offset:6144
	ds_read_b128 v[192:195], v158 offset:7168
	global_load_lds_dwordx4 v[154:155], off
	v_lshl_add_u64 v[154:155], s[8:9], 0, v[152:153]
	s_add_i32 m0, s29, 0xe000
	s_nop 0
	global_load_lds_dwordx4 v[154:155], off
	s_waitcnt lgkmcnt(8)
	s_barrier
	s_waitcnt lgkmcnt(0)
	s_setprio 1
	v_mfma_f32_16x16x32_bf16 v[126:129], v[130:133], v[160:163], v[126:129]
	v_mfma_f32_16x16x32_bf16 v[122:125], v[138:141], v[160:163], v[122:125]
	v_mfma_f32_16x16x32_bf16 v[118:121], v[130:133], v[168:171], v[118:121]
	v_mfma_f32_16x16x32_bf16 v[110:113], v[138:141], v[168:171], v[110:113]
	v_mfma_f32_16x16x32_bf16 v[102:105], v[130:133], v[180:183], v[102:105]
	v_mfma_f32_16x16x32_bf16 v[94:97], v[138:141], v[180:183], v[94:97]
	v_mfma_f32_16x16x32_bf16 v[86:89], v[130:133], v[188:191], v[86:89]
	v_mfma_f32_16x16x32_bf16 v[78:81], v[138:141], v[188:191], v[78:81]
	v_mfma_f32_16x16x32_bf16 v[126:129], v[134:137], v[164:167], v[126:129]
	v_mfma_f32_16x16x32_bf16 v[122:125], v[142:145], v[164:167], v[122:125]
	v_mfma_f32_16x16x32_bf16 v[118:121], v[134:137], v[172:175], v[118:121]
	v_mfma_f32_16x16x32_bf16 v[110:113], v[142:145], v[172:175], v[110:113]
	v_mfma_f32_16x16x32_bf16 v[102:105], v[134:137], v[184:187], v[102:105]
	v_mfma_f32_16x16x32_bf16 v[94:97], v[142:145], v[184:187], v[94:97]
	v_mfma_f32_16x16x32_bf16 v[86:89], v[134:137], v[192:195], v[86:89]
	v_mfma_f32_16x16x32_bf16 v[78:81], v[142:145], v[192:195], v[78:81]
	s_setprio 0
	s_barrier
	s_add_i32 s27, 0, 0x14000
	v_add_u32_e32 v154, s27, v157
	s_add_i32 s8, s26, s18
	ds_read_b128 v[196:199], v154
	ds_read_b128 v[200:203], v154 offset:1024
	ds_read_b128 v[204:207], v154 offset:2048
	ds_read_b128 v[226:229], v154 offset:3072
	v_lshl_add_u64 v[154:155], s[12:13], 0, v[148:149]
	s_mov_b32 m0, s8
	v_lshl_add_u64 v[176:177], s[12:13], 0, v[146:147]
	global_load_lds_dwordx4 v[154:155], off
	s_add_i32 m0, s8, 0x2000
	s_nop 0
	global_load_lds_dwordx4 v[176:177], off
	s_barrier
	s_waitcnt lgkmcnt(0)
	s_setprio 1
	v_mfma_f32_16x16x32_bf16 v[114:117], v[196:199], v[160:163], v[114:117]
	v_mfma_f32_16x16x32_bf16 v[106:109], v[204:207], v[160:163], v[106:109]
	v_mfma_f32_16x16x32_bf16 v[98:101], v[196:199], v[168:171], v[98:101]
	v_mfma_f32_16x16x32_bf16 v[90:93], v[204:207], v[168:171], v[90:93]
	v_mfma_f32_16x16x32_bf16 v[82:85], v[196:199], v[180:183], v[82:85]
	v_mfma_f32_16x16x32_bf16 v[74:77], v[204:207], v[180:183], v[74:77]
	v_mfma_f32_16x16x32_bf16 v[70:73], v[196:199], v[188:191], v[70:73]
	v_mfma_f32_16x16x32_bf16 v[66:69], v[204:207], v[188:191], v[66:69]
	v_mfma_f32_16x16x32_bf16 v[114:117], v[200:203], v[164:167], v[114:117]
	v_mfma_f32_16x16x32_bf16 v[106:109], v[226:229], v[164:167], v[106:109]
	v_mfma_f32_16x16x32_bf16 v[98:101], v[200:203], v[172:175], v[98:101]
	v_mfma_f32_16x16x32_bf16 v[90:93], v[226:229], v[172:175], v[90:93]
	v_mfma_f32_16x16x32_bf16 v[82:85], v[200:203], v[184:187], v[82:85]
	v_mfma_f32_16x16x32_bf16 v[74:77], v[226:229], v[184:187], v[74:77]
	v_mfma_f32_16x16x32_bf16 v[70:73], v[200:203], v[192:195], v[70:73]
	v_mfma_f32_16x16x32_bf16 v[66:69], v[226:229], v[192:195], v[66:69]
	s_setprio 0
	s_mov_b32 m0, s29
	v_lshl_add_u64 v[208:209], s[14:15], 0, v[148:149]
	s_barrier
	ds_read_b128 v[160:163], v158 offset:16384
	ds_read_b128 v[164:167], v158 offset:17408
	ds_read_b128 v[168:171], v158 offset:18432
	ds_read_b128 v[172:175], v158 offset:19456
	ds_read_b128 v[180:183], v158 offset:20480
	ds_read_b128 v[184:187], v158 offset:21504
	ds_read_b128 v[188:191], v158 offset:22528
	ds_read_b128 v[192:195], v158 offset:23552
	global_load_lds_dwordx4 v[208:209], off
	v_lshl_add_u64 v[230:231], s[14:15], 0, v[146:147]
	s_mov_b32 m0, s30
	s_nop 0
	global_load_lds_dwordx4 v[230:231], off
	s_barrier
	s_waitcnt lgkmcnt(0)
	s_setprio 1
	v_mfma_f32_16x16x32_bf16 v[62:65], v[130:133], v[160:163], v[62:65]
	v_mfma_f32_16x16x32_bf16 v[58:61], v[138:141], v[160:163], v[58:61]
	v_mfma_f32_16x16x32_bf16 v[54:57], v[130:133], v[168:171], v[54:57]
	v_mfma_f32_16x16x32_bf16 v[46:49], v[138:141], v[168:171], v[46:49]
	v_mfma_f32_16x16x32_bf16 v[38:41], v[130:133], v[180:183], v[38:41]
	v_mfma_f32_16x16x32_bf16 v[30:33], v[138:141], v[180:183], v[30:33]
	v_mfma_f32_16x16x32_bf16 v[22:25], v[130:133], v[188:191], v[22:25]
	v_mfma_f32_16x16x32_bf16 v[14:17], v[138:141], v[188:191], v[14:17]
	v_mfma_f32_16x16x32_bf16 v[62:65], v[134:137], v[164:167], v[62:65]
	v_mfma_f32_16x16x32_bf16 v[58:61], v[142:145], v[164:167], v[58:61]
	v_mfma_f32_16x16x32_bf16 v[54:57], v[134:137], v[172:175], v[54:57]
	v_mfma_f32_16x16x32_bf16 v[46:49], v[142:145], v[172:175], v[46:49]
	v_mfma_f32_16x16x32_bf16 v[38:41], v[134:137], v[184:187], v[38:41]
	v_mfma_f32_16x16x32_bf16 v[30:33], v[142:145], v[184:187], v[30:33]
	v_mfma_f32_16x16x32_bf16 v[22:25], v[134:137], v[192:195], v[22:25]
	v_mfma_f32_16x16x32_bf16 v[14:17], v[142:145], v[192:195], v[14:17]
	s_setprio 0
	s_barrier
; #define PG8_STAGE(bufoff, gbase, voff) do { _Pragma("unroll") for (int _i = 0; _i < 2; ++_i) \
;         __builtin_amdgcn_global_load_lds((const unsigned*)((const char*)(gbase) + (voff)[_i]), (LAS unsigned*)(lds + (bufoff) + ldsw + _i * 8192), 16, 0, 0); } while (0)
; #define PG8_LDA(dst, b, h) do { _Pragma("unroll") for (int m = 0; m < 4; ++m) _Pragma("unroll") for (int k = 0; k < 2; ++k) dst[m][k] = *(const LAS bf16x8*)(lds + PG8_SA(b, h) + aoff + m * 2048 + k * 1024); } while (0)
; #define PG8_LDB(dst, b, h) do { _Pragma("unroll") for (int n = 0; n < 2; ++n) _Pragma("unroll") for (int k = 0; k < 2; ++k) dst[n][k] = *(const LAS bf16x8*)(lds + PG8_SB(b, h) + boff + n * 2048 + k * 1024); } while (0)
; #define PG8_MMA(ai, bj, At, Bt) do { __builtin_amdgcn_s_setprio(1); _Pragma("unroll") for (int m = 0; m < 4; ++m) _Pragma("unroll") for (int n = 0; n < 2; ++n) _Pragma("unroll") for (int k = 0; k < 2; ++k) \
;         acc[ai][bj][m][n] = __builtin_amdgcn_mfma_f32_16x16x32_bf16(Bt[n][k], At[m][k], acc[ai][bj][m][n], 0, 0, 0); __builtin_amdgcn_s_setprio(0); } while (0)
; #define PG8_WAIT_V(n) asm volatile("s_waitcnt vmcnt(" #n ")" ::: "memory")
; #define PG8_WAIT_L(n) asm volatile("s_waitcnt lgkmcnt(" #n ")" ::: "memory")
; #define PG8_BAR __builtin_amdgcn_s_barrier()
; #define PG8_SCHED __builtin_amdgcn_sched_barrier(0)
; template <class Epi>
; __device__ __forceinline__ void gemm_phase(LAS unsigned char* lds, const Gemm g, const Epi& E) {
;     ...
;             PG8_STAGE(PG8_SB(0, 1), b2 + hstepB, voffB);
;             PG8_WAIT_V(6); PG8_BAR; PG8_MMA(1, 1, At, B1); PG8_BAR;
;             PG8_LDB(B0, 1, 0); PG8_SCHED; PG8_LDA(At, 1, 0); PG8_STAGE(PG8_SA(0, 1), a2 + hstepA, voffA);
;             PG8_WAIT_L(8); PG8_BAR; PG8_WAIT_L(0); PG8_MMA(0, 0, At, B0); PG8_BAR; PG8_SCHED;
;             PG8_LDB(B1, 1, 1); PG8_STAGE(PG8_SB(1, 0), b3, voffB);
;             PG8_BAR; PG8_WAIT_L(0); PG8_MMA(0, 1, At, B1); PG8_BAR;
;             PG8_LDA(At, 1, 1); PG8_STAGE(PG8_SA(1, 0), a3, voffA);
	s_add_u32 s8, s12, 0xb0000
	s_addc_u32 s9, s13, 0
	s_add_i32 s26, s27, s18
	v_lshl_add_u64 v[130:131], s[8:9], 0, v[148:149]
	s_mov_b32 m0, s26
	s_nop 0
	global_load_lds_dwordx4 v[130:131], off
	v_lshl_add_u64 v[130:131], s[8:9], 0, v[146:147]
	s_add_i32 m0, s26, 0x2000
	s_nop 0
	global_load_lds_dwordx4 v[130:131], off
	s_waitcnt vmcnt(6)
	s_barrier
	s_setprio 1
	v_mfma_f32_16x16x32_bf16 v[50:53], v[196:199], v[160:163], v[50:53]
	v_mfma_f32_16x16x32_bf16 v[42:45], v[204:207], v[160:163], v[42:45]
	v_mfma_f32_16x16x32_bf16 v[34:37], v[196:199], v[168:171], v[34:37]
	v_mfma_f32_16x16x32_bf16 v[26:29], v[204:207], v[168:171], v[26:29]
	v_mfma_f32_16x16x32_bf16 v[18:21], v[196:199], v[180:183], v[18:21]
	v_mfma_f32_16x16x32_bf16 v[10:13], v[204:207], v[180:183], v[10:13]
	v_mfma_f32_16x16x32_bf16 v[6:9], v[196:199], v[188:191], v[6:9]
	v_mfma_f32_16x16x32_bf16 v[2:5], v[204:207], v[188:191], v[2:5]
	v_mfma_f32_16x16x32_bf16 v[50:53], v[200:203], v[164:167], v[50:53]
	v_mfma_f32_16x16x32_bf16 v[42:45], v[226:229], v[164:167], v[42:45]
	v_mfma_f32_16x16x32_bf16 v[34:37], v[200:203], v[172:175], v[34:37]
	v_mfma_f32_16x16x32_bf16 v[26:29], v[226:229], v[172:175], v[26:29]
	v_mfma_f32_16x16x32_bf16 v[18:21], v[200:203], v[184:187], v[18:21]
	v_mfma_f32_16x16x32_bf16 v[10:13], v[226:229], v[184:187], v[10:13]
	v_mfma_f32_16x16x32_bf16 v[6:9], v[200:203], v[192:195], v[6:9]
	v_mfma_f32_16x16x32_bf16 v[2:5], v[226:229], v[192:195], v[2:5]
	s_setprio 0
	s_add_i32 s26, 0, 0x18000
	v_add_u32_e32 v142, s26, v157
	s_barrier
	ds_read_b128 v[130:133], v142
	ds_read_b128 v[134:137], v142 offset:1024
	ds_read_b128 v[138:141], v142 offset:2048
	ds_read_b128 v[142:145], v142 offset:3072
	s_add_u32 s8, s14, 0xb0000
	s_addc_u32 s9, s15, 0
	s_mov_b32 m0, s31
	v_lshl_add_u64 v[196:197], s[8:9], 0, v[148:149]
	ds_read_b128 v[160:163], v158 offset:32768
	ds_read_b128 v[164:167], v158 offset:33792
	ds_read_b128 v[168:171], v158 offset:34816
	ds_read_b128 v[172:175], v158 offset:35840
	ds_read_b128 v[180:183], v158 offset:36864
	ds_read_b128 v[184:187], v158 offset:37888
	ds_read_b128 v[188:191], v158 offset:38912
	ds_read_b128 v[192:195], v158 offset:39936
	global_load_lds_dwordx4 v[196:197], off
	v_lshl_add_u64 v[196:197], s[8:9], 0, v[146:147]
	s_mov_b32 m0, s36
	s_nop 0
	global_load_lds_dwordx4 v[196:197], off
	s_waitcnt lgkmcnt(8)
	s_barrier
	s_waitcnt lgkmcnt(0)
	s_setprio 1
	v_mfma_f32_16x16x32_bf16 v[126:129], v[130:133], v[160:163], v[126:129]
	v_mfma_f32_16x16x32_bf16 v[122:125], v[138:141], v[160:163], v[122:125]
	v_mfma_f32_16x16x32_bf16 v[118:121], v[130:133], v[168:171], v[118:121]
	v_mfma_f32_16x16x32_bf16 v[110:113], v[138:141], v[168:171], v[110:113]
	v_mfma_f32_16x16x32_bf16 v[102:105], v[130:133], v[180:183], v[102:105]
	v_mfma_f32_16x16x32_bf16 v[94:97], v[138:141], v[180:183], v[94:97]
	v_mfma_f32_16x16x32_bf16 v[86:89], v[130:133], v[188:191], v[86:89]
	v_mfma_f32_16x16x32_bf16 v[78:81], v[138:141], v[188:191], v[78:81]
	v_mfma_f32_16x16x32_bf16 v[126:129], v[134:137], v[164:167], v[126:129]
	v_mfma_f32_16x16x32_bf16 v[122:125], v[142:145], v[164:167], v[122:125]
	v_mfma_f32_16x16x32_bf16 v[118:121], v[134:137], v[172:175], v[118:121]
	v_mfma_f32_16x16x32_bf16 v[110:113], v[142:145], v[172:175], v[110:113]
	v_mfma_f32_16x16x32_bf16 v[102:105], v[134:137], v[184:187], v[102:105]
	v_mfma_f32_16x16x32_bf16 v[94:97], v[142:145], v[184:187], v[94:97]
	v_mfma_f32_16x16x32_bf16 v[86:89], v[134:137], v[192:195], v[86:89]
	v_mfma_f32_16x16x32_bf16 v[78:81], v[142:145], v[192:195], v[78:81]
	s_setprio 0
	s_barrier
	s_add_i32 s14, 0, 0x1c000
	s_add_i32 s8, s26, s18
	v_add_u32_e32 v159, s14, v157
	v_lshl_add_u64 v[154:155], v[154:155], 0, s[86:87]
	s_mov_b32 m0, s8
	ds_read_b128 v[196:199], v159
	ds_read_b128 v[200:203], v159 offset:1024
	ds_read_b128 v[204:207], v159 offset:2048
	ds_read_b128 v[226:229], v159 offset:3072
	global_load_lds_dwordx4 v[154:155], off
	v_lshl_add_u64 v[154:155], v[176:177], 0, s[86:87]
	s_add_i32 m0, s8, 0x2000
	s_nop 0
	global_load_lds_dwordx4 v[154:155], off
	s_barrier
	s_waitcnt lgkmcnt(0)
	s_setprio 1
	v_mfma_f32_16x16x32_bf16 v[114:117], v[196:199], v[160:163], v[114:117]
	v_mfma_f32_16x16x32_bf16 v[106:109], v[204:207], v[160:163], v[106:109]
	v_mfma_f32_16x16x32_bf16 v[98:101], v[196:199], v[168:171], v[98:101]
	v_mfma_f32_16x16x32_bf16 v[90:93], v[204:207], v[168:171], v[90:93]
	v_mfma_f32_16x16x32_bf16 v[82:85], v[196:199], v[180:183], v[82:85]
	v_mfma_f32_16x16x32_bf16 v[74:77], v[204:207], v[180:183], v[74:77]
	v_mfma_f32_16x16x32_bf16 v[70:73], v[196:199], v[188:191], v[70:73]
	v_mfma_f32_16x16x32_bf16 v[66:69], v[204:207], v[188:191], v[66:69]
	v_mfma_f32_16x16x32_bf16 v[114:117], v[200:203], v[164:167], v[114:117]
	v_mfma_f32_16x16x32_bf16 v[106:109], v[226:229], v[164:167], v[106:109]
	v_mfma_f32_16x16x32_bf16 v[98:101], v[200:203], v[172:175], v[98:101]
	v_mfma_f32_16x16x32_bf16 v[90:93], v[226:229], v[172:175], v[90:93]
	v_mfma_f32_16x16x32_bf16 v[82:85], v[200:203], v[184:187], v[82:85]
	v_mfma_f32_16x16x32_bf16 v[74:77], v[226:229], v[184:187], v[74:77]
	v_mfma_f32_16x16x32_bf16 v[70:73], v[200:203], v[192:195], v[70:73]
	v_mfma_f32_16x16x32_bf16 v[66:69], v[226:229], v[192:195], v[66:69]
	s_setprio 0
	s_mov_b32 m0, s52
	v_lshl_add_u64 v[154:155], v[208:209], 0, s[86:87]
	s_barrier
	ds_read_b128 v[160:163], v158 offset:49152
	ds_read_b128 v[164:167], v158 offset:50176
	ds_read_b128 v[168:171], v158 offset:51200
	ds_read_b128 v[172:175], v158 offset:52224
	ds_read_b128 v[180:183], v158 offset:53248
	ds_read_b128 v[184:187], v158 offset:54272
	ds_read_b128 v[188:191], v158 offset:55296
	ds_read_b128 v[192:195], v158 offset:56320
	global_load_lds_dwordx4 v[154:155], off
	v_lshl_add_u64 v[154:155], v[230:231], 0, s[86:87]
	s_mov_b32 m0, s53
	s_nop 0
	global_load_lds_dwordx4 v[154:155], off
	s_barrier
; #define PG8_STAGE(bufoff, gbase, voff) do { _Pragma("unroll") for (int _i = 0; _i < 2; ++_i) \
;         __builtin_amdgcn_global_load_lds((const unsigned*)((const char*)(gbase) + (voff)[_i]), (LAS unsigned*)(lds + (bufoff) + ldsw + _i * 8192), 16, 0, 0); } while (0)
; #define PG8_MMA(ai, bj, At, Bt) do { __builtin_amdgcn_s_setprio(1); _Pragma("unroll") for (int m = 0; m < 4; ++m) _Pragma("unroll") for (int n = 0; n < 2; ++n) _Pragma("unroll") for (int k = 0; k < 2; ++k) \
;         acc[ai][bj][m][n] = __builtin_amdgcn_mfma_f32_16x16x32_bf16(Bt[n][k], At[m][k], acc[ai][bj][m][n], 0, 0, 0); __builtin_amdgcn_s_setprio(0); } while (0)
; #define PG8_WAIT_V(n) asm volatile("s_waitcnt vmcnt(" #n ")" ::: "memory")
; #define PG8_WAIT_L(n) asm volatile("s_waitcnt lgkmcnt(" #n ")" ::: "memory")
; #define PG8_BAR __builtin_amdgcn_s_barrier()
; template <class Epi>
; __device__ __forceinline__ void gemm_phase(LAS unsigned char* lds, const Gemm g, const Epi& E) {
;     ...
;             PG8_BAR; PG8_WAIT_L(0); PG8_MMA(1, 0, At, B0); PG8_BAR; PG8_SCHED;
;             PG8_STAGE(PG8_SB(1, 1), b3 + hstepB, voffB);
;             PG8_WAIT_V(6); PG8_BAR; PG8_MMA(1, 1, At, B1); PG8_BAR;
;         }
;     __device__ __forceinline__ void operator()(const AccT& acc, const Unit& u, int wr, int wc, int fr, int fq) const {
;         asm volatile("" : "+v"(fr), "+v"(fq));
;         const int gpm = mapA.src(u.pm);
;         const int mb = gpm < 32 ? 32 : (gpm - 32) >> 3;
;         const int row0 = gpm * 256 + wr * 64 + fr, col0 = u.pn * 256 + wc * 32 + 4 * fq;
;         const float* gp = modl + ((size_t)mb * 6 + gi) * 1024;
;         f32x4 gv[2][2];
; #pragma unroll
;         for (int bj = 0; bj < 2; ++bj)
; #pragma unroll
;             for (int n = 0; n < 2; ++n) { gv[bj][n] = *(const f32x4*)(gp + col0 + bj * 128 + n * 16); if (scale) gv[bj][n] = gv[bj][n] * *(const f32x4*)(scale + col0 + bj * 128 + n * 16); }
;         const float* sbase = (gpm < 32 ? Xc : Xl) + (size_t)row0 * 1024 + col0;
; #pragma unroll
;         for (int ai = 0; ai < 2; ++ai) {
;             f32x4 xo[4][2][2];
; #pragma unroll
;             for (int m = 0; m < 4; ++m)
; #pragma unroll
;                 for (int bj = 0; bj < 2; ++bj)
; #pragma unroll
;                     for (int n = 0; n < 2; ++n) xo[m][bj][n] = *(const f32x4*)(sbase + (size_t)(ai * 128 + m * 16) * 1024 + bj * 128 + n * 16);
	s_waitcnt lgkmcnt(0)
	s_setprio 1
	v_mfma_f32_16x16x32_bf16 v[62:65], v[130:133], v[160:163], v[62:65]
	v_mfma_f32_16x16x32_bf16 v[58:61], v[138:141], v[160:163], v[58:61]
	v_mfma_f32_16x16x32_bf16 v[54:57], v[130:133], v[168:171], v[54:57]
	v_mfma_f32_16x16x32_bf16 v[46:49], v[138:141], v[168:171], v[46:49]
	v_mfma_f32_16x16x32_bf16 v[38:41], v[130:133], v[180:183], v[38:41]
	v_mfma_f32_16x16x32_bf16 v[30:33], v[138:141], v[180:183], v[30:33]
	v_mfma_f32_16x16x32_bf16 v[22:25], v[130:133], v[188:191], v[22:25]
	v_mfma_f32_16x16x32_bf16 v[14:17], v[138:141], v[188:191], v[14:17]
	v_mfma_f32_16x16x32_bf16 v[62:65], v[134:137], v[164:167], v[62:65]
	v_mfma_f32_16x16x32_bf16 v[58:61], v[142:145], v[164:167], v[58:61]
	v_mfma_f32_16x16x32_bf16 v[54:57], v[134:137], v[172:175], v[54:57]
	v_mfma_f32_16x16x32_bf16 v[46:49], v[142:145], v[172:175], v[46:49]
	v_mfma_f32_16x16x32_bf16 v[38:41], v[134:137], v[184:187], v[38:41]
	v_mfma_f32_16x16x32_bf16 v[30:33], v[142:145], v[184:187], v[30:33]
	v_mfma_f32_16x16x32_bf16 v[22:25], v[134:137], v[192:195], v[22:25]
	v_mfma_f32_16x16x32_bf16 v[14:17], v[142:145], v[192:195], v[14:17]
	s_setprio 0
	s_barrier
	s_add_u32 s8, s12, 0xb0080
	s_addc_u32 s9, s13, 0
	s_add_i32 s12, s14, s18
	v_lshl_add_u64 v[130:131], s[8:9], 0, v[148:149]
	s_mov_b32 m0, s12
	s_nop 0
	global_load_lds_dwordx4 v[130:131], off
	v_lshl_add_u64 v[130:131], s[8:9], 0, v[146:147]
	s_add_i32 m0, s12, 0x2000
	s_nop 0
	global_load_lds_dwordx4 v[130:131], off
	s_waitcnt vmcnt(6)
	s_barrier
	s_setprio 1
	v_mfma_f32_16x16x32_bf16 v[50:53], v[196:199], v[160:163], v[50:53]
	v_mfma_f32_16x16x32_bf16 v[42:45], v[204:207], v[160:163], v[42:45]
	v_mfma_f32_16x16x32_bf16 v[34:37], v[196:199], v[168:171], v[34:37]
	v_mfma_f32_16x16x32_bf16 v[26:29], v[204:207], v[168:171], v[26:29]
	v_mfma_f32_16x16x32_bf16 v[18:21], v[196:199], v[180:183], v[18:21]
	v_mfma_f32_16x16x32_bf16 v[10:13], v[204:207], v[180:183], v[10:13]
	v_mfma_f32_16x16x32_bf16 v[6:9], v[196:199], v[188:191], v[6:9]
	v_mfma_f32_16x16x32_bf16 v[2:5], v[204:207], v[188:191], v[2:5]
	v_mfma_f32_16x16x32_bf16 v[50:53], v[200:203], v[164:167], v[50:53]
	v_mfma_f32_16x16x32_bf16 v[42:45], v[226:229], v[164:167], v[42:45]
	v_mfma_f32_16x16x32_bf16 v[34:37], v[200:203], v[172:175], v[34:37]
	v_mfma_f32_16x16x32_bf16 v[26:29], v[226:229], v[172:175], v[26:29]
	v_mfma_f32_16x16x32_bf16 v[18:21], v[200:203], v[184:187], v[18:21]
	v_mfma_f32_16x16x32_bf16 v[10:13], v[226:229], v[184:187], v[10:13]
	v_mfma_f32_16x16x32_bf16 v[6:9], v[200:203], v[192:195], v[6:9]
	v_mfma_f32_16x16x32_bf16 v[2:5], v[226:229], v[192:195], v[2:5]
	s_setprio 0
	s_add_i32 s67, s67, 2
	s_add_u32 s65, s65, 0x100
	s_addc_u32 s66, s66, 0
	s_cmp_gt_u32 s67, 41
	s_mov_b64 s[8:9], s[10:11]
	s_barrier
	s_cbranch_scc0 .LBB0_547
	v_readlane_b32 s8, v255, 27
	s_cmp_ge_i32 s64, s8
	s_cselect_b32 s8, s25, 0
	s_add_i32 s10, s64, s8
	s_sub_i32 s8, s10, 32
	s_lshl_b32 s9, s61, 8
	s_ashr_i32 s8, s8, 3
	s_or_b32 s9, s9, s50
	v_mov_b32_e32 v130, v1
	v_mov_b32_e32 v159, v156
	s_mul_i32 s8, s8, 6
	s_cmp_gt_i32 s10, 31
	s_cselect_b32 s8, s8, 0xc0
	v_lshl_add_u32 v130, v130, 2, s9
	s_ashr_i32 s9, s8, 31
	s_lshl_b64 s[8:9], s[8:9], 12
	v_readlane_b32 s12, v255, 14
	v_readlane_b32 s13, v255, 15
	s_add_u32 s8, s12, s8
	v_ashrrev_i32_e32 v131, 31, v130
	s_addc_u32 s9, s13, s9
	v_lshlrev_b64 v[154:155], 2, v[130:131]
	v_lshl_add_u64 v[130:131], s[8:9], 0, v[154:155]
	s_mov_b64 s[8:9], 0x5000
	v_lshl_add_u64 v[132:133], v[130:131], 0, s[8:9]
	s_movk_i32 s8, 0x5000
	v_add_co_u32_e32 v130, vcc, s8, v130
	s_lshl_b32 s8, s10, 8
	s_add_i32 s8, s8, s44
	v_add_u32_e32 v160, s8, v159
	v_ashrrev_i32_e32 v161, 31, v160
	v_readlane_b32 s8, v254, 0
	v_lshlrev_b64 v[160:161], 12, v[160:161]
	v_readlane_b32 s9, v254, 1
	v_addc_co_u32_e32 v131, vcc, 0, v131, vcc
	s_nop 0
	v_lshl_add_u64 v[160:161], s[8:9], 0, v[160:161]
	v_lshl_add_u64 v[154:155], v[160:161], 0, v[154:155]
	v_add_co_u32_e32 v176, vcc, s45, v154
	global_load_dwordx4 v[138:141], v[132:133], off offset:64
	global_load_dwordx4 v[134:137], v[132:133], off offset:512
	global_load_dwordx4 v[142:145], v[130:131], off
	s_nop 0
	global_load_dwordx4 v[130:133], v[132:133], off offset:576
	v_addc_co_u32_e32 v177, vcc, 0, v155, vcc
	v_add_co_u32_e32 v208, vcc, s19, v154
	global_load_dwordx4 v[160:163], v[154:155], off
	global_load_dwordx4 v[164:167], v[154:155], off offset:64
	global_load_dwordx4 v[168:171], v[154:155], off offset:512
	global_load_dwordx4 v[172:175], v[154:155], off offset:576
	v_addc_co_u32_e32 v209, vcc, 0, v155, vcc
	v_add_co_u32_e32 v246, vcc, s88, v154
	global_load_dwordx4 v[180:183], v[176:177], off
	global_load_dwordx4 v[184:187], v[176:177], off offset:64
	global_load_dwordx4 v[188:191], v[176:177], off offset:512
	global_load_dwordx4 v[192:195], v[176:177], off offset:576
	v_addc_co_u32_e32 v247, vcc, 0, v155, vcc
	global_load_dwordx4 v[196:199], v[208:209], off
	global_load_dwordx4 v[200:203], v[208:209], off offset:64
	global_load_dwordx4 v[204:207], v[208:209], off offset:512
	global_load_dwordx4 v[226:229], v[208:209], off offset:576
	global_load_dwordx4 v[230:233], v[246:247], off
	global_load_dwordx4 v[234:237], v[246:247], off offset:64
	global_load_dwordx4 v[238:241], v[246:247], off offset:512
	global_load_dwordx4 v[242:245], v[246:247], off offset:576
	s_mov_b64 s[8:9], 0x30000
	v_lshl_add_u64 v[248:249], v[154:155], 0, s[84:85]
	v_lshl_add_u64 v[250:251], v[154:155], 0, s[82:83]
	v_lshl_add_u64 v[252:253], v[154:155], 0, s[8:9]
	s_waitcnt vmcnt(0)
;     __device__ __forceinline__ void operator()(const AccT& acc, const Unit& u, int wr, int wc, int fr, int fq) const {
;     ...
; #pragma unroll
;         for (int ai = 0; ai < 2; ++ai) {
;             f32x4 xo[4][2][2];
; #pragma unroll
;             for (int m = 0; m < 4; ++m)
; #pragma unroll
;                 for (int bj = 0; bj < 2; ++bj)
; #pragma unroll
;                     for (int n = 0; n < 2; ++n) xo[m][bj][n] = *(const f32x4*)(sbase + (size_t)(ai * 128 + m * 16) * 1024 + bj * 128 + n * 16);
;             __builtin_amdgcn_sched_barrier(0);
; #pragma unroll
;             for (int m = 0; m < 4; ++m) { float* rowp = X + (size_t)(row0 + ai * 128 + m * 16) * 1024 + col0;
; #pragma unroll
;                 for (int bj = 0; bj < 2; ++bj)
; #pragma unroll
;                     for (int n = 0; n < 2; ++n) *(f32x4*)(rowp + bj * 128 + n * 16) = xo[m][bj][n] + gv[bj][n] * acc[ai][bj][m][n]; }
	v_pk_fma_f32 v[108:109], v[108:109], v[132:133], v[174:175]
	v_pk_fma_f32 v[106:107], v[106:107], v[130:131], v[172:173]
	v_pk_fma_f32 v[92:93], v[92:93], v[132:133], v[194:195]
	v_pk_fma_f32 v[90:91], v[90:91], v[130:131], v[192:193]
	v_pk_fma_f32 v[76:77], v[76:77], v[132:133], v[228:229]
	v_pk_fma_f32 v[74:75], v[74:75], v[130:131], v[226:227]
	global_store_dwordx4 v[154:155], v[106:109], off offset:576
	global_store_dwordx4 v[248:249], v[90:93], off offset:576
	global_store_dwordx4 v[250:251], v[74:77], off offset:576
	v_pk_fma_f32 v[108:109], v[120:121], v[144:145], v[182:183]
	v_pk_fma_f32 v[106:107], v[118:119], v[142:143], v[180:181]
	v_pk_fma_f32 v[92:93], v[104:105], v[144:145], v[198:199]
	v_pk_fma_f32 v[90:91], v[102:103], v[142:143], v[196:197]
	v_pk_fma_f32 v[76:77], v[88:89], v[144:145], v[232:233]
	v_pk_fma_f32 v[74:75], v[86:87], v[142:143], v[230:231]
	v_pk_fma_f32 v[128:129], v[128:129], v[144:145], v[162:163]
	v_pk_fma_f32 v[126:127], v[126:127], v[142:143], v[160:161]
	v_pk_fma_f32 v[124:125], v[124:125], v[140:141], v[166:167]
	v_pk_fma_f32 v[122:123], v[122:123], v[138:139], v[164:165]
	v_pk_fma_f32 v[116:117], v[116:117], v[136:137], v[170:171]
	v_pk_fma_f32 v[114:115], v[114:115], v[134:135], v[168:169]
	global_store_dwordx4 v[176:177], v[106:109], off
	v_pk_fma_f32 v[100:101], v[100:101], v[136:137], v[190:191]
	v_pk_fma_f32 v[98:99], v[98:99], v[134:135], v[188:189]
	v_pk_fma_f32 v[108:109], v[112:113], v[140:141], v[186:187]
	v_pk_fma_f32 v[106:107], v[110:111], v[138:139], v[184:185]
	global_store_dwordx4 v[208:209], v[90:93], off
	v_pk_fma_f32 v[84:85], v[84:85], v[136:137], v[206:207]
	v_pk_fma_f32 v[82:83], v[82:83], v[134:135], v[204:205]
	v_pk_fma_f32 v[92:93], v[96:97], v[140:141], v[202:203]
	v_pk_fma_f32 v[90:91], v[94:95], v[138:139], v[200:201]
	global_store_dwordx4 v[246:247], v[74:77], off
	v_pk_fma_f32 v[72:73], v[72:73], v[136:137], v[240:241]
	v_pk_fma_f32 v[70:71], v[70:71], v[134:135], v[238:239]
	v_pk_fma_f32 v[76:77], v[80:81], v[140:141], v[236:237]
	v_pk_fma_f32 v[74:75], v[78:79], v[138:139], v[234:235]
	v_pk_fma_f32 v[68:69], v[68:69], v[132:133], v[244:245]
	v_pk_fma_f32 v[66:67], v[66:67], v[130:131], v[242:243]
	global_store_dwordx4 v[154:155], v[126:129], off
	global_store_dwordx4 v[154:155], v[122:125], off offset:64
	global_store_dwordx4 v[154:155], v[114:117], off offset:512
	global_store_dwordx4 v[248:249], v[106:109], off offset:64
	global_store_dwordx4 v[248:249], v[98:101], off offset:512
	global_store_dwordx4 v[250:251], v[90:93], off offset:64
	global_store_dwordx4 v[250:251], v[82:85], off offset:512
	global_store_dwordx4 v[252:253], v[74:77], off offset:64
	global_store_dwordx4 v[252:253], v[70:73], off offset:512
	global_store_dwordx4 v[252:253], v[66:69], off offset:576
	s_mov_b64 s[8:9], 0x80000
	v_lshl_add_u64 v[160:161], v[154:155], 0, s[8:9]
	s_mov_b32 s8, 0x80000
	v_add_co_u32_e32 v162, vcc, s8, v154
	s_mov_b64 s[8:9], 0x90000
	s_nop 0
	v_addc_co_u32_e32 v163, vcc, 0, v155, vcc
	v_lshl_add_u64 v[164:165], v[154:155], 0, s[8:9]
	s_mov_b32 s8, 0x90000
	v_add_co_u32_e32 v166, vcc, s8, v154
	s_mov_b64 s[8:9], 0xa0000
	s_nop 0
	v_addc_co_u32_e32 v167, vcc, 0, v155, vcc
	v_lshl_add_u64 v[168:169], v[154:155], 0, s[8:9]
	s_mov_b32 s8, 0xa0000
	v_add_co_u32_e32 v170, vcc, s8, v154
	s_mov_b64 s[8:9], 0xb0000
	s_nop 0
	v_addc_co_u32_e32 v171, vcc, 0, v155, vcc
	v_lshl_add_u64 v[172:173], v[154:155], 0, s[8:9]
	s_mov_b32 s8, 0xb0000
	v_add_co_u32_e32 v154, vcc, s8, v154
	global_load_dwordx4 v[66:69], v[162:163], off
	global_load_dwordx4 v[70:73], v[162:163], off offset:64
	global_load_dwordx4 v[74:77], v[162:163], off offset:512
	global_load_dwordx4 v[78:81], v[162:163], off offset:576
	v_addc_co_u32_e32 v155, vcc, 0, v155, vcc
	global_load_dwordx4 v[82:85], v[166:167], off
	global_load_dwordx4 v[86:89], v[166:167], off offset:64
	global_load_dwordx4 v[90:93], v[166:167], off offset:512
	global_load_dwordx4 v[94:97], v[166:167], off offset:576
	global_load_dwordx4 v[98:101], v[170:171], off
	global_load_dwordx4 v[102:105], v[170:171], off offset:64
	global_load_dwordx4 v[106:109], v[170:171], off offset:512
	global_load_dwordx4 v[110:113], v[170:171], off offset:576
	global_load_dwordx4 v[114:117], v[154:155], off
	global_load_dwordx4 v[118:121], v[154:155], off offset:64
	global_load_dwordx4 v[122:125], v[154:155], off offset:512
	global_load_dwordx4 v[126:129], v[154:155], off offset:576
	s_waitcnt vmcnt(0)
; #define PG8_WAIT_V(n) asm volatile("s_waitcnt vmcnt(" #n ")" ::: "memory")
; #define PG8_BAR __builtin_amdgcn_s_barrier()
; template <class Epi>
; __device__ __forceinline__ void gemm_phase(LAS unsigned char* lds, const Gemm g, const Epi& E) {
;     ...
;         if (!has_next) break;
; #pragma unroll
;         for (int a = 0; a < 2; ++a)
; #pragma unroll
;             for (int b = 0; b < 2; ++b)
; #pragma unroll
;                 for (int m = 0; m < 4; ++m)
; #pragma unroll
;                     for (int n = 0; n < 2; ++n) acc[a][b][m][n] = (f32x4){0.f, 0.f, 0.f, 0.f};
;         cur = nxt; cA = nA; cB = nB; ++ui;
;     }
;     PG8_WAIT_V(0);
;     if (wr == 0) PG8_BAR;
;     PG8_BAR;
;     __device__ __forceinline__ void operator()(const AccT& acc, const Unit& u, int wr, int wc, int fr, int fq) const {
;     ...
;             for (int m = 0; m < 4; ++m) { float* rowp = X + (size_t)(row0 + ai * 128 + m * 16) * 1024 + col0;
; #pragma unroll
;                 for (int bj = 0; bj < 2; ++bj)
; #pragma unroll
;                     for (int n = 0; n < 2; ++n) *(f32x4*)(rowp + bj * 128 + n * 16) = xo[m][bj][n] + gv[bj][n] * acc[ai][bj][m][n]; }
;             __builtin_amdgcn_sched_barrier(0);
	v_pk_fma_f32 v[44:45], v[44:45], v[132:133], v[80:81]
	v_pk_fma_f32 v[42:43], v[42:43], v[130:131], v[78:79]
	v_pk_fma_f32 v[28:29], v[28:29], v[132:133], v[96:97]
	v_pk_fma_f32 v[26:27], v[26:27], v[130:131], v[94:95]
	v_pk_fma_f32 v[12:13], v[12:13], v[132:133], v[112:113]
	v_pk_fma_f32 v[10:11], v[10:11], v[130:131], v[110:111]
	global_store_dwordx4 v[160:161], v[42:45], off offset:576
	global_store_dwordx4 v[164:165], v[26:29], off offset:576
	global_store_dwordx4 v[168:169], v[10:13], off offset:576
	v_pk_fma_f32 v[44:45], v[56:57], v[144:145], v[84:85]
	v_pk_fma_f32 v[42:43], v[54:55], v[142:143], v[82:83]
	v_pk_fma_f32 v[28:29], v[40:41], v[144:145], v[100:101]
	v_pk_fma_f32 v[26:27], v[38:39], v[142:143], v[98:99]
	v_pk_fma_f32 v[12:13], v[24:25], v[144:145], v[116:117]
	v_pk_fma_f32 v[10:11], v[22:23], v[142:143], v[114:115]
	v_pk_fma_f32 v[64:65], v[64:65], v[144:145], v[68:69]
	v_pk_fma_f32 v[62:63], v[62:63], v[142:143], v[66:67]
	v_pk_fma_f32 v[60:61], v[60:61], v[140:141], v[72:73]
	v_pk_fma_f32 v[58:59], v[58:59], v[138:139], v[70:71]
	v_pk_fma_f32 v[52:53], v[52:53], v[136:137], v[76:77]
	v_pk_fma_f32 v[50:51], v[50:51], v[134:135], v[74:75]
	global_store_dwordx4 v[166:167], v[42:45], off
	v_pk_fma_f32 v[36:37], v[36:37], v[136:137], v[92:93]
	v_pk_fma_f32 v[34:35], v[34:35], v[134:135], v[90:91]
	v_pk_fma_f32 v[44:45], v[48:49], v[140:141], v[88:89]
	v_pk_fma_f32 v[42:43], v[46:47], v[138:139], v[86:87]
	global_store_dwordx4 v[170:171], v[26:29], off
	v_pk_fma_f32 v[20:21], v[20:21], v[136:137], v[108:109]
	v_pk_fma_f32 v[18:19], v[18:19], v[134:135], v[106:107]
	v_pk_fma_f32 v[28:29], v[32:33], v[140:141], v[104:105]
	v_pk_fma_f32 v[26:27], v[30:31], v[138:139], v[102:103]
	global_store_dwordx4 v[154:155], v[10:13], off
	v_pk_fma_f32 v[8:9], v[8:9], v[136:137], v[124:125]
	v_pk_fma_f32 v[6:7], v[6:7], v[134:135], v[122:123]
	v_pk_fma_f32 v[12:13], v[16:17], v[140:141], v[120:121]
	v_pk_fma_f32 v[10:11], v[14:15], v[138:139], v[118:119]
	v_pk_fma_f32 v[4:5], v[4:5], v[132:133], v[128:129]
	v_pk_fma_f32 v[2:3], v[2:3], v[130:131], v[126:127]
	global_store_dwordx4 v[162:163], v[62:65], off
	global_store_dwordx4 v[160:161], v[58:61], off offset:64
	global_store_dwordx4 v[160:161], v[50:53], off offset:512
	global_store_dwordx4 v[164:165], v[42:45], off offset:64
	global_store_dwordx4 v[164:165], v[34:37], off offset:512
	global_store_dwordx4 v[168:169], v[26:29], off offset:64
	global_store_dwordx4 v[168:169], v[18:21], off offset:512
	global_store_dwordx4 v[172:173], v[10:13], off offset:64
	global_store_dwordx4 v[172:173], v[6:9], off offset:512
	global_store_dwordx4 v[172:173], v[2:5], off offset:576
	s_and_b64 vcc, exec, s[2:3]
	s_mov_b32 s61, s59
	s_mov_b32 s64, s60
	s_mov_b64 s[10:11], s[6:7]
	s_mov_b64 s[8:9], s[4:5]
	s_cbranch_vccz .LBB0_540
	s_waitcnt vmcnt(0)
	s_cmpk_gt_u32 s1, 0xff
	s_movk_i32 s36, 0xf000
	s_cbranch_scc1 .LBB0_551
	s_barrier
